# nt (streaming) hint on the epilogue stores of every multi-round GEMM phase (FFN-in, mix, proj) so output streams do not displace A/B tiles in L2
# baseline (speedup 1.0000x reference)
.LBB0_504:
	s_cmp_gt_u32 s6, 16
	s_cbranch_scc0 .LBB0_508
	s_and_saveexec_b64 s[0:1], s[20:21]
	s_cbranch_execz .LBB0_507
	v_mul_f32_e32 v128, 0xbfb8aa3b, v124
	v_mul_f32_e32 v129, 0xbfb8aa3b, v125
	v_mul_f32_e32 v130, 0xbfb8aa3b, v126
	v_mul_f32_e32 v131, 0xbfb8aa3b, v127
	v_exp_f32_e32 v128, v128
	v_exp_f32_e32 v129, v129
	v_exp_f32_e32 v130, v130
	v_exp_f32_e32 v131, v131
	v_add_f32_e32 v128, 1.0, v128
	v_add_f32_e32 v129, 1.0, v129
	v_add_f32_e32 v130, 1.0, v130
	v_add_f32_e32 v131, 1.0, v131
	v_rcp_f32_e32 v128, v128
	v_rcp_f32_e32 v129, v129
	v_rcp_f32_e32 v130, v130
	v_rcp_f32_e32 v131, v131
	v_mad_i64_i32 v[136:137], s[30:31], v216, s63, v[186:187]
	v_or_b32_e32 v132, 16, v216
	global_store_dwordx4 v[136:137], v[128:131], off nt
	v_mad_i64_i32 v[138:139], s[30:31], v132, s63, v[186:187]
	s_nop 0
	v_mul_f32_e32 v128, 0xbfb8aa3b, v116
	v_mul_f32_e32 v129, 0xbfb8aa3b, v117
	v_mul_f32_e32 v130, 0xbfb8aa3b, v118
	v_mul_f32_e32 v131, 0xbfb8aa3b, v119
	v_exp_f32_e32 v128, v128
	v_exp_f32_e32 v129, v129
	v_exp_f32_e32 v130, v130
	v_exp_f32_e32 v131, v131
	v_add_f32_e32 v128, 1.0, v128
	v_add_f32_e32 v129, 1.0, v129
	v_add_f32_e32 v130, 1.0, v130
	v_add_f32_e32 v131, 1.0, v131
	v_rcp_f32_e32 v128, v128
	v_rcp_f32_e32 v129, v129
	v_rcp_f32_e32 v130, v130
	v_rcp_f32_e32 v131, v131
	v_mul_f32_e32 v132, 0xbfb8aa3b, v108
	v_mul_f32_e32 v133, 0xbfb8aa3b, v109
	v_exp_f32_e32 v132, v132
	global_store_dwordx4 v[138:139], v[128:131], off nt
	v_exp_f32_e32 v133, v133
	v_add_u32_e32 v144, 0x90, v216
	v_mul_f32_e32 v130, 0xbfb8aa3b, v110
	v_mul_f32_e32 v131, 0xbfb8aa3b, v111
	v_exp_f32_e32 v130, v130
	v_exp_f32_e32 v131, v131
	v_add_f32_e32 v128, 1.0, v132
	v_add_f32_e32 v129, 1.0, v133
	v_add_f32_e32 v130, 1.0, v130
	v_add_f32_e32 v131, 1.0, v131
	v_rcp_f32_e32 v128, v128
	v_rcp_f32_e32 v129, v129
	v_rcp_f32_e32 v130, v130
	v_rcp_f32_e32 v131, v131
	v_or_b32_e32 v132, 32, v216
	v_mad_i64_i32 v[140:141], s[30:31], v132, s63, v[186:187]
	global_store_dwordx4 v[140:141], v[128:131], off nt
	v_or_b32_e32 v132, 48, v216
	v_mad_i64_i32 v[142:143], s[30:31], v132, s63, v[186:187]
	v_mul_f32_e32 v128, 0xbfb8aa3b, v100
	v_mul_f32_e32 v129, 0xbfb8aa3b, v101
	v_mul_f32_e32 v130, 0xbfb8aa3b, v102
	v_mul_f32_e32 v131, 0xbfb8aa3b, v103
	v_exp_f32_e32 v128, v128
	v_exp_f32_e32 v129, v129
	v_exp_f32_e32 v130, v130
	v_exp_f32_e32 v131, v131
	v_add_f32_e32 v128, 1.0, v128
	v_add_f32_e32 v129, 1.0, v129
	v_add_f32_e32 v130, 1.0, v130
	v_add_f32_e32 v131, 1.0, v131
	v_rcp_f32_e32 v128, v128
	v_rcp_f32_e32 v129, v129
	v_rcp_f32_e32 v130, v130
	v_rcp_f32_e32 v131, v131
	v_mul_f32_e32 v132, 0xbfb8aa3b, v92
	v_exp_f32_e32 v132, v132
	v_mul_f32_e32 v133, 0xbfb8aa3b, v93
	v_exp_f32_e32 v133, v133
	global_store_dwordx4 v[142:143], v[128:131], off nt
	v_mul_f32_e32 v145, 0xbfb8aa3b, v77
	v_exp_f32_e32 v145, v145
	v_mul_f32_e32 v129, 0xbfb8aa3b, v94
	v_add_f32_e32 v128, 1.0, v132
	v_exp_f32_e32 v129, v129
	v_mul_f32_e32 v131, 0xbfb8aa3b, v95
	v_rcp_f32_e32 v130, v128
	v_add_f32_e32 v128, 1.0, v133
	v_exp_f32_e32 v133, v131
	v_rcp_f32_e32 v131, v128
	v_add_f32_e32 v128, 1.0, v129
	v_rcp_f32_e32 v132, v128
	v_add_f32_e32 v128, 1.0, v133
	v_rcp_f32_e32 v133, v128
	v_add_u32_e32 v128, 0x80, v216
	v_mad_i64_i32 v[128:129], s[30:31], v128, s63, v[186:187]
	global_store_dwordx4 v[128:129], v[130:133], off nt
	v_mul_f32_e32 v146, 0xbfb8aa3b, v66
	v_mul_f32_e32 v147, 0xbfb8aa3b, v67
	v_mul_f32_e32 v130, 0xbfb8aa3b, v84
	v_exp_f32_e32 v130, v130
	v_mul_f32_e32 v131, 0xbfb8aa3b, v85
	v_exp_f32_e32 v131, v131
	v_mul_f32_e32 v133, 0xbfb8aa3b, v87
	v_add_f32_e32 v130, 1.0, v130
	v_rcp_f32_e32 v132, v130
	v_add_f32_e32 v130, 1.0, v131
	v_mul_f32_e32 v131, 0xbfb8aa3b, v86
	v_exp_f32_e32 v131, v131
	v_exp_f32_e32 v135, v133
	v_rcp_f32_e32 v133, v130
	v_exp_f32_e32 v146, v146
	v_add_f32_e32 v130, 1.0, v131
	v_rcp_f32_e32 v134, v130
	v_add_f32_e32 v130, 1.0, v135
	v_rcp_f32_e32 v135, v130
	v_mad_i64_i32 v[130:131], s[30:31], v144, s63, v[186:187]
	v_mul_f32_e32 v144, 0xbfb8aa3b, v76
	global_store_dwordx4 v[130:131], v[132:135], off nt
	v_exp_f32_e32 v144, v144
	v_exp_f32_e32 v147, v147
	v_mul_f32_e32 v134, 0xbfb8aa3b, v78
	v_mul_f32_e32 v135, 0xbfb8aa3b, v79
	v_exp_f32_e32 v134, v134
	v_exp_f32_e32 v135, v135
	v_add_f32_e32 v132, 1.0, v144
	v_add_f32_e32 v133, 1.0, v145
	v_add_f32_e32 v134, 1.0, v134
	v_add_f32_e32 v135, 1.0, v135
	v_rcp_f32_e32 v132, v132
	v_rcp_f32_e32 v133, v133
	v_rcp_f32_e32 v134, v134
	v_rcp_f32_e32 v135, v135
	v_add_u32_e32 v144, 0xa0, v216
	v_mad_i64_i32 v[148:149], s[30:31], v144, s63, v[186:187]
	global_store_dwordx4 v[148:149], v[132:135], off nt
	v_add_u32_e32 v144, 0xb0, v216
	v_mad_i64_i32 v[150:151], s[30:31], v144, s63, v[186:187]
	v_mul_f32_e32 v132, 0xbfb8aa3b, v68
	v_mul_f32_e32 v133, 0xbfb8aa3b, v69
	v_mul_f32_e32 v134, 0xbfb8aa3b, v70
	v_mul_f32_e32 v135, 0xbfb8aa3b, v71
	v_exp_f32_e32 v132, v132
	v_exp_f32_e32 v133, v133
	v_exp_f32_e32 v134, v134
	v_exp_f32_e32 v135, v135
	v_add_f32_e32 v132, 1.0, v132
	v_add_f32_e32 v133, 1.0, v133
	v_add_f32_e32 v134, 1.0, v134
	v_add_f32_e32 v135, 1.0, v135
	v_rcp_f32_e32 v132, v132
	v_rcp_f32_e32 v133, v133
	v_rcp_f32_e32 v134, v134
	v_rcp_f32_e32 v135, v135
	v_mul_f32_e32 v144, 0xbfb8aa3b, v120
	v_mul_f32_e32 v145, 0xbfb8aa3b, v121
	v_exp_f32_e32 v144, v144
	global_store_dwordx4 v[150:151], v[132:135], off nt
	v_exp_f32_e32 v145, v145
	v_add_f32_e32 v146, 1.0, v146
	v_mul_f32_e32 v134, 0xbfb8aa3b, v122
	v_mul_f32_e32 v135, 0xbfb8aa3b, v123
	v_exp_f32_e32 v134, v134
	v_exp_f32_e32 v135, v135
	v_add_f32_e32 v132, 1.0, v144
	v_add_f32_e32 v133, 1.0, v145
	v_add_f32_e32 v134, 1.0, v134
	v_add_f32_e32 v135, 1.0, v135
	v_rcp_f32_e32 v132, v132
	v_rcp_f32_e32 v133, v133
	v_rcp_f32_e32 v134, v134
	v_rcp_f32_e32 v135, v135
	v_mul_f32_e32 v144, 0xbfb8aa3b, v112
	v_mul_f32_e32 v145, 0xbfb8aa3b, v113
	v_exp_f32_e32 v144, v144
	global_store_dwordx4 v[136:137], v[132:135], off offset:16 nt
	v_exp_f32_e32 v145, v145
	v_mul_f32_e32 v136, 0xbfb8aa3b, v104
	v_mul_f32_e32 v134, 0xbfb8aa3b, v114
	v_mul_f32_e32 v135, 0xbfb8aa3b, v115
	v_exp_f32_e32 v134, v134
	v_exp_f32_e32 v135, v135
	v_add_f32_e32 v132, 1.0, v144
	v_add_f32_e32 v133, 1.0, v145
	v_add_f32_e32 v134, 1.0, v134
	v_add_f32_e32 v135, 1.0, v135
	v_rcp_f32_e32 v132, v132
	v_rcp_f32_e32 v133, v133
	v_rcp_f32_e32 v134, v134
	v_rcp_f32_e32 v135, v135
	v_mul_f32_e32 v137, 0xbfb8aa3b, v105
	v_exp_f32_e32 v136, v136
	v_exp_f32_e32 v137, v137
	global_store_dwordx4 v[138:139], v[132:135], off offset:16 nt
	v_mul_f32_e32 v138, 0xbfb8aa3b, v82
	v_mul_f32_e32 v139, 0xbfb8aa3b, v83
	v_mul_f32_e32 v134, 0xbfb8aa3b, v106
	v_mul_f32_e32 v135, 0xbfb8aa3b, v107
	v_exp_f32_e32 v134, v134
	v_exp_f32_e32 v135, v135
	v_add_f32_e32 v132, 1.0, v136
	v_add_f32_e32 v133, 1.0, v137
	v_add_f32_e32 v134, 1.0, v134
	v_add_f32_e32 v135, 1.0, v135
	v_rcp_f32_e32 v132, v132
	v_rcp_f32_e32 v133, v133
	v_rcp_f32_e32 v134, v134
	v_rcp_f32_e32 v135, v135
	v_mul_f32_e32 v136, 0xbfb8aa3b, v96
	v_mul_f32_e32 v137, 0xbfb8aa3b, v97
	v_exp_f32_e32 v136, v136
	global_store_dwordx4 v[140:141], v[132:135], off offset:16 nt
	v_exp_f32_e32 v137, v137
	v_exp_f32_e32 v138, v138
	v_mul_f32_e32 v134, 0xbfb8aa3b, v98
	v_mul_f32_e32 v135, 0xbfb8aa3b, v99
	v_exp_f32_e32 v134, v134
	v_exp_f32_e32 v135, v135
	v_add_f32_e32 v132, 1.0, v136
	v_add_f32_e32 v133, 1.0, v137
	v_add_f32_e32 v134, 1.0, v134
	v_add_f32_e32 v135, 1.0, v135
	v_rcp_f32_e32 v132, v132
	v_rcp_f32_e32 v133, v133
	v_rcp_f32_e32 v134, v134
	v_rcp_f32_e32 v135, v135
	v_mul_f32_e32 v136, 0xbfb8aa3b, v88
	v_mul_f32_e32 v137, 0xbfb8aa3b, v89
	v_exp_f32_e32 v136, v136
	v_exp_f32_e32 v137, v137
	global_store_dwordx4 v[142:143], v[132:135], off offset:16 nt
	v_exp_f32_e32 v139, v139
	v_mul_f32_e32 v140, 0xbfb8aa3b, v72
	v_mul_f32_e32 v134, 0xbfb8aa3b, v90
	v_mul_f32_e32 v135, 0xbfb8aa3b, v91
	v_add_f32_e32 v132, 1.0, v136
	v_add_f32_e32 v133, 1.0, v137
	v_exp_f32_e32 v134, v134
	v_exp_f32_e32 v135, v135
	v_mul_f32_e32 v136, 0xbfb8aa3b, v80
	v_mul_f32_e32 v137, 0xbfb8aa3b, v81
	v_exp_f32_e32 v136, v136
	v_exp_f32_e32 v137, v137
	v_mul_f32_e32 v141, 0xbfb8aa3b, v73
	v_mul_f32_e32 v142, 0xbfb8aa3b, v74
	v_mul_f32_e32 v143, 0xbfb8aa3b, v75
	v_exp_f32_e32 v140, v140
	v_exp_f32_e32 v141, v141
	v_exp_f32_e32 v142, v142
	v_exp_f32_e32 v143, v143
	v_mul_f32_e32 v144, 0xbfb8aa3b, v64
	v_mul_f32_e32 v145, 0xbfb8aa3b, v65
	v_exp_f32_e32 v144, v144
	v_exp_f32_e32 v145, v145
	v_add_f32_e32 v134, 1.0, v134
	v_add_f32_e32 v135, 1.0, v135
	v_rcp_f32_e32 v132, v132
	v_rcp_f32_e32 v133, v133
	v_rcp_f32_e32 v134, v134
	v_rcp_f32_e32 v135, v135
	v_add_f32_e32 v136, 1.0, v136
	v_add_f32_e32 v137, 1.0, v137
	v_add_f32_e32 v138, 1.0, v138
	v_add_f32_e32 v139, 1.0, v139
	v_rcp_f32_e32 v136, v136
	v_rcp_f32_e32 v137, v137
	v_rcp_f32_e32 v138, v138
	v_rcp_f32_e32 v139, v139
	v_add_f32_e32 v140, 1.0, v140
	v_add_f32_e32 v141, 1.0, v141
	v_add_f32_e32 v142, 1.0, v142
	v_add_f32_e32 v143, 1.0, v143
	v_rcp_f32_e32 v140, v140
	v_rcp_f32_e32 v141, v141
	v_rcp_f32_e32 v142, v142
	v_rcp_f32_e32 v143, v143
	v_add_f32_e32 v144, 1.0, v144
	v_add_f32_e32 v145, 1.0, v145
	v_add_f32_e32 v147, 1.0, v147
	v_rcp_f32_e32 v144, v144
	v_rcp_f32_e32 v145, v145
	v_rcp_f32_e32 v146, v146
	v_rcp_f32_e32 v147, v147
	global_store_dwordx4 v[128:129], v[132:135], off offset:16 nt
	global_store_dwordx4 v[130:131], v[136:139], off offset:16 nt
	global_store_dwordx4 v[148:149], v[140:143], off offset:16 nt
	global_store_dwordx4 v[150:151], v[144:147], off offset:16 nt

.LBB0_517:
	v_cvt_pk_bf16_f32 v128, v128, v129
	v_cvt_pk_bf16_f32 v129, v130, v131
	v_cvt_pk_bf16_f32 v130, v132, v133
	v_mov_b64_e32 v[132:133], s[14:15]
	v_lshl_add_u32 v178, s6, 8, v211
	v_mad_i64_i32 v[132:133], s[30:31], v216, s64, v[132:133]
	v_cvt_pk_bf16_f32 v131, v134, v135
	v_lshl_add_u64 v[136:137], v[178:179], 1, v[132:133]
	s_and_b64 vcc, exec, s[0:1]
	s_mov_b64 s[30:31], -1
	global_store_dwordx4 v[136:137], v[128:131], off nt
	s_cbranch_vccnz .LBB0_521
	s_nop 0
	v_mul_f32_e32 v128, 0xbfb8aa3b, v116
	v_mul_f32_e32 v129, 0xbfb8aa3b, v117
	v_mul_f32_e32 v130, 0xbfb8aa3b, v118
	v_mul_f32_e32 v131, 0xbfb8aa3b, v119
	v_exp_f32_e32 v128, v128
	v_exp_f32_e32 v129, v129
	v_exp_f32_e32 v130, v130
	v_exp_f32_e32 v131, v131
	v_add_f32_e32 v128, 1.0, v128
	v_add_f32_e32 v129, 1.0, v129
	v_add_f32_e32 v130, 1.0, v130
	v_add_f32_e32 v131, 1.0, v131
	v_rcp_f32_e32 v128, v128
	v_rcp_f32_e32 v129, v129
	v_rcp_f32_e32 v130, v130
	v_rcp_f32_e32 v131, v131
	s_cbranch_execz .LBB0_522

.LBB0_525:
	v_cvt_pk_bf16_f32 v128, v128, v129
	v_cvt_pk_bf16_f32 v129, v130, v131
	v_cvt_pk_bf16_f32 v130, v132, v133
	v_cvt_pk_bf16_f32 v131, v134, v135
	v_or_b32_e32 v134, 16, v216
	v_mov_b64_e32 v[132:133], s[14:15]
	v_mad_i64_i32 v[132:133], s[30:31], v134, s64, v[132:133]
	v_lshl_add_u64 v[138:139], v[178:179], 1, v[132:133]
	s_and_b64 vcc, exec, s[0:1]
	s_mov_b64 s[30:31], -1
	global_store_dwordx4 v[138:139], v[128:131], off nt
	s_cbranch_vccnz .LBB0_529
	s_nop 0
	v_mul_f32_e32 v128, 0xbfb8aa3b, v108
	v_mul_f32_e32 v129, 0xbfb8aa3b, v109
	v_mul_f32_e32 v130, 0xbfb8aa3b, v110
	v_mul_f32_e32 v131, 0xbfb8aa3b, v111
	v_exp_f32_e32 v128, v128
	v_exp_f32_e32 v129, v129
	v_exp_f32_e32 v130, v130
	v_exp_f32_e32 v131, v131
	v_add_f32_e32 v128, 1.0, v128
	v_add_f32_e32 v129, 1.0, v129
	v_add_f32_e32 v130, 1.0, v130
	v_add_f32_e32 v131, 1.0, v131
	v_rcp_f32_e32 v128, v128
	v_rcp_f32_e32 v129, v129
	v_rcp_f32_e32 v130, v130
	v_rcp_f32_e32 v131, v131
	s_cbranch_execz .LBB0_530

.LBB0_533:
	v_cvt_pk_bf16_f32 v128, v128, v129
	v_cvt_pk_bf16_f32 v129, v130, v131
	v_cvt_pk_bf16_f32 v130, v132, v133
	v_cvt_pk_bf16_f32 v131, v134, v135
	v_or_b32_e32 v134, 32, v216
	v_mov_b64_e32 v[132:133], s[14:15]
	v_mad_i64_i32 v[132:133], s[30:31], v134, s64, v[132:133]
	v_lshl_add_u64 v[140:141], v[178:179], 1, v[132:133]
	s_and_b64 vcc, exec, s[0:1]
	s_mov_b64 s[30:31], -1
	global_store_dwordx4 v[140:141], v[128:131], off nt
	s_cbranch_vccnz .LBB0_537
	s_nop 0
	v_mul_f32_e32 v128, 0xbfb8aa3b, v100
	v_mul_f32_e32 v129, 0xbfb8aa3b, v101
	v_mul_f32_e32 v130, 0xbfb8aa3b, v102
	v_mul_f32_e32 v131, 0xbfb8aa3b, v103
	v_exp_f32_e32 v128, v128
	v_exp_f32_e32 v129, v129
	v_exp_f32_e32 v130, v130
	v_exp_f32_e32 v131, v131
	v_add_f32_e32 v128, 1.0, v128
	v_add_f32_e32 v129, 1.0, v129
	v_add_f32_e32 v130, 1.0, v130
	v_add_f32_e32 v131, 1.0, v131
	v_rcp_f32_e32 v128, v128
	v_rcp_f32_e32 v129, v129
	v_rcp_f32_e32 v130, v130
	v_rcp_f32_e32 v131, v131
	s_cbranch_execz .LBB0_538

.LBB0_541:
	v_cvt_pk_bf16_f32 v128, v128, v129
	v_cvt_pk_bf16_f32 v129, v130, v131
	v_cvt_pk_bf16_f32 v130, v132, v133
	v_cvt_pk_bf16_f32 v131, v134, v135
	v_or_b32_e32 v134, 48, v216
	v_mov_b64_e32 v[132:133], s[14:15]
	v_mad_i64_i32 v[132:133], s[30:31], v134, s64, v[132:133]
	v_lshl_add_u64 v[142:143], v[178:179], 1, v[132:133]
	s_and_b64 vcc, exec, s[0:1]
	s_mov_b64 s[30:31], -1
	global_store_dwordx4 v[142:143], v[128:131], off nt
	s_cbranch_vccnz .LBB0_545
	s_nop 0
	v_mul_f32_e32 v128, 0xbfb8aa3b, v92
	v_mul_f32_e32 v129, 0xbfb8aa3b, v93
	v_mul_f32_e32 v130, 0xbfb8aa3b, v94
	v_mul_f32_e32 v131, 0xbfb8aa3b, v95
	v_exp_f32_e32 v128, v128
	v_exp_f32_e32 v129, v129
	v_exp_f32_e32 v130, v130
	v_exp_f32_e32 v131, v131
	v_add_f32_e32 v128, 1.0, v128
	v_add_f32_e32 v129, 1.0, v129
	v_add_f32_e32 v130, 1.0, v130
	v_add_f32_e32 v131, 1.0, v131
	v_rcp_f32_e32 v128, v128
	v_rcp_f32_e32 v129, v129
	v_rcp_f32_e32 v130, v130
	v_rcp_f32_e32 v131, v131
	s_cbranch_execz .LBB0_546

.LBB0_549:
	v_cvt_pk_bf16_f32 v128, v128, v129
	v_cvt_pk_bf16_f32 v129, v130, v131
	v_add_u32_e32 v144, 0x80, v216
	v_cvt_pk_bf16_f32 v130, v132, v133
	v_mov_b64_e32 v[132:133], s[14:15]
	v_mad_i64_i32 v[132:133], s[30:31], v144, s64, v[132:133]
	v_cvt_pk_bf16_f32 v131, v134, v135
	v_lshl_add_u64 v[144:145], v[178:179], 1, v[132:133]
	s_and_b64 vcc, exec, s[0:1]
	s_mov_b64 s[30:31], -1
	global_store_dwordx4 v[144:145], v[128:131], off nt
	s_cbranch_vccnz .LBB0_553
	s_nop 0
	v_mul_f32_e32 v128, 0xbfb8aa3b, v84
	v_mul_f32_e32 v129, 0xbfb8aa3b, v85
	v_mul_f32_e32 v130, 0xbfb8aa3b, v86
	v_mul_f32_e32 v131, 0xbfb8aa3b, v87
	v_exp_f32_e32 v128, v128
	v_exp_f32_e32 v129, v129
	v_exp_f32_e32 v130, v130
	v_exp_f32_e32 v131, v131
	v_add_f32_e32 v128, 1.0, v128
	v_add_f32_e32 v129, 1.0, v129
	v_add_f32_e32 v130, 1.0, v130
	v_add_f32_e32 v131, 1.0, v131
	v_rcp_f32_e32 v128, v128
	v_rcp_f32_e32 v129, v129
	v_rcp_f32_e32 v130, v130
	v_rcp_f32_e32 v131, v131
	s_cbranch_execz .LBB0_554

.LBB0_557:
	v_cvt_pk_bf16_f32 v128, v128, v129
	v_cvt_pk_bf16_f32 v129, v130, v131
	v_cvt_pk_bf16_f32 v130, v132, v133
	v_cvt_pk_bf16_f32 v131, v134, v135
	v_add_u32_e32 v134, 0x90, v216
	v_mov_b64_e32 v[132:133], s[14:15]
	v_mad_i64_i32 v[132:133], s[30:31], v134, s64, v[132:133]
	v_lshl_add_u64 v[146:147], v[178:179], 1, v[132:133]
	s_and_b64 vcc, exec, s[0:1]
	s_mov_b64 s[30:31], -1
	global_store_dwordx4 v[146:147], v[128:131], off nt
	s_cbranch_vccnz .LBB0_561
	s_nop 0
	v_mul_f32_e32 v128, 0xbfb8aa3b, v76
	v_mul_f32_e32 v129, 0xbfb8aa3b, v77
	v_mul_f32_e32 v130, 0xbfb8aa3b, v78
	v_mul_f32_e32 v131, 0xbfb8aa3b, v79
	v_exp_f32_e32 v128, v128
	v_exp_f32_e32 v129, v129
	v_exp_f32_e32 v130, v130
	v_exp_f32_e32 v131, v131
	v_add_f32_e32 v128, 1.0, v128
	v_add_f32_e32 v129, 1.0, v129
	v_add_f32_e32 v130, 1.0, v130
	v_add_f32_e32 v131, 1.0, v131
	v_rcp_f32_e32 v128, v128
	v_rcp_f32_e32 v129, v129
	v_rcp_f32_e32 v130, v130
	v_rcp_f32_e32 v131, v131
	s_cbranch_execz .LBB0_562

.LBB0_565:
	v_cvt_pk_bf16_f32 v128, v128, v129
	v_cvt_pk_bf16_f32 v129, v130, v131
	v_cvt_pk_bf16_f32 v130, v132, v133
	v_cvt_pk_bf16_f32 v131, v134, v135
	v_add_u32_e32 v134, 0xa0, v216
	v_mov_b64_e32 v[132:133], s[14:15]
	v_mad_i64_i32 v[132:133], s[30:31], v134, s64, v[132:133]
	v_lshl_add_u64 v[148:149], v[178:179], 1, v[132:133]
	s_and_b64 vcc, exec, s[0:1]
	s_mov_b64 s[30:31], -1
	global_store_dwordx4 v[148:149], v[128:131], off nt
	s_cbranch_vccnz .LBB0_569
	s_nop 0
	v_mul_f32_e32 v128, 0xbfb8aa3b, v68
	v_mul_f32_e32 v129, 0xbfb8aa3b, v69
	v_mul_f32_e32 v130, 0xbfb8aa3b, v70
	v_mul_f32_e32 v131, 0xbfb8aa3b, v71
	v_exp_f32_e32 v128, v128
	v_exp_f32_e32 v129, v129
	v_exp_f32_e32 v130, v130
	v_exp_f32_e32 v131, v131
	v_add_f32_e32 v128, 1.0, v128
	v_add_f32_e32 v129, 1.0, v129
	v_add_f32_e32 v130, 1.0, v130
	v_add_f32_e32 v131, 1.0, v131
	v_rcp_f32_e32 v128, v128
	v_rcp_f32_e32 v129, v129
	v_rcp_f32_e32 v130, v130
	v_rcp_f32_e32 v131, v131
	s_cbranch_execz .LBB0_570

.LBB0_573:
	v_cvt_pk_bf16_f32 v128, v128, v129
	v_cvt_pk_bf16_f32 v129, v130, v131
	v_cvt_pk_bf16_f32 v130, v132, v133
	v_cvt_pk_bf16_f32 v131, v134, v135
	v_add_u32_e32 v134, 0xb0, v216
	v_mov_b64_e32 v[132:133], s[14:15]
	v_mad_i64_i32 v[132:133], s[30:31], v134, s64, v[132:133]
	v_lshl_add_u64 v[150:151], v[178:179], 1, v[132:133]
	s_and_b64 vcc, exec, s[0:1]
	s_mov_b64 s[30:31], -1
	global_store_dwordx4 v[150:151], v[128:131], off nt
	s_cbranch_vccnz .LBB0_577
	s_nop 0
	v_mul_f32_e32 v128, 0xbfb8aa3b, v60
	v_mul_f32_e32 v129, 0xbfb8aa3b, v61
	v_mul_f32_e32 v130, 0xbfb8aa3b, v62
	v_mul_f32_e32 v131, 0xbfb8aa3b, v63
	v_exp_f32_e32 v128, v128
	v_exp_f32_e32 v129, v129
	v_exp_f32_e32 v130, v130
	v_exp_f32_e32 v131, v131
	v_add_f32_e32 v128, 1.0, v128
	v_add_f32_e32 v129, 1.0, v129
	v_add_f32_e32 v130, 1.0, v130
	v_add_f32_e32 v131, 1.0, v131
	v_rcp_f32_e32 v128, v128
	v_rcp_f32_e32 v129, v129
	v_rcp_f32_e32 v130, v130
	v_rcp_f32_e32 v131, v131
	s_cbranch_execz .LBB0_578

.LBB0_581:
	v_cvt_pk_bf16_f32 v128, v128, v129
	v_cvt_pk_bf16_f32 v129, v130, v131
	v_cvt_pk_bf16_f32 v130, v132, v133
	v_cvt_pk_bf16_f32 v131, v134, v135
	s_and_b64 vcc, exec, s[0:1]
	s_mov_b64 s[30:31], -1
	global_store_dwordx4 v[136:137], v[128:131], off offset:256 nt
	s_cbranch_vccnz .LBB0_585
	s_nop 0
	v_mul_f32_e32 v128, 0xbfb8aa3b, v52
	v_mul_f32_e32 v129, 0xbfb8aa3b, v53
	v_mul_f32_e32 v130, 0xbfb8aa3b, v54
	v_mul_f32_e32 v131, 0xbfb8aa3b, v55
	v_exp_f32_e32 v128, v128
	v_exp_f32_e32 v129, v129
	v_exp_f32_e32 v130, v130
	v_exp_f32_e32 v131, v131
	v_add_f32_e32 v128, 1.0, v128
	v_add_f32_e32 v129, 1.0, v129
	v_add_f32_e32 v130, 1.0, v130
	v_add_f32_e32 v131, 1.0, v131
	v_rcp_f32_e32 v128, v128
	v_rcp_f32_e32 v129, v129
	v_rcp_f32_e32 v130, v130
	v_rcp_f32_e32 v131, v131
	s_cbranch_execz .LBB0_586

.LBB0_589:
	v_cvt_pk_bf16_f32 v128, v128, v129
	v_cvt_pk_bf16_f32 v129, v130, v131
	v_cvt_pk_bf16_f32 v130, v132, v133
	v_cvt_pk_bf16_f32 v131, v134, v135
	s_and_b64 vcc, exec, s[0:1]
	s_mov_b64 s[30:31], -1
	global_store_dwordx4 v[138:139], v[128:131], off offset:256 nt
	s_cbranch_vccnz .LBB0_593
	s_nop 0
	v_mul_f32_e32 v128, 0xbfb8aa3b, v44
	v_mul_f32_e32 v129, 0xbfb8aa3b, v45
	v_mul_f32_e32 v130, 0xbfb8aa3b, v46
	v_mul_f32_e32 v131, 0xbfb8aa3b, v47
	v_exp_f32_e32 v128, v128
	v_exp_f32_e32 v129, v129
	v_exp_f32_e32 v130, v130
	v_exp_f32_e32 v131, v131
	v_add_f32_e32 v128, 1.0, v128
	v_add_f32_e32 v129, 1.0, v129
	v_add_f32_e32 v130, 1.0, v130
	v_add_f32_e32 v131, 1.0, v131
	v_rcp_f32_e32 v128, v128
	v_rcp_f32_e32 v129, v129
	v_rcp_f32_e32 v130, v130
	v_rcp_f32_e32 v131, v131
	s_cbranch_execz .LBB0_594

.LBB0_597:
	v_cvt_pk_bf16_f32 v128, v128, v129
	v_cvt_pk_bf16_f32 v129, v130, v131
	v_cvt_pk_bf16_f32 v130, v132, v133
	v_cvt_pk_bf16_f32 v131, v134, v135
	s_and_b64 vcc, exec, s[0:1]
	s_mov_b64 s[30:31], -1
	global_store_dwordx4 v[140:141], v[128:131], off offset:256 nt
	s_cbranch_vccnz .LBB0_601
	s_nop 0
	v_mul_f32_e32 v128, 0xbfb8aa3b, v36
	v_mul_f32_e32 v129, 0xbfb8aa3b, v37
	v_mul_f32_e32 v130, 0xbfb8aa3b, v38
	v_mul_f32_e32 v131, 0xbfb8aa3b, v39
	v_exp_f32_e32 v128, v128
	v_exp_f32_e32 v129, v129
	v_exp_f32_e32 v130, v130
	v_exp_f32_e32 v131, v131
	v_add_f32_e32 v128, 1.0, v128
	v_add_f32_e32 v129, 1.0, v129
	v_add_f32_e32 v130, 1.0, v130
	v_add_f32_e32 v131, 1.0, v131
	v_rcp_f32_e32 v128, v128
	v_rcp_f32_e32 v129, v129
	v_rcp_f32_e32 v130, v130
	v_rcp_f32_e32 v131, v131
	s_cbranch_execz .LBB0_602

.LBB0_605:
	v_cvt_pk_bf16_f32 v128, v128, v129
	v_cvt_pk_bf16_f32 v129, v130, v131
	v_cvt_pk_bf16_f32 v130, v132, v133
	v_cvt_pk_bf16_f32 v131, v134, v135
	s_and_b64 vcc, exec, s[0:1]
	s_mov_b64 s[30:31], -1
	global_store_dwordx4 v[142:143], v[128:131], off offset:256 nt
	s_cbranch_vccnz .LBB0_609
	s_nop 0
	v_mul_f32_e32 v128, 0xbfb8aa3b, v28
	v_mul_f32_e32 v129, 0xbfb8aa3b, v29
	v_mul_f32_e32 v130, 0xbfb8aa3b, v30
	v_mul_f32_e32 v131, 0xbfb8aa3b, v31
	v_exp_f32_e32 v128, v128
	v_exp_f32_e32 v129, v129
	v_exp_f32_e32 v130, v130
	v_exp_f32_e32 v131, v131
	v_add_f32_e32 v128, 1.0, v128
	v_add_f32_e32 v129, 1.0, v129
	v_add_f32_e32 v130, 1.0, v130
	v_add_f32_e32 v131, 1.0, v131
	v_rcp_f32_e32 v128, v128
	v_rcp_f32_e32 v129, v129
	v_rcp_f32_e32 v130, v130
	v_rcp_f32_e32 v131, v131
	s_cbranch_execz .LBB0_610

.LBB0_613:
	v_cvt_pk_bf16_f32 v128, v128, v129
	v_cvt_pk_bf16_f32 v129, v130, v131
	v_cvt_pk_bf16_f32 v130, v132, v133
	v_cvt_pk_bf16_f32 v131, v134, v135
	s_and_b64 vcc, exec, s[0:1]
	s_mov_b64 s[30:31], -1
	global_store_dwordx4 v[144:145], v[128:131], off offset:256 nt
	s_cbranch_vccnz .LBB0_617
	s_nop 0
	v_mul_f32_e32 v128, 0xbfb8aa3b, v20
	v_mul_f32_e32 v129, 0xbfb8aa3b, v21
	v_mul_f32_e32 v130, 0xbfb8aa3b, v22
	v_mul_f32_e32 v131, 0xbfb8aa3b, v23
	v_exp_f32_e32 v128, v128
	v_exp_f32_e32 v129, v129
	v_exp_f32_e32 v130, v130
	v_exp_f32_e32 v131, v131
	v_add_f32_e32 v128, 1.0, v128
	v_add_f32_e32 v129, 1.0, v129
	v_add_f32_e32 v130, 1.0, v130
	v_add_f32_e32 v131, 1.0, v131
	v_rcp_f32_e32 v128, v128
	v_rcp_f32_e32 v129, v129
	v_rcp_f32_e32 v130, v130
	v_rcp_f32_e32 v131, v131
	s_cbranch_execz .LBB0_618

.LBB0_621:
	v_cvt_pk_bf16_f32 v128, v128, v129
	v_cvt_pk_bf16_f32 v129, v130, v131
	v_cvt_pk_bf16_f32 v130, v132, v133
	v_cvt_pk_bf16_f32 v131, v134, v135
	s_and_b64 vcc, exec, s[0:1]
	s_mov_b64 s[30:31], -1
	global_store_dwordx4 v[146:147], v[128:131], off offset:256 nt
	s_cbranch_vccnz .LBB0_625
	s_nop 0
	v_mul_f32_e32 v128, 0xbfb8aa3b, v12
	v_mul_f32_e32 v129, 0xbfb8aa3b, v13
	v_mul_f32_e32 v130, 0xbfb8aa3b, v14
	v_mul_f32_e32 v131, 0xbfb8aa3b, v15
	v_exp_f32_e32 v128, v128
	v_exp_f32_e32 v129, v129
	v_exp_f32_e32 v130, v130
	v_exp_f32_e32 v131, v131
	v_add_f32_e32 v128, 1.0, v128
	v_add_f32_e32 v129, 1.0, v129
	v_add_f32_e32 v130, 1.0, v130
	v_add_f32_e32 v131, 1.0, v131
	v_rcp_f32_e32 v128, v128
	v_rcp_f32_e32 v129, v129
	v_rcp_f32_e32 v130, v130
	v_rcp_f32_e32 v131, v131
	s_cbranch_execz .LBB0_626

.LBB0_629:
	v_cvt_pk_bf16_f32 v128, v128, v129
	v_cvt_pk_bf16_f32 v129, v130, v131
	v_cvt_pk_bf16_f32 v130, v132, v133
	v_cvt_pk_bf16_f32 v131, v134, v135
	s_and_b64 vcc, exec, s[0:1]
	s_mov_b64 s[30:31], -1
	global_store_dwordx4 v[148:149], v[128:131], off offset:256 nt
	s_cbranch_vccnz .LBB0_633
	s_nop 0
	v_mul_f32_e32 v128, 0xbfb8aa3b, v4
	v_mul_f32_e32 v129, 0xbfb8aa3b, v5
	v_mul_f32_e32 v130, 0xbfb8aa3b, v6
	v_mul_f32_e32 v131, 0xbfb8aa3b, v7
	v_exp_f32_e32 v128, v128
	v_exp_f32_e32 v129, v129
	v_exp_f32_e32 v130, v130
	v_exp_f32_e32 v131, v131
	v_add_f32_e32 v128, 1.0, v128
	v_add_f32_e32 v129, 1.0, v129
	v_add_f32_e32 v130, 1.0, v130
	v_add_f32_e32 v131, 1.0, v131
	v_rcp_f32_e32 v128, v128
	v_rcp_f32_e32 v129, v129
	v_rcp_f32_e32 v130, v130
	v_rcp_f32_e32 v131, v131
	s_cbranch_execz .LBB0_634

.LBB0_637:
	v_cvt_pk_bf16_f32 v128, v128, v129
	v_cvt_pk_bf16_f32 v129, v130, v131
	v_cvt_pk_bf16_f32 v130, v132, v133
	v_cvt_pk_bf16_f32 v131, v134, v135
	global_store_dwordx4 v[150:151], v[128:131], off offset:256 nt

.LBB0_651:
	v_cndmask_b32_e64 v200, 1.0, v215, s[6:7]
	v_lshlrev_b32_e32 v178, 1, v180
	v_pk_mul_f32 v[122:123], v[200:201], v[122:123] op_sel_hi:[0,1]
	v_pk_mul_f32 v[120:121], v[200:201], v[120:121] op_sel_hi:[0,1]
	v_lshl_add_u64 v[198:199], s[34:35], 0, v[178:179]
	v_pk_mul_f32 v[126:127], v[200:201], v[126:127] op_sel_hi:[0,1]
	v_pk_mul_f32 v[124:125], v[200:201], v[124:125] op_sel_hi:[0,1]
	v_cvt_pk_bf16_f32 v120, v120, v121
	v_cvt_pk_bf16_f32 v121, v122, v123
	v_mad_i64_i32 v[122:123], s[6:7], s30, v216, 0
	v_cvt_pk_bf16_f32 v124, v124, v125
	v_cvt_pk_bf16_f32 v125, v126, v127
	v_lshl_add_u64 v[122:123], v[122:123], 1, v[198:199]
	s_and_b64 vcc, exec, s[0:1]
	s_mov_b64 s[6:7], -1
	global_store_dwordx2 v[122:123], v[124:125], off nt
	global_store_dwordx2 v[122:123], v[120:121], off offset:64 nt
	s_cbranch_vccnz .LBB0_656
	s_cmp_lt_i32 s10, 4
	s_cbranch_scc1 .LBB0_654
	s_cmp_eq_u32 s10, 4
	s_cselect_b64 s[6:7], -1, 0
	s_cbranch_execz .LBB0_655
	s_branch .LBB0_656

.LBB0_658:
	v_mov_b32_e32 v201, v200
	v_mov_b32_e32 v122, v200
	v_mov_b32_e32 v123, v200
	v_or_b32_e32 v120, 16, v216
	v_pk_mul_f32 v[114:115], v[122:123], v[114:115]
	v_pk_mul_f32 v[112:113], v[200:201], v[112:113]
	v_pk_mul_f32 v[118:119], v[122:123], v[118:119]
	v_pk_mul_f32 v[116:117], v[200:201], v[116:117]
	v_cvt_pk_bf16_f32 v112, v112, v113
	v_cvt_pk_bf16_f32 v113, v114, v115
	v_mad_i64_i32 v[114:115], s[6:7], s30, v120, 0
	v_cvt_pk_bf16_f32 v116, v116, v117
	v_cvt_pk_bf16_f32 v117, v118, v119
	v_lshl_add_u64 v[114:115], v[114:115], 1, v[198:199]
	s_and_b64 vcc, exec, s[0:1]
	s_mov_b64 s[6:7], -1
	global_store_dwordx2 v[114:115], v[116:117], off nt
	global_store_dwordx2 v[114:115], v[112:113], off offset:64 nt
	s_cbranch_vccnz .LBB0_663
	s_cmp_lt_i32 s10, 4
	s_cbranch_scc1 .LBB0_661
	s_cmp_eq_u32 s10, 4
	s_cselect_b64 s[6:7], -1, 0
	s_cbranch_execz .LBB0_662
	s_branch .LBB0_663

.LBB0_665:
	v_mov_b32_e32 v114, v200
	v_mov_b32_e32 v115, v200
	v_or_b32_e32 v112, 32, v216
	v_pk_mul_f32 v[106:107], v[114:115], v[106:107]
	v_pk_mul_f32 v[104:105], v[200:201], v[104:105]
	v_pk_mul_f32 v[110:111], v[114:115], v[110:111]
	v_pk_mul_f32 v[108:109], v[200:201], v[108:109]
	v_cvt_pk_bf16_f32 v104, v104, v105
	v_cvt_pk_bf16_f32 v105, v106, v107
	v_mad_i64_i32 v[106:107], s[6:7], s30, v112, 0
	v_cvt_pk_bf16_f32 v108, v108, v109
	v_cvt_pk_bf16_f32 v109, v110, v111
	v_lshl_add_u64 v[106:107], v[106:107], 1, v[198:199]
	s_and_b64 vcc, exec, s[0:1]
	s_mov_b64 s[6:7], -1
	global_store_dwordx2 v[106:107], v[108:109], off nt
	global_store_dwordx2 v[106:107], v[104:105], off offset:64 nt
	s_cbranch_vccnz .LBB0_670
	s_cmp_lt_i32 s10, 4
	s_cbranch_scc1 .LBB0_668
	s_cmp_eq_u32 s10, 4
	s_cselect_b64 s[6:7], -1, 0
	s_cbranch_execz .LBB0_669
	s_branch .LBB0_670

.LBB0_672:
	v_mov_b32_e32 v106, v200
	v_mov_b32_e32 v107, v200
	v_or_b32_e32 v104, 48, v216
	v_pk_mul_f32 v[98:99], v[106:107], v[98:99]
	v_pk_mul_f32 v[96:97], v[200:201], v[96:97]
	v_pk_mul_f32 v[102:103], v[106:107], v[102:103]
	v_pk_mul_f32 v[100:101], v[200:201], v[100:101]
	v_cvt_pk_bf16_f32 v96, v96, v97
	v_cvt_pk_bf16_f32 v97, v98, v99
	v_mad_i64_i32 v[98:99], s[6:7], s30, v104, 0
	v_cvt_pk_bf16_f32 v100, v100, v101
	v_cvt_pk_bf16_f32 v101, v102, v103
	v_lshl_add_u64 v[98:99], v[98:99], 1, v[198:199]
	s_and_b64 vcc, exec, s[0:1]
	s_mov_b64 s[6:7], -1
	global_store_dwordx2 v[98:99], v[100:101], off nt
	global_store_dwordx2 v[98:99], v[96:97], off offset:64 nt
	s_cbranch_vccnz .LBB0_677
	s_cmp_lt_i32 s10, 4
	s_cbranch_scc1 .LBB0_675
	s_cmp_eq_u32 s10, 4
	s_cselect_b64 s[6:7], -1, 0
	s_cbranch_execz .LBB0_676
	s_branch .LBB0_677

.LBB0_686:
	v_mov_b32_e32 v98, v200
	v_mov_b32_e32 v99, v200
	v_add_u32_e32 v97, 0x80, v216
	v_pk_mul_f32 v[90:91], v[98:99], v[90:91]
	v_pk_mul_f32 v[88:89], v[200:201], v[88:89]
	v_pk_mul_f32 v[94:95], v[98:99], v[94:95]
	v_pk_mul_f32 v[92:93], v[200:201], v[92:93]
	v_cvt_pk_bf16_f32 v88, v88, v89
	v_cvt_pk_bf16_f32 v89, v90, v91
	v_mad_i64_i32 v[90:91], s[6:7], s30, v97, 0
	v_cvt_pk_bf16_f32 v92, v92, v93
	v_cvt_pk_bf16_f32 v93, v94, v95
	v_lshl_add_u64 v[90:91], v[90:91], 1, v[198:199]
	s_and_b64 vcc, exec, s[0:1]
	s_mov_b64 s[6:7], -1
	global_store_dwordx2 v[90:91], v[92:93], off nt
	global_store_dwordx2 v[90:91], v[88:89], off offset:64 nt
	s_cbranch_vccnz .LBB0_691
	s_cmp_lt_i32 s10, 4
	s_cbranch_scc1 .LBB0_689
	s_cmp_eq_u32 s10, 4
	s_cselect_b64 s[6:7], -1, 0
	s_cbranch_execz .LBB0_690
	s_branch .LBB0_691

.LBB0_693:
	v_mov_b32_e32 v90, v200
	v_mov_b32_e32 v91, v200
	v_add_u32_e32 v88, 0x90, v216
	v_pk_mul_f32 v[82:83], v[90:91], v[82:83]
	v_pk_mul_f32 v[80:81], v[200:201], v[80:81]
	v_pk_mul_f32 v[86:87], v[90:91], v[86:87]
	v_pk_mul_f32 v[84:85], v[200:201], v[84:85]
	v_cvt_pk_bf16_f32 v80, v80, v81
	v_cvt_pk_bf16_f32 v81, v82, v83
	v_mad_i64_i32 v[82:83], s[6:7], s30, v88, 0
	v_cvt_pk_bf16_f32 v84, v84, v85
	v_cvt_pk_bf16_f32 v85, v86, v87
	v_lshl_add_u64 v[82:83], v[82:83], 1, v[198:199]
	s_and_b64 vcc, exec, s[0:1]
	s_mov_b64 s[6:7], -1
	global_store_dwordx2 v[82:83], v[84:85], off nt
	global_store_dwordx2 v[82:83], v[80:81], off offset:64 nt
	s_cbranch_vccnz .LBB0_698
	s_cmp_lt_i32 s10, 4
	s_cbranch_scc1 .LBB0_696
	s_cmp_eq_u32 s10, 4
	s_cselect_b64 s[6:7], -1, 0
	s_cbranch_execz .LBB0_697
	s_branch .LBB0_698

.LBB0_700:
	v_mov_b32_e32 v82, v200
	v_mov_b32_e32 v83, v200
	v_add_u32_e32 v80, 0xa0, v216
	v_pk_mul_f32 v[74:75], v[82:83], v[74:75]
	v_pk_mul_f32 v[72:73], v[200:201], v[72:73]
	v_pk_mul_f32 v[78:79], v[82:83], v[78:79]
	v_pk_mul_f32 v[76:77], v[200:201], v[76:77]
	v_cvt_pk_bf16_f32 v72, v72, v73
	v_cvt_pk_bf16_f32 v73, v74, v75
	v_mad_i64_i32 v[74:75], s[6:7], s30, v80, 0
	v_cvt_pk_bf16_f32 v76, v76, v77
	v_cvt_pk_bf16_f32 v77, v78, v79
	v_lshl_add_u64 v[74:75], v[74:75], 1, v[198:199]
	s_and_b64 vcc, exec, s[0:1]
	s_mov_b64 s[0:1], -1
	global_store_dwordx2 v[74:75], v[76:77], off nt
	global_store_dwordx2 v[74:75], v[72:73], off offset:64 nt
	s_cbranch_vccnz .LBB0_705
	s_cmp_lt_i32 s10, 4
	s_cbranch_scc1 .LBB0_703
	s_cmp_eq_u32 s10, 4
	s_cselect_b64 s[0:1], -1, 0
	s_cbranch_execz .LBB0_704
	s_branch .LBB0_705

.LBB0_707:
	v_mov_b32_e32 v74, v200
	v_mov_b32_e32 v75, v200
	v_add_u32_e32 v72, 0xb0, v216
	v_pk_mul_f32 v[66:67], v[74:75], v[66:67]
	v_pk_mul_f32 v[64:65], v[200:201], v[64:65]
	s_or_b32 s25, s23, 2
	v_cvt_pk_bf16_f32 v64, v64, v65
	v_cvt_pk_bf16_f32 v65, v66, v67
	v_mad_i64_i32 v[66:67], s[0:1], s30, v72, 0
	s_cmp_lt_i32 s25, 8
	v_pk_mul_f32 v[70:71], v[74:75], v[70:71]
	v_pk_mul_f32 v[68:69], v[200:201], v[68:69]
	s_cselect_b64 s[0:1], -1, 0
	v_cvt_pk_bf16_f32 v68, v68, v69
	v_cvt_pk_bf16_f32 v69, v70, v71
	v_lshl_add_u64 v[66:67], v[66:67], 1, v[198:199]
	s_mov_b64 s[6:7], -1
	s_and_b64 vcc, exec, s[0:1]
	global_store_dwordx2 v[66:67], v[68:69], off nt
	global_store_dwordx2 v[66:67], v[64:65], off offset:64 nt
	s_cbranch_vccnz .LBB0_716
	s_lshl_b32 s6, s23, 6
	s_add_i32 s10, s6, 0xfffffe80
	s_lshl_b64 s[6:7], s[10:11], 1
	s_add_u32 s34, s53, s6
	s_addc_u32 s35, s54, s7
	s_mov_b64 s[30:31], 0x300
	s_cbranch_execz .LBB0_717

.LBB0_711:
	s_waitcnt vmcnt(0)
	v_pk_mul_f32 v[74:75], v[58:59], v[150:151]
	v_pk_mul_f32 v[76:77], v[56:57], v[148:149]
	v_pk_mul_f32 v[68:69], v[58:59], v[146:147]
	v_pk_mul_f32 v[70:71], v[56:57], v[144:145]
	v_pk_fma_f32 v[74:75], v[62:63], v[146:147], v[74:75]
	v_pk_fma_f32 v[76:77], v[60:61], v[144:145], v[76:77]
	v_cndmask_b32_e64 v66, 1.0, v215, s[0:1]
	v_pk_fma_f32 v[68:69], v[62:63], v[150:151], v[68:69] neg_lo:[0,0,1] neg_hi:[0,0,1]
	v_pk_fma_f32 v[70:71], v[60:61], v[148:149], v[70:71] neg_lo:[0,0,1] neg_hi:[0,0,1]
	v_cndmask_b32_e64 v59, v59, v75, s[0:1]
	v_cndmask_b32_e64 v58, v58, v74, s[0:1]
	v_cndmask_b32_e64 v57, v57, v77, s[0:1]
	v_cndmask_b32_e64 v56, v56, v76, s[0:1]
	v_cndmask_b32_e64 v63, v63, v69, s[0:1]
	v_cndmask_b32_e64 v62, v62, v68, s[0:1]
	v_cndmask_b32_e64 v61, v61, v71, s[0:1]
	v_cndmask_b32_e64 v60, v60, v70, s[0:1]
	v_pk_mul_f32 v[58:59], v[66:67], v[58:59] op_sel_hi:[0,1]
	v_pk_mul_f32 v[56:57], v[66:67], v[56:57] op_sel_hi:[0,1]
	v_lshl_add_u64 v[64:65], s[34:35], 0, v[178:179]
	v_pk_mul_f32 v[62:63], v[66:67], v[62:63] op_sel_hi:[0,1]
	v_pk_mul_f32 v[60:61], v[66:67], v[60:61] op_sel_hi:[0,1]
	v_cvt_pk_bf16_f32 v56, v56, v57
	v_cvt_pk_bf16_f32 v57, v58, v59
	v_mad_i64_i32 v[58:59], s[34:35], s30, v216, 0
	v_cvt_pk_bf16_f32 v60, v60, v61
	v_cvt_pk_bf16_f32 v61, v62, v63
	v_lshl_add_u64 v[58:59], v[58:59], 1, v[64:65]
	global_store_dwordx2 v[58:59], v[60:61], off nt
	global_store_dwordx2 v[58:59], v[56:57], off offset:64 nt
	v_pk_mul_f32 v[60:61], v[50:51], v[142:143]
	v_pk_mul_f32 v[62:63], v[48:49], v[140:141]
	v_pk_mul_f32 v[56:57], v[50:51], v[138:139]
	v_pk_mul_f32 v[58:59], v[48:49], v[136:137]
	v_pk_fma_f32 v[60:61], v[54:55], v[138:139], v[60:61]
	v_pk_fma_f32 v[62:63], v[52:53], v[136:137], v[62:63]
	v_pk_fma_f32 v[56:57], v[54:55], v[142:143], v[56:57] neg_lo:[0,0,1] neg_hi:[0,0,1]
	v_pk_fma_f32 v[58:59], v[52:53], v[140:141], v[58:59] neg_lo:[0,0,1] neg_hi:[0,0,1]
	v_cndmask_b32_e64 v49, v49, v63, s[0:1]
	v_cndmask_b32_e64 v48, v48, v62, s[0:1]
	v_cndmask_b32_e64 v51, v51, v61, s[0:1]
	v_cndmask_b32_e64 v50, v50, v60, s[0:1]
	v_cndmask_b32_e64 v53, v53, v59, s[0:1]
	v_cndmask_b32_e64 v52, v52, v58, s[0:1]
	v_cndmask_b32_e64 v55, v55, v57, s[0:1]
	v_cndmask_b32_e64 v54, v54, v56, s[0:1]
	v_pk_mul_f32 v[50:51], v[66:67], v[50:51] op_sel_hi:[0,1]
	v_pk_mul_f32 v[48:49], v[66:67], v[48:49] op_sel_hi:[0,1]
	v_pk_mul_f32 v[54:55], v[66:67], v[54:55] op_sel_hi:[0,1]
	v_pk_mul_f32 v[52:53], v[66:67], v[52:53] op_sel_hi:[0,1]
	v_cvt_pk_bf16_f32 v48, v48, v49
	v_cvt_pk_bf16_f32 v49, v50, v51
	v_mad_i64_i32 v[50:51], s[34:35], s30, v120, 0
	v_cvt_pk_bf16_f32 v52, v52, v53
	v_cvt_pk_bf16_f32 v53, v54, v55
	v_lshl_add_u64 v[50:51], v[50:51], 1, v[64:65]
	global_store_dwordx2 v[50:51], v[52:53], off nt
	global_store_dwordx2 v[50:51], v[48:49], off offset:64 nt
	v_pk_mul_f32 v[52:53], v[42:43], v[134:135]
	v_pk_mul_f32 v[54:55], v[40:41], v[132:133]
	v_pk_mul_f32 v[48:49], v[42:43], v[130:131]
	v_pk_mul_f32 v[50:51], v[40:41], v[128:129]
	v_pk_fma_f32 v[52:53], v[46:47], v[130:131], v[52:53]
	v_pk_fma_f32 v[54:55], v[44:45], v[128:129], v[54:55]
	v_pk_fma_f32 v[48:49], v[46:47], v[134:135], v[48:49] neg_lo:[0,0,1] neg_hi:[0,0,1]
	v_pk_fma_f32 v[50:51], v[44:45], v[132:133], v[50:51] neg_lo:[0,0,1] neg_hi:[0,0,1]
	v_cndmask_b32_e64 v41, v41, v55, s[0:1]
	v_cndmask_b32_e64 v40, v40, v54, s[0:1]
	v_cndmask_b32_e64 v43, v43, v53, s[0:1]
	v_cndmask_b32_e64 v42, v42, v52, s[0:1]
	v_cndmask_b32_e64 v45, v45, v51, s[0:1]
	v_cndmask_b32_e64 v44, v44, v50, s[0:1]
	v_cndmask_b32_e64 v47, v47, v49, s[0:1]
	v_cndmask_b32_e64 v46, v46, v48, s[0:1]
	v_pk_mul_f32 v[42:43], v[66:67], v[42:43] op_sel_hi:[0,1]
	v_pk_mul_f32 v[40:41], v[66:67], v[40:41] op_sel_hi:[0,1]
	v_pk_mul_f32 v[46:47], v[66:67], v[46:47] op_sel_hi:[0,1]
	v_pk_mul_f32 v[44:45], v[66:67], v[44:45] op_sel_hi:[0,1]
	v_cvt_pk_bf16_f32 v40, v40, v41
	v_cvt_pk_bf16_f32 v41, v42, v43
	v_mad_i64_i32 v[42:43], s[34:35], s30, v112, 0
	v_cvt_pk_bf16_f32 v44, v44, v45
	v_cvt_pk_bf16_f32 v45, v46, v47
	v_lshl_add_u64 v[42:43], v[42:43], 1, v[64:65]
	global_store_dwordx2 v[42:43], v[44:45], off nt
	global_store_dwordx2 v[42:43], v[40:41], off offset:64 nt
	v_pk_mul_f32 v[44:45], v[34:35], v[158:159]
	v_pk_mul_f32 v[46:47], v[32:33], v[156:157]
	v_pk_mul_f32 v[40:41], v[34:35], v[154:155]
	v_pk_mul_f32 v[42:43], v[32:33], v[152:153]
	v_pk_fma_f32 v[44:45], v[38:39], v[154:155], v[44:45]
	v_pk_fma_f32 v[46:47], v[36:37], v[152:153], v[46:47]
	v_pk_fma_f32 v[40:41], v[38:39], v[158:159], v[40:41] neg_lo:[0,0,1] neg_hi:[0,0,1]
	v_pk_fma_f32 v[42:43], v[36:37], v[156:157], v[42:43] neg_lo:[0,0,1] neg_hi:[0,0,1]
	v_cndmask_b32_e64 v33, v33, v47, s[0:1]
	v_cndmask_b32_e64 v32, v32, v46, s[0:1]
	v_cndmask_b32_e64 v35, v35, v45, s[0:1]
	v_cndmask_b32_e64 v34, v34, v44, s[0:1]
	v_cndmask_b32_e64 v37, v37, v43, s[0:1]
	v_cndmask_b32_e64 v36, v36, v42, s[0:1]
	v_cndmask_b32_e64 v39, v39, v41, s[0:1]
	v_cndmask_b32_e64 v38, v38, v40, s[0:1]
	v_pk_mul_f32 v[34:35], v[66:67], v[34:35] op_sel_hi:[0,1]
	v_pk_mul_f32 v[32:33], v[66:67], v[32:33] op_sel_hi:[0,1]
	v_pk_mul_f32 v[38:39], v[66:67], v[38:39] op_sel_hi:[0,1]
	v_pk_mul_f32 v[36:37], v[66:67], v[36:37] op_sel_hi:[0,1]
	v_cvt_pk_bf16_f32 v32, v32, v33
	v_cvt_pk_bf16_f32 v33, v34, v35
	v_mad_i64_i32 v[34:35], s[34:35], s30, v104, 0
	v_cvt_pk_bf16_f32 v36, v36, v37
	v_cvt_pk_bf16_f32 v37, v38, v39
	v_lshl_add_u64 v[34:35], v[34:35], 1, v[64:65]
	s_and_b64 vcc, exec, s[6:7]
	global_store_dwordx2 v[34:35], v[36:37], off nt
	global_store_dwordx2 v[34:35], v[32:33], off offset:64 nt
	s_cbranch_vccnz .LBB0_713
	v_lshlrev_b32_e32 v178, 2, v96
	v_lshl_add_u64 v[32:33], v[182:183], 0, v[178:179]
	v_lshl_add_u64 v[34:35], v[184:185], 0, v[178:179]
	global_load_dwordx4 v[148:151], v[32:33], off
	global_load_dwordx4 v[140:143], v[32:33], off offset:2048
	global_load_dwordx4 v[144:147], v[34:35], off
	global_load_dwordx4 v[136:139], v[34:35], off offset:2048
	v_or_b32_e32 v32, 0x1000, v178
	v_mov_b32_e32 v33, v179
	v_lshl_add_u64 v[34:35], v[182:183], 0, v[32:33]
	v_lshl_add_u64 v[32:33], v[184:185], 0, v[32:33]
	v_or_b32_e32 v178, 0x1800, v178
	global_load_dwordx4 v[132:135], v[34:35], off
	global_load_dwordx4 v[128:131], v[32:33], off
	v_lshl_add_u64 v[32:33], v[182:183], 0, v[178:179]
	v_lshl_add_u64 v[34:35], v[184:185], 0, v[178:179]
	global_load_dwordx4 v[156:159], v[32:33], off
	global_load_dwordx4 v[152:155], v[34:35], off
.LBB0_713:
	s_waitcnt vmcnt(5)
	v_pk_mul_f32 v[32:33], v[26:27], v[146:147]
	v_pk_mul_f32 v[36:37], v[26:27], v[150:151]
	v_pk_mul_f32 v[38:39], v[24:25], v[148:149]
	v_pk_mul_f32 v[34:35], v[24:25], v[144:145]
	v_pk_fma_f32 v[32:33], v[30:31], v[150:151], v[32:33] neg_lo:[0,0,1] neg_hi:[0,0,1]
	v_pk_fma_f32 v[36:37], v[30:31], v[146:147], v[36:37]
	v_pk_fma_f32 v[38:39], v[28:29], v[144:145], v[38:39]
	v_mov_b32_e32 v67, v66
	v_pk_fma_f32 v[34:35], v[28:29], v[148:149], v[34:35] neg_lo:[0,0,1] neg_hi:[0,0,1]
	v_cndmask_b32_e64 v25, v25, v39, s[0:1]
	v_cndmask_b32_e64 v24, v24, v38, s[0:1]
	v_cndmask_b32_e64 v27, v27, v37, s[0:1]
	v_cndmask_b32_e64 v26, v26, v36, s[0:1]
	v_cndmask_b32_e64 v31, v31, v33, s[0:1]
	v_cndmask_b32_e64 v30, v30, v32, s[0:1]
	v_mov_b32_e32 v32, v66
	v_mov_b32_e32 v33, v66
	v_cndmask_b32_e64 v29, v29, v35, s[0:1]
	v_cndmask_b32_e64 v28, v28, v34, s[0:1]
	v_pk_mul_f32 v[26:27], v[32:33], v[26:27]
	v_pk_mul_f32 v[24:25], v[66:67], v[24:25]
	v_pk_mul_f32 v[30:31], v[32:33], v[30:31]
	v_pk_mul_f32 v[28:29], v[66:67], v[28:29]
	v_cvt_pk_bf16_f32 v24, v24, v25
	v_cvt_pk_bf16_f32 v25, v26, v27
	v_mad_i64_i32 v[26:27], s[6:7], s30, v97, 0
	v_cvt_pk_bf16_f32 v28, v28, v29
	v_cvt_pk_bf16_f32 v29, v30, v31
	v_lshl_add_u64 v[26:27], v[26:27], 1, v[64:65]
	global_store_dwordx2 v[26:27], v[28:29], off nt
	global_store_dwordx2 v[26:27], v[24:25], off offset:64 nt
	v_pk_mul_f32 v[28:29], v[18:19], v[142:143]
	v_pk_mul_f32 v[30:31], v[16:17], v[140:141]
	s_waitcnt vmcnt(6)
	v_pk_mul_f32 v[24:25], v[18:19], v[138:139]
	v_pk_mul_f32 v[26:27], v[16:17], v[136:137]
	v_pk_fma_f32 v[28:29], v[22:23], v[138:139], v[28:29]
	v_pk_fma_f32 v[30:31], v[20:21], v[136:137], v[30:31]
	v_pk_fma_f32 v[24:25], v[22:23], v[142:143], v[24:25] neg_lo:[0,0,1] neg_hi:[0,0,1]
	v_pk_fma_f32 v[26:27], v[20:21], v[140:141], v[26:27] neg_lo:[0,0,1] neg_hi:[0,0,1]
	v_cndmask_b32_e64 v17, v17, v31, s[0:1]
	v_cndmask_b32_e64 v16, v16, v30, s[0:1]
	v_cndmask_b32_e64 v19, v19, v29, s[0:1]
	v_cndmask_b32_e64 v18, v18, v28, s[0:1]
	v_cndmask_b32_e64 v21, v21, v27, s[0:1]
	v_cndmask_b32_e64 v20, v20, v26, s[0:1]
	v_cndmask_b32_e64 v23, v23, v25, s[0:1]
	v_cndmask_b32_e64 v22, v22, v24, s[0:1]
	v_pk_mul_f32 v[18:19], v[32:33], v[18:19]
	v_pk_mul_f32 v[16:17], v[66:67], v[16:17]
	v_pk_mul_f32 v[22:23], v[32:33], v[22:23]
	v_pk_mul_f32 v[20:21], v[66:67], v[20:21]
	v_cvt_pk_bf16_f32 v16, v16, v17
	v_cvt_pk_bf16_f32 v17, v18, v19
	v_mad_i64_i32 v[18:19], s[6:7], s30, v88, 0
	v_cvt_pk_bf16_f32 v20, v20, v21
	v_cvt_pk_bf16_f32 v21, v22, v23
	v_lshl_add_u64 v[18:19], v[18:19], 1, v[64:65]
	global_store_dwordx2 v[18:19], v[20:21], off nt
	global_store_dwordx2 v[18:19], v[16:17], off offset:64 nt
	s_waitcnt vmcnt(7)
	v_pk_mul_f32 v[20:21], v[10:11], v[134:135]
	v_pk_mul_f32 v[22:23], v[8:9], v[132:133]
	s_waitcnt vmcnt(6)
	v_pk_mul_f32 v[16:17], v[10:11], v[130:131]
	v_pk_mul_f32 v[18:19], v[8:9], v[128:129]
	v_pk_fma_f32 v[20:21], v[14:15], v[130:131], v[20:21]
	v_pk_fma_f32 v[22:23], v[12:13], v[128:129], v[22:23]
	v_pk_fma_f32 v[16:17], v[14:15], v[134:135], v[16:17] neg_lo:[0,0,1] neg_hi:[0,0,1]
	v_pk_fma_f32 v[18:19], v[12:13], v[132:133], v[18:19] neg_lo:[0,0,1] neg_hi:[0,0,1]
	v_cndmask_b32_e64 v9, v9, v23, s[0:1]
	v_cndmask_b32_e64 v8, v8, v22, s[0:1]
	v_cndmask_b32_e64 v11, v11, v21, s[0:1]
	v_cndmask_b32_e64 v10, v10, v20, s[0:1]
	v_cndmask_b32_e64 v13, v13, v19, s[0:1]
	v_cndmask_b32_e64 v12, v12, v18, s[0:1]
	v_cndmask_b32_e64 v15, v15, v17, s[0:1]
	v_cndmask_b32_e64 v14, v14, v16, s[0:1]
	v_pk_mul_f32 v[10:11], v[32:33], v[10:11]
	v_pk_mul_f32 v[8:9], v[66:67], v[8:9]
	v_pk_mul_f32 v[14:15], v[32:33], v[14:15]
	v_pk_mul_f32 v[12:13], v[66:67], v[12:13]
	v_cvt_pk_bf16_f32 v8, v8, v9
	v_cvt_pk_bf16_f32 v9, v10, v11
	v_mad_i64_i32 v[10:11], s[6:7], s30, v80, 0
	v_cvt_pk_bf16_f32 v12, v12, v13
	v_cvt_pk_bf16_f32 v13, v14, v15
	v_lshl_add_u64 v[10:11], v[10:11], 1, v[64:65]
	global_store_dwordx2 v[10:11], v[12:13], off nt
	global_store_dwordx2 v[10:11], v[8:9], off offset:64 nt
	s_waitcnt vmcnt(7)
	v_pk_mul_f32 v[12:13], v[2:3], v[158:159]
	v_pk_mul_f32 v[14:15], v[0:1], v[156:157]
	s_waitcnt vmcnt(6)
	v_pk_mul_f32 v[8:9], v[2:3], v[154:155]
	v_pk_mul_f32 v[10:11], v[0:1], v[152:153]
	v_pk_fma_f32 v[12:13], v[6:7], v[154:155], v[12:13]
	v_pk_fma_f32 v[14:15], v[4:5], v[152:153], v[14:15]
	v_pk_fma_f32 v[8:9], v[6:7], v[158:159], v[8:9] neg_lo:[0,0,1] neg_hi:[0,0,1]
	v_pk_fma_f32 v[10:11], v[4:5], v[156:157], v[10:11] neg_lo:[0,0,1] neg_hi:[0,0,1]
	v_cndmask_b32_e64 v1, v1, v15, s[0:1]
	v_cndmask_b32_e64 v0, v0, v14, s[0:1]
	v_cndmask_b32_e64 v3, v3, v13, s[0:1]
	v_cndmask_b32_e64 v2, v2, v12, s[0:1]
	v_cndmask_b32_e64 v5, v5, v11, s[0:1]
	v_cndmask_b32_e64 v4, v4, v10, s[0:1]
	v_cndmask_b32_e64 v7, v7, v9, s[0:1]
	v_cndmask_b32_e64 v6, v6, v8, s[0:1]
	v_pk_mul_f32 v[2:3], v[32:33], v[2:3]
	v_pk_mul_f32 v[0:1], v[66:67], v[0:1]
	v_pk_mul_f32 v[6:7], v[32:33], v[6:7]
	v_pk_mul_f32 v[4:5], v[66:67], v[4:5]
	v_cvt_pk_bf16_f32 v0, v0, v1
	v_cvt_pk_bf16_f32 v1, v2, v3
	v_mad_i64_i32 v[2:3], s[0:1], s30, v72, 0
	v_cvt_pk_bf16_f32 v4, v4, v5
	v_cvt_pk_bf16_f32 v5, v6, v7
	v_lshl_add_u64 v[2:3], v[2:3], 1, v[64:65]
	global_store_dwordx2 v[2:3], v[4:5], off nt
	global_store_dwordx2 v[2:3], v[0:1], off offset:64 nt
	s_andn2_b64 vcc, exec, s[4:5]
	s_mov_b64 s[0:1], -1
	s_cbranch_vccnz .LBB0_488

.LBB0_726:
	s_cmpk_gt_i32 s10, 0x47f
	s_mov_b64 s[4:5], -1
	s_cbranch_scc0 .LBB0_764
	s_cmpk_gt_u32 s10, 0x1a7f
	s_cbranch_scc0 .LBB0_737
	s_add_i32 s8, s10, 0xffffe580
	s_cmpk_gt_u32 s8, 0x57f
	s_load_dwordx2 s[4:5], s[2:3], 0x30
	s_cselect_b64 s[6:7], -1, 0
	v_cndmask_b32_e64 v0, 0, 1, s[6:7]
	s_nop 0
	v_readfirstlane_b32 s6, v0
	s_or_b32 s9, s6, 2
	s_mul_i32 s6, s9, 0xb00000
	s_waitcnt lgkmcnt(0)
	s_add_u32 s6, s4, s6
	s_addc_u32 s7, s5, 0
	s_mul_i32 s9, s9, 0x580000
	s_add_u32 s4, s14, s9
	s_addc_u32 s5, s15, 0
	s_add_i32 s9, s10, 0xe000
	s_cmpk_lt_u32 s8, 0x580
	s_cselect_b32 s9, s8, s9
	s_bfe_u32 s8, s9, 0xb0005
	s_lshl_b32 s9, s9, 5
	v_lshl_add_u32 v0, s8, 6, v37
	s_and_b32 s9, s9, 0x3e0
	v_ashrrev_i32_e32 v1, 31, v0
	v_or_b32_e32 v2, s9, v36
	v_lshlrev_b64 v[0:1], 12, v[0:1]
	v_lshl_add_u64 v[0:1], s[6:7], 0, v[0:1]
	v_lshlrev_b32_e32 v20, 2, v2
	v_lshl_add_u64 v[0:1], v[0:1], 0, v[20:21]
	s_movk_i32 s6, 0x2000
	v_add_co_u32_e32 v2, vcc, s6, v0
	s_movk_i32 s6, 0x4000
	s_nop 0
	v_addc_co_u32_e32 v3, vcc, 0, v1, vcc
	v_add_co_u32_e32 v4, vcc, s6, v0
	s_mov_b32 s6, 0xe000
	s_nop 0
	v_addc_co_u32_e32 v5, vcc, 0, v1, vcc
	v_add_co_u32_e32 v6, vcc, s20, v0
	s_nop 1
	v_addc_co_u32_e32 v7, vcc, 0, v1, vcc
	v_add_co_u32_e32 v8, vcc, s21, v0
	s_nop 1
	v_addc_co_u32_e32 v9, vcc, 0, v1, vcc
	v_add_co_u32_e32 v10, vcc, s22, v0
	s_nop 1
	v_addc_co_u32_e32 v11, vcc, 0, v1, vcc
	v_add_co_u32_e32 v12, vcc, s23, v0
	s_nop 1
	v_addc_co_u32_e32 v13, vcc, 0, v1, vcc
	v_add_co_u32_e32 v14, vcc, s6, v0
	s_nop 1
	v_addc_co_u32_e32 v15, vcc, 0, v1, vcc
	global_load_dword v18, v[0:1], off
	global_load_dword v19, v[2:3], off
	global_load_dword v20, v[4:5], off
	global_load_dword v23, v[6:7], off
	global_load_dword v24, v[8:9], off
	global_load_dword v25, v[10:11], off
	global_load_dword v26, v[12:13], off
	global_load_dword v27, v[14:15], off
	v_add_co_u32_e32 v2, vcc, s24, v0
	s_nop 1
	v_addc_co_u32_e32 v3, vcc, 0, v1, vcc
	v_add_co_u32_e32 v4, vcc, s25, v0
	s_nop 1
	v_addc_co_u32_e32 v5, vcc, 0, v1, vcc
	v_add_co_u32_e32 v6, vcc, s26, v0
	s_nop 1
	v_addc_co_u32_e32 v7, vcc, 0, v1, vcc
	v_add_co_u32_e32 v8, vcc, s27, v0
	s_nop 1
	v_addc_co_u32_e32 v9, vcc, 0, v1, vcc
	v_add_co_u32_e32 v10, vcc, s28, v0
	s_nop 1
	v_addc_co_u32_e32 v11, vcc, 0, v1, vcc
	v_add_co_u32_e32 v12, vcc, s29, v0
	s_nop 1
	v_addc_co_u32_e32 v13, vcc, 0, v1, vcc
	v_add_co_u32_e32 v14, vcc, s30, v0
	s_nop 1
	v_addc_co_u32_e32 v15, vcc, 0, v1, vcc
	v_add_co_u32_e32 v16, vcc, s31, v0
	s_nop 1
	v_addc_co_u32_e32 v17, vcc, 0, v1, vcc
	global_load_dword v28, v[2:3], off
	global_load_dword v29, v[4:5], off
	global_load_dword v30, v[6:7], off
	global_load_dword v31, v[8:9], off
	global_load_dword v32, v[10:11], off
	global_load_dword v33, v[12:13], off
	global_load_dword v34, v[14:15], off
	global_load_dword v35, v[16:17], off
	v_add_co_u32_e32 v2, vcc, s33, v0
	s_nop 1
	v_addc_co_u32_e32 v3, vcc, 0, v1, vcc
	v_add_co_u32_e32 v4, vcc, s34, v0
	s_nop 1
	v_addc_co_u32_e32 v5, vcc, 0, v1, vcc
	v_add_co_u32_e32 v6, vcc, s35, v0
	s_nop 1
	v_addc_co_u32_e32 v7, vcc, 0, v1, vcc
	v_add_co_u32_e32 v8, vcc, s36, v0
	s_nop 1
	v_addc_co_u32_e32 v9, vcc, 0, v1, vcc
	v_add_co_u32_e32 v10, vcc, s37, v0
	s_nop 1
	v_addc_co_u32_e32 v11, vcc, 0, v1, vcc
	v_add_co_u32_e32 v12, vcc, s38, v0
	s_nop 1
	v_addc_co_u32_e32 v13, vcc, 0, v1, vcc
	v_add_co_u32_e32 v14, vcc, s39, v0
	s_nop 1
	v_addc_co_u32_e32 v15, vcc, 0, v1, vcc
	v_add_co_u32_e32 v16, vcc, s40, v0
	s_nop 1
	v_addc_co_u32_e32 v17, vcc, 0, v1, vcc
	global_load_dword v51, v[2:3], off
	global_load_dword v52, v[4:5], off
	global_load_dword v53, v[6:7], off
	global_load_dword v54, v[8:9], off
	global_load_dword v55, v[10:11], off
	global_load_dword v56, v[12:13], off
	global_load_dword v57, v[14:15], off
	s_nop 0
	global_load_dword v16, v[16:17], off
	v_add_co_u32_e32 v2, vcc, s41, v0
	s_nop 1
	v_addc_co_u32_e32 v3, vcc, 0, v1, vcc
	v_add_co_u32_e32 v4, vcc, s42, v0
	s_nop 1
	v_addc_co_u32_e32 v5, vcc, 0, v1, vcc
	v_add_co_u32_e32 v6, vcc, s43, v0
	s_nop 1
	v_addc_co_u32_e32 v7, vcc, 0, v1, vcc
	v_add_co_u32_e32 v8, vcc, s44, v0
	s_nop 1
	v_addc_co_u32_e32 v9, vcc, 0, v1, vcc
	v_add_co_u32_e32 v10, vcc, s45, v0
	s_nop 1
	v_addc_co_u32_e32 v11, vcc, 0, v1, vcc
	v_add_co_u32_e32 v12, vcc, s46, v0
	s_nop 1
	v_addc_co_u32_e32 v13, vcc, 0, v1, vcc
	v_add_co_u32_e32 v14, vcc, s47, v0
	s_nop 1
	v_addc_co_u32_e32 v15, vcc, 0, v1, vcc
	v_add_co_u32_e32 v0, vcc, s48, v0
	s_nop 1
	v_addc_co_u32_e32 v1, vcc, 0, v1, vcc
	global_load_dword v2, v[2:3], off
	s_nop 0
	global_load_dword v3, v[4:5], off
	s_nop 0
	global_load_dword v4, v[6:7], off
	global_load_dword v5, v[8:9], off
	s_nop 0
	global_load_dword v6, v[10:11], off
	global_load_dword v7, v[12:13], off
	global_load_dword v8, v[14:15], off
	s_nop 0
	global_load_dword v0, v[0:1], off
	s_waitcnt vmcnt(30)
	ds_write2_b32 v42, v18, v19 offset1:66
	s_waitcnt vmcnt(28)
	ds_write2_b32 v42, v20, v23 offset0:132 offset1:198
	s_waitcnt vmcnt(26)
	ds_write2_b32 v43, v24, v25 offset0:8 offset1:74
	s_waitcnt vmcnt(24)
	ds_write2_b32 v43, v26, v27 offset0:140 offset1:206
	s_waitcnt vmcnt(22)
	ds_write2_b32 v44, v28, v29 offset0:16 offset1:82
	s_waitcnt vmcnt(20)
	ds_write2_b32 v44, v30, v31 offset0:148 offset1:214
	s_waitcnt vmcnt(18)
	ds_write2_b32 v45, v32, v33 offset0:24 offset1:90
	s_waitcnt vmcnt(16)
	ds_write2_b32 v45, v34, v35 offset0:156 offset1:222
	s_waitcnt vmcnt(14)
	ds_write2_b32 v46, v51, v52 offset0:32 offset1:98
	s_waitcnt vmcnt(12)
	ds_write2_b32 v46, v53, v54 offset0:164 offset1:230
	s_waitcnt vmcnt(10)
	ds_write2_b32 v47, v55, v56 offset0:40 offset1:106
	s_waitcnt vmcnt(8)
	ds_write2_b32 v47, v57, v16 offset0:172 offset1:238
	s_waitcnt vmcnt(6)
	ds_write2_b32 v48, v2, v3 offset0:48 offset1:114
	s_waitcnt vmcnt(4)
	ds_write2_b32 v48, v4, v5 offset0:180 offset1:246
	s_waitcnt vmcnt(2)
	ds_write2_b32 v49, v6, v7 offset0:56 offset1:122
	s_waitcnt vmcnt(0)
	ds_write2_b32 v49, v8, v0 offset0:188 offset1:254
	s_waitcnt lgkmcnt(0)
	v_add_u32_e32 v0, s9, v38
	v_cmp_gt_i32_e32 vcc, s49, v0
	s_and_saveexec_b64 s[6:7], vcc
	s_cbranch_execz .LBB0_730
	ds_read2_b32 v[2:3], v50 offset1:33
	ds_read2_b32 v[4:5], v50 offset0:66 offset1:99
	ds_read2_b32 v[6:7], v50 offset0:132 offset1:165
	ds_read2_b32 v[8:9], v50 offset0:198 offset1:231
	v_lshrrev_b32_e32 v1, 8, v0
	s_waitcnt lgkmcnt(3)
	v_cvt_pk_bf16_f32 v2, v2, v3
	s_waitcnt lgkmcnt(2)
	v_cvt_pk_bf16_f32 v3, v4, v5
	s_waitcnt lgkmcnt(1)
	v_cvt_pk_bf16_f32 v4, v6, v7
	v_mad_i32_i24 v6, v1, 44, s8
	v_ashrrev_i32_e32 v7, 31, v6
	v_lshlrev_b64 v[6:7], 15, v[6:7]
	v_lshlrev_b32_e32 v0, 7, v0
	v_lshl_add_u64 v[6:7], s[4:5], 0, v[6:7]
	v_and_b32_e32 v20, 0x7f80, v0
	v_lshl_add_u64 v[0:1], v[6:7], 0, v[20:21]
	v_mov_b32_e32 v23, v21
	s_waitcnt lgkmcnt(0)
	v_cvt_pk_bf16_f32 v5, v8, v9
	v_lshl_add_u64 v[0:1], v[0:1], 0, v[22:23]
	global_store_dwordx4 v[0:1], v[2:5], off nt
.LBB0_730:
	s_or_b64 exec, exec, s[6:7]
	v_add_u32_e32 v0, s9, v39
	v_cmp_gt_i32_e32 vcc, s49, v0
	s_and_saveexec_b64 s[6:7], vcc
	s_cbranch_execz .LBB0_732
	ds_read2_b32 v[2:3], v50 offset0:8 offset1:41
	ds_read2_b32 v[4:5], v50 offset0:74 offset1:107
	ds_read2_b32 v[6:7], v50 offset0:140 offset1:173
	ds_read2_b32 v[8:9], v50 offset0:206 offset1:239
	v_lshrrev_b32_e32 v1, 8, v0
	s_waitcnt lgkmcnt(3)
	v_cvt_pk_bf16_f32 v2, v2, v3
	s_waitcnt lgkmcnt(2)
	v_cvt_pk_bf16_f32 v3, v4, v5
	s_waitcnt lgkmcnt(1)
	v_cvt_pk_bf16_f32 v4, v6, v7
	v_mad_i32_i24 v6, v1, 44, s8
	v_ashrrev_i32_e32 v7, 31, v6
	v_lshlrev_b64 v[6:7], 15, v[6:7]
	v_lshlrev_b32_e32 v0, 7, v0
	v_lshl_add_u64 v[6:7], s[4:5], 0, v[6:7]
	v_and_b32_e32 v20, 0x7f80, v0
	v_lshl_add_u64 v[0:1], v[6:7], 0, v[20:21]
	v_mov_b32_e32 v23, v21
	s_waitcnt lgkmcnt(0)
	v_cvt_pk_bf16_f32 v5, v8, v9
	v_lshl_add_u64 v[0:1], v[0:1], 0, v[22:23]
	global_store_dwordx4 v[0:1], v[2:5], off nt
.LBB0_732:
	s_or_b64 exec, exec, s[6:7]
	v_add_u32_e32 v0, s9, v40
	v_cmp_gt_i32_e32 vcc, s49, v0
	s_and_saveexec_b64 s[6:7], vcc
	s_cbranch_execz .LBB0_734
	ds_read2_b32 v[2:3], v50 offset0:16 offset1:49
	ds_read2_b32 v[4:5], v50 offset0:82 offset1:115
	ds_read2_b32 v[6:7], v50 offset0:148 offset1:181
	ds_read2_b32 v[8:9], v50 offset0:214 offset1:247
	v_lshrrev_b32_e32 v1, 8, v0
	s_waitcnt lgkmcnt(3)
	v_cvt_pk_bf16_f32 v2, v2, v3
	s_waitcnt lgkmcnt(2)
	v_cvt_pk_bf16_f32 v3, v4, v5
	s_waitcnt lgkmcnt(1)
	v_cvt_pk_bf16_f32 v4, v6, v7
	v_mad_i32_i24 v6, v1, 44, s8
	v_ashrrev_i32_e32 v7, 31, v6
	v_lshlrev_b64 v[6:7], 15, v[6:7]
	v_lshlrev_b32_e32 v0, 7, v0
	v_lshl_add_u64 v[6:7], s[4:5], 0, v[6:7]
	v_and_b32_e32 v20, 0x7f80, v0
	v_lshl_add_u64 v[0:1], v[6:7], 0, v[20:21]
	v_mov_b32_e32 v23, v21
	s_waitcnt lgkmcnt(0)
	v_cvt_pk_bf16_f32 v5, v8, v9
	v_lshl_add_u64 v[0:1], v[0:1], 0, v[22:23]
	global_store_dwordx4 v[0:1], v[2:5], off nt
.LBB0_734:
	s_or_b64 exec, exec, s[6:7]
	v_add_u32_e32 v0, s9, v41
	v_cmp_gt_i32_e32 vcc, s49, v0
	s_and_saveexec_b64 s[6:7], vcc
	s_cbranch_execz .LBB0_736
	ds_read2_b32 v[2:3], v50 offset0:24 offset1:57
	ds_read2_b32 v[4:5], v50 offset0:90 offset1:123
	ds_read2_b32 v[6:7], v50 offset0:156 offset1:189
	ds_read2_b32 v[8:9], v50 offset0:222 offset1:255
	v_lshrrev_b32_e32 v1, 8, v0
	s_waitcnt lgkmcnt(3)
	v_cvt_pk_bf16_f32 v2, v2, v3
	s_waitcnt lgkmcnt(2)
	v_cvt_pk_bf16_f32 v3, v4, v5
	s_waitcnt lgkmcnt(1)
	v_cvt_pk_bf16_f32 v4, v6, v7
	v_mad_i32_i24 v6, v1, 44, s8
	v_ashrrev_i32_e32 v7, 31, v6
	v_lshlrev_b64 v[6:7], 15, v[6:7]
	v_lshlrev_b32_e32 v0, 7, v0
	v_lshl_add_u64 v[6:7], s[4:5], 0, v[6:7]
	v_and_b32_e32 v20, 0x7f80, v0
	v_lshl_add_u64 v[0:1], v[6:7], 0, v[20:21]
	v_mov_b32_e32 v23, v21
	s_waitcnt lgkmcnt(0)
	v_cvt_pk_bf16_f32 v5, v8, v9
	v_lshl_add_u64 v[0:1], v[0:1], 0, v[22:23]
	global_store_dwordx4 v[0:1], v[2:5], off nt

.LBB0_737:
	s_and_b64 vcc, exec, s[4:5]
	s_cbranch_vccz .LBB0_763
	s_add_i32 s8, s10, 0xfffffb80
	s_cmpk_gt_u32 s8, 0xaff
	s_load_dwordx2 s[4:5], s[2:3], 0x28
	s_cselect_b64 s[6:7], -1, 0
	v_cndmask_b32_e64 v0, 0, 1, s[6:7]
	s_nop 0
	v_readfirstlane_b32 s6, v0
	s_or_b32 s9, s6, 2
	s_mul_i32 s6, s9, 0x1600000
	s_waitcnt lgkmcnt(0)
	s_add_u32 s6, s4, s6
	s_addc_u32 s7, s5, 0
	s_mul_i32 s9, s9, 0xb00000
	s_add_u32 s4, s12, s9
	s_addc_u32 s5, s13, 0
	s_add_i32 s9, s10, 0xf080
	s_cmpk_lt_u32 s8, 0xb00
	s_cselect_b32 s8, s8, s9
	s_and_b32 s9, s8, 0xffff
	s_mul_i32 s9, s9, 0xba2f
	s_lshr_b32 s84, s9, 23
	s_mul_i32 s9, s84, 0xb0
	s_sub_i32 s8, s8, s9
	s_lshl_b32 s8, s8, 5
	s_and_b32 s85, s8, 0xffe0
	v_or_b32_e32 v2, s85, v36
	v_lshl_add_u32 v3, s84, 6, v37
	v_mov_b64_e32 v[0:1], s[6:7]
	v_mad_i64_i32 v[0:1], s[6:7], v3, s51, v[0:1]
	v_lshlrev_b32_e32 v20, 2, v2
	v_lshl_add_u64 v[0:1], v[0:1], 0, v[20:21]
	v_add_co_u32_e32 v2, vcc, s52, v0
	s_nop 1
	v_addc_co_u32_e32 v3, vcc, 0, v1, vcc
	v_add_co_u32_e32 v4, vcc, s27, v0
	s_nop 1
	v_addc_co_u32_e32 v5, vcc, 0, v1, vcc
	v_add_co_u32_e32 v6, vcc, s53, v0
	s_nop 1
	v_addc_co_u32_e32 v7, vcc, 0, v1, vcc
	v_add_co_u32_e32 v8, vcc, s39, v0
	s_nop 1
	v_addc_co_u32_e32 v9, vcc, 0, v1, vcc
	v_add_co_u32_e32 v10, vcc, s54, v0
	s_nop 1
	v_addc_co_u32_e32 v11, vcc, 0, v1, vcc
	v_add_co_u32_e32 v12, vcc, s55, v0
	s_nop 1
	v_addc_co_u32_e32 v13, vcc, 0, v1, vcc
	v_add_co_u32_e32 v14, vcc, s56, v0
	s_nop 1
	v_addc_co_u32_e32 v15, vcc, 0, v1, vcc
	global_load_dword v18, v[0:1], off
	global_load_dword v19, v[2:3], off
	global_load_dword v20, v[4:5], off
	global_load_dword v23, v[6:7], off
	global_load_dword v24, v[8:9], off
	global_load_dword v25, v[10:11], off
	global_load_dword v26, v[12:13], off
	global_load_dword v27, v[14:15], off
	v_add_co_u32_e32 v2, vcc, s57, v0
	s_nop 1
	v_addc_co_u32_e32 v3, vcc, 0, v1, vcc
	v_add_co_u32_e32 v4, vcc, s58, v0
	s_nop 1
	v_addc_co_u32_e32 v5, vcc, 0, v1, vcc
	v_add_co_u32_e32 v6, vcc, s59, v0
	s_nop 1
	v_addc_co_u32_e32 v7, vcc, 0, v1, vcc
	v_add_co_u32_e32 v8, vcc, s60, v0
	s_nop 1
	v_addc_co_u32_e32 v9, vcc, 0, v1, vcc
	v_add_co_u32_e32 v10, vcc, s61, v0
	s_nop 1
	v_addc_co_u32_e32 v11, vcc, 0, v1, vcc
	v_add_co_u32_e32 v12, vcc, s62, v0
	s_nop 1
	v_addc_co_u32_e32 v13, vcc, 0, v1, vcc
	v_add_co_u32_e32 v14, vcc, s63, v0
	s_nop 1
	v_addc_co_u32_e32 v15, vcc, 0, v1, vcc
	v_add_co_u32_e32 v16, vcc, s64, v0
	s_nop 1
	v_addc_co_u32_e32 v17, vcc, 0, v1, vcc
	global_load_dword v28, v[2:3], off
	global_load_dword v29, v[4:5], off
	global_load_dword v30, v[6:7], off
	global_load_dword v31, v[8:9], off
	global_load_dword v32, v[10:11], off
	global_load_dword v33, v[12:13], off
	global_load_dword v34, v[14:15], off
	global_load_dword v35, v[16:17], off
	v_add_co_u32_e32 v2, vcc, s65, v0
	s_nop 1
	v_addc_co_u32_e32 v3, vcc, 0, v1, vcc
	v_add_co_u32_e32 v4, vcc, s66, v0
	s_nop 1
	v_addc_co_u32_e32 v5, vcc, 0, v1, vcc
	v_add_co_u32_e32 v6, vcc, s67, v0
	s_nop 1
	v_addc_co_u32_e32 v7, vcc, 0, v1, vcc
	v_add_co_u32_e32 v8, vcc, s68, v0
	s_nop 1
	v_addc_co_u32_e32 v9, vcc, 0, v1, vcc
	v_add_co_u32_e32 v10, vcc, s69, v0
	s_nop 1
	v_addc_co_u32_e32 v11, vcc, 0, v1, vcc
	v_add_co_u32_e32 v12, vcc, s70, v0
	s_nop 1
	v_addc_co_u32_e32 v13, vcc, 0, v1, vcc
	v_add_co_u32_e32 v14, vcc, s71, v0
	s_nop 1
	v_addc_co_u32_e32 v15, vcc, 0, v1, vcc
	v_add_co_u32_e32 v16, vcc, s72, v0
	s_nop 1
	v_addc_co_u32_e32 v17, vcc, 0, v1, vcc
	global_load_dword v51, v[2:3], off
	global_load_dword v52, v[4:5], off
	global_load_dword v53, v[6:7], off
	global_load_dword v54, v[8:9], off
	global_load_dword v55, v[10:11], off
	global_load_dword v56, v[12:13], off
	global_load_dword v57, v[14:15], off
	s_nop 0
	global_load_dword v16, v[16:17], off
	v_add_co_u32_e32 v2, vcc, s73, v0
	s_nop 1
	v_addc_co_u32_e32 v3, vcc, 0, v1, vcc
	v_add_co_u32_e32 v4, vcc, s74, v0
	s_nop 1
	v_addc_co_u32_e32 v5, vcc, 0, v1, vcc
	v_add_co_u32_e32 v6, vcc, s75, v0
	s_nop 1
	v_addc_co_u32_e32 v7, vcc, 0, v1, vcc
	v_add_co_u32_e32 v8, vcc, s76, v0
	s_nop 1
	v_addc_co_u32_e32 v9, vcc, 0, v1, vcc
	v_add_co_u32_e32 v10, vcc, s77, v0
	s_nop 1
	v_addc_co_u32_e32 v11, vcc, 0, v1, vcc
	v_add_co_u32_e32 v12, vcc, s78, v0
	s_nop 1
	v_addc_co_u32_e32 v13, vcc, 0, v1, vcc
	v_add_co_u32_e32 v14, vcc, s79, v0
	s_nop 1
	v_addc_co_u32_e32 v15, vcc, 0, v1, vcc
	v_add_co_u32_e32 v0, vcc, s80, v0
	s_nop 1
	v_addc_co_u32_e32 v1, vcc, 0, v1, vcc
	global_load_dword v2, v[2:3], off
	s_nop 0
	global_load_dword v3, v[4:5], off
	s_nop 0
	global_load_dword v4, v[6:7], off
	global_load_dword v5, v[8:9], off
	s_nop 0
	global_load_dword v6, v[10:11], off
	global_load_dword v7, v[12:13], off
	global_load_dword v8, v[14:15], off
	s_nop 0
	global_load_dword v0, v[0:1], off
	s_waitcnt vmcnt(30)
	ds_write2_b32 v42, v18, v19 offset1:66
	s_waitcnt vmcnt(28)
	ds_write2_b32 v42, v20, v23 offset0:132 offset1:198
	s_waitcnt vmcnt(26)
	ds_write2_b32 v43, v24, v25 offset0:8 offset1:74
	s_waitcnt vmcnt(24)
	ds_write2_b32 v43, v26, v27 offset0:140 offset1:206
	s_waitcnt vmcnt(22)
	ds_write2_b32 v44, v28, v29 offset0:16 offset1:82
	s_waitcnt vmcnt(20)
	ds_write2_b32 v44, v30, v31 offset0:148 offset1:214
	s_waitcnt vmcnt(18)
	ds_write2_b32 v45, v32, v33 offset0:24 offset1:90
	s_waitcnt vmcnt(16)
	ds_write2_b32 v45, v34, v35 offset0:156 offset1:222
	s_waitcnt vmcnt(14)
	ds_write2_b32 v46, v51, v52 offset0:32 offset1:98
	s_waitcnt vmcnt(12)
	ds_write2_b32 v46, v53, v54 offset0:164 offset1:230
	s_waitcnt vmcnt(10)
	ds_write2_b32 v47, v55, v56 offset0:40 offset1:106
	s_waitcnt vmcnt(8)
	ds_write2_b32 v47, v57, v16 offset0:172 offset1:238
	s_waitcnt vmcnt(6)
	ds_write2_b32 v48, v2, v3 offset0:48 offset1:114
	s_waitcnt vmcnt(4)
	ds_write2_b32 v48, v4, v5 offset0:180 offset1:246
	s_waitcnt vmcnt(2)
	ds_write2_b32 v49, v6, v7 offset0:56 offset1:122
	s_waitcnt vmcnt(0)
	ds_write2_b32 v49, v8, v0 offset0:188 offset1:254
	s_waitcnt lgkmcnt(0)
	v_add_u32_e32 v8, s85, v38
	v_cmp_gt_i32_e32 vcc, s81, v8
	s_and_saveexec_b64 s[6:7], vcc
	s_cbranch_execz .LBB0_744
	ds_read2_b32 v[0:1], v50 offset1:33
	ds_read2_b32 v[2:3], v50 offset0:66 offset1:99
	ds_read2_b32 v[4:5], v50 offset0:132 offset1:165
	ds_read2_b32 v[6:7], v50 offset0:198 offset1:231
	v_cmp_lt_i32_e32 vcc, s50, v8
	v_lshlrev_b32_e32 v9, 1, v8
	v_and_b32_e32 v10, 0x7f, v8
	s_and_saveexec_b64 s[8:9], vcc
	s_xor_b64 s[8:9], exec, s[8:9]
	v_add_u32_e32 v8, 0x7fffea00, v9
	v_and_b32_e32 v8, 0x7fffff00, v8
	v_or3_b32 v8, v10, v8, s82
	s_andn2_saveexec_b64 s[8:9], s[8:9]
	v_and_or_b32 v8, v9, s83, v10
	s_or_b64 exec, exec, s[8:9]
	s_waitcnt lgkmcnt(3)
	v_cvt_pk_bf16_f32 v0, v0, v1
	s_waitcnt lgkmcnt(2)
	v_cvt_pk_bf16_f32 v1, v2, v3
	s_waitcnt lgkmcnt(1)
	v_cvt_pk_bf16_f32 v2, v4, v5
	v_ashrrev_i32_e32 v4, 4, v8
	v_and_b32_e32 v4, -16, v4
	v_add_u32_e32 v4, s84, v4
	v_ashrrev_i32_e32 v5, 31, v4
	s_waitcnt lgkmcnt(0)
	v_cvt_pk_bf16_f32 v3, v6, v7
	v_lshlrev_b64 v[4:5], 15, v[4:5]
	v_lshlrev_b32_e32 v6, 7, v8
	v_lshl_add_u64 v[4:5], s[4:5], 0, v[4:5]
	v_and_b32_e32 v20, 0x7f80, v6
	v_lshl_add_u64 v[4:5], v[4:5], 0, v[20:21]
	v_mov_b32_e32 v23, v21
	v_lshl_add_u64 v[4:5], v[4:5], 0, v[22:23]
	global_store_dwordx4 v[4:5], v[0:3], off nt
.LBB0_744:
	s_or_b64 exec, exec, s[6:7]
	v_add_u32_e32 v8, s85, v39
	v_cmp_gt_i32_e32 vcc, s81, v8
	s_and_saveexec_b64 s[6:7], vcc
	s_cbranch_execz .LBB0_750
	ds_read2_b32 v[0:1], v50 offset0:8 offset1:41
	ds_read2_b32 v[2:3], v50 offset0:74 offset1:107
	ds_read2_b32 v[4:5], v50 offset0:140 offset1:173
	ds_read2_b32 v[6:7], v50 offset0:206 offset1:239
	v_cmp_lt_i32_e32 vcc, s50, v8
	v_lshlrev_b32_e32 v9, 1, v8
	v_and_b32_e32 v10, 0x7f, v8
	s_and_saveexec_b64 s[8:9], vcc
	s_xor_b64 s[8:9], exec, s[8:9]
	v_add_u32_e32 v8, 0x7fffea00, v9
	v_and_b32_e32 v8, 0x7fffff00, v8
	v_or3_b32 v8, v10, v8, s82
	s_andn2_saveexec_b64 s[8:9], s[8:9]
	v_and_or_b32 v8, v9, s83, v10
	s_or_b64 exec, exec, s[8:9]
	s_waitcnt lgkmcnt(3)
	v_cvt_pk_bf16_f32 v0, v0, v1
	s_waitcnt lgkmcnt(2)
	v_cvt_pk_bf16_f32 v1, v2, v3
	s_waitcnt lgkmcnt(1)
	v_cvt_pk_bf16_f32 v2, v4, v5
	v_ashrrev_i32_e32 v4, 4, v8
	v_and_b32_e32 v4, -16, v4
	v_add_u32_e32 v4, s84, v4
	v_ashrrev_i32_e32 v5, 31, v4
	s_waitcnt lgkmcnt(0)
	v_cvt_pk_bf16_f32 v3, v6, v7
	v_lshlrev_b64 v[4:5], 15, v[4:5]
	v_lshlrev_b32_e32 v6, 7, v8
	v_lshl_add_u64 v[4:5], s[4:5], 0, v[4:5]
	v_and_b32_e32 v20, 0x7f80, v6
	v_lshl_add_u64 v[4:5], v[4:5], 0, v[20:21]
	v_mov_b32_e32 v23, v21
	v_lshl_add_u64 v[4:5], v[4:5], 0, v[22:23]
	global_store_dwordx4 v[4:5], v[0:3], off nt
.LBB0_750:
	s_or_b64 exec, exec, s[6:7]
	v_add_u32_e32 v8, s85, v40
	v_cmp_gt_i32_e32 vcc, s81, v8
	s_and_saveexec_b64 s[6:7], vcc
	s_cbranch_execz .LBB0_756
	ds_read2_b32 v[0:1], v50 offset0:16 offset1:49
	ds_read2_b32 v[2:3], v50 offset0:82 offset1:115
	ds_read2_b32 v[4:5], v50 offset0:148 offset1:181
	ds_read2_b32 v[6:7], v50 offset0:214 offset1:247
	v_cmp_lt_i32_e32 vcc, s50, v8
	v_lshlrev_b32_e32 v9, 1, v8
	v_and_b32_e32 v10, 0x7f, v8
	s_and_saveexec_b64 s[8:9], vcc
	s_xor_b64 s[8:9], exec, s[8:9]
	v_add_u32_e32 v8, 0x7fffea00, v9
	v_and_b32_e32 v8, 0x7fffff00, v8
	v_or3_b32 v8, v10, v8, s82
	s_andn2_saveexec_b64 s[8:9], s[8:9]
	v_and_or_b32 v8, v9, s83, v10
	s_or_b64 exec, exec, s[8:9]
	s_waitcnt lgkmcnt(3)
	v_cvt_pk_bf16_f32 v0, v0, v1
	s_waitcnt lgkmcnt(2)
	v_cvt_pk_bf16_f32 v1, v2, v3
	s_waitcnt lgkmcnt(1)
	v_cvt_pk_bf16_f32 v2, v4, v5
	v_ashrrev_i32_e32 v4, 4, v8
	v_and_b32_e32 v4, -16, v4
	v_add_u32_e32 v4, s84, v4
	v_ashrrev_i32_e32 v5, 31, v4
	s_waitcnt lgkmcnt(0)
	v_cvt_pk_bf16_f32 v3, v6, v7
	v_lshlrev_b64 v[4:5], 15, v[4:5]
	v_lshlrev_b32_e32 v6, 7, v8
	v_lshl_add_u64 v[4:5], s[4:5], 0, v[4:5]
	v_and_b32_e32 v20, 0x7f80, v6
	v_lshl_add_u64 v[4:5], v[4:5], 0, v[20:21]
	v_mov_b32_e32 v23, v21
	v_lshl_add_u64 v[4:5], v[4:5], 0, v[22:23]
	global_store_dwordx4 v[4:5], v[0:3], off nt
.LBB0_756:
	s_or_b64 exec, exec, s[6:7]
	v_add_u32_e32 v8, s85, v41
	v_cmp_gt_i32_e32 vcc, s81, v8
	s_and_saveexec_b64 s[6:7], vcc
	s_cbranch_execz .LBB0_762
	ds_read2_b32 v[0:1], v50 offset0:24 offset1:57
	ds_read2_b32 v[2:3], v50 offset0:90 offset1:123
	ds_read2_b32 v[4:5], v50 offset0:156 offset1:189
	ds_read2_b32 v[6:7], v50 offset0:222 offset1:255
	v_cmp_lt_i32_e32 vcc, s50, v8
	v_lshlrev_b32_e32 v9, 1, v8
	v_and_b32_e32 v10, 0x7f, v8
	s_and_saveexec_b64 s[8:9], vcc
	s_xor_b64 s[8:9], exec, s[8:9]
	v_add_u32_e32 v8, 0x7fffea00, v9
	v_and_b32_e32 v8, 0x7fffff00, v8
	v_or3_b32 v8, v10, v8, s82
	s_andn2_saveexec_b64 s[8:9], s[8:9]
	v_and_or_b32 v8, v9, s83, v10
	s_or_b64 exec, exec, s[8:9]
	s_waitcnt lgkmcnt(3)
	v_cvt_pk_bf16_f32 v0, v0, v1
	s_waitcnt lgkmcnt(2)
	v_cvt_pk_bf16_f32 v1, v2, v3
	s_waitcnt lgkmcnt(1)
	v_cvt_pk_bf16_f32 v2, v4, v5
	v_ashrrev_i32_e32 v4, 4, v8
	v_and_b32_e32 v4, -16, v4
	v_add_u32_e32 v4, s84, v4
	v_ashrrev_i32_e32 v5, 31, v4
	s_waitcnt lgkmcnt(0)
	v_cvt_pk_bf16_f32 v3, v6, v7
	v_lshlrev_b64 v[4:5], 15, v[4:5]
	v_lshlrev_b32_e32 v6, 7, v8
	v_lshl_add_u64 v[4:5], s[4:5], 0, v[4:5]
	v_and_b32_e32 v20, 0x7f80, v6
	v_lshl_add_u64 v[4:5], v[4:5], 0, v[20:21]
	v_mov_b32_e32 v23, v21
	v_lshl_add_u64 v[4:5], v[4:5], 0, v[22:23]
	global_store_dwordx4 v[4:5], v[0:3], off nt

.LBB0_766:
	v_lshl_add_u64 v[34:35], v[26:27], 0, s[4:5]
	v_add_co_u32_e32 v160, vcc, 0x2400000, v34
	v_mov_b32_e32 v8, s6
	s_nop 0
	v_addc_co_u32_e32 v161, vcc, 0, v35, vcc
	v_add_co_u32_e32 v162, vcc, 0x2409000, v34
	ds_read_b128 v[52:55], v8
	ds_read_b128 v[56:59], v8 offset:16
	ds_read_b128 v[60:63], v8 offset:32
	ds_read_b128 v[64:67], v8 offset:48
	ds_read_b128 v[68:71], v8 offset:4096
	ds_read_b128 v[72:75], v8 offset:4112
	ds_read_b128 v[76:79], v8 offset:8192
	ds_read_b128 v[80:83], v8 offset:8208
	ds_read_b128 v[84:87], v8 offset:12288
	ds_read_b128 v[88:91], v8 offset:12304
	ds_read_b128 v[92:95], v8 offset:16384
	ds_read_b128 v[96:99], v8 offset:16400
	ds_read_b128 v[100:103], v8 offset:20480
	ds_read_b128 v[104:107], v8 offset:20496
	ds_read_b128 v[108:111], v8 offset:24576
	ds_read_b128 v[112:115], v8 offset:24592
	ds_read_b128 v[116:119], v8 offset:28672
	ds_read_b128 v[120:123], v8 offset:28688
	ds_read_b128 v[124:127], v8 offset:4128
	ds_read_b128 v[0:3], v8 offset:4144
	ds_read_b128 v[128:131], v8 offset:8224
	ds_read_b128 v[132:135], v8 offset:8240
	ds_read_b128 v[136:139], v8 offset:12320
	ds_read_b128 v[4:7], v8 offset:12336
	ds_read_b128 v[140:143], v8 offset:16416
	ds_read_b128 v[144:147], v8 offset:16432
	ds_read_b128 v[148:151], v8 offset:20512
	ds_read_b128 v[12:15], v8 offset:20528
	ds_read_b128 v[152:155], v8 offset:24608
	ds_read_b128 v[16:19], v8 offset:24624
	ds_read_b128 v[156:159], v8 offset:28704
	ds_read_b128 v[8:11], v8 offset:28720
	v_addc_co_u32_e32 v163, vcc, 0, v35, vcc
	v_add_co_u32_e32 v164, vcc, 0x2412000, v34
	global_load_dword v160, v[160:161], off
	s_nop 0
	global_load_dword v161, v[162:163], off
	v_addc_co_u32_e32 v165, vcc, 0, v35, vcc
	v_add_co_u32_e32 v162, vcc, 0x241b000, v34
	s_waitcnt lgkmcnt(14)
	v_mov_b32_e32 v168, v116
	v_addc_co_u32_e32 v163, vcc, 0, v35, vcc
	v_add_co_u32_e32 v166, vcc, 0x2424000, v34
	global_load_dword v164, v[164:165], off
	s_nop 0
	global_load_dword v165, v[162:163], off
	v_addc_co_u32_e32 v167, vcc, 0, v35, vcc
	v_add_co_u32_e32 v162, vcc, 0x242d000, v34
	v_mov_b32_e32 v169, v120
	s_nop 0
	v_addc_co_u32_e32 v163, vcc, 0, v35, vcc
	v_mov_b32_e32 v120, v117
	v_mov_b32_e32 v116, v118
	v_mov_b32_e32 v117, v122
	v_mov_b32_e32 v122, v119
	v_mov_b32_e32 v118, v52
	v_mov_b32_e32 v119, v68
	v_mov_b32_e32 v68, v53
	v_mov_b32_e32 v52, v54
	v_mov_b32_e32 v53, v70
	v_mov_b32_e32 v70, v55
	v_mov_b32_e32 v54, v56
	v_mov_b32_e32 v55, v72
	v_mov_b32_e32 v72, v57
	v_mov_b32_e32 v56, v58
	v_mov_b32_e32 v57, v74
	v_mov_b32_e32 v74, v59
	v_mov_b32_e32 v58, v60
	s_waitcnt lgkmcnt(13)
	v_mov_b32_e32 v59, v124
	v_mov_b32_e32 v124, v61
	v_mov_b32_e32 v60, v62
	v_mov_b32_e32 v61, v126
	v_mov_b32_e32 v126, v63
	v_mov_b32_e32 v62, v64
	s_waitcnt lgkmcnt(12)
	v_mov_b32_e32 v63, v0
	v_mov_b32_e32 v0, v65
	v_mov_b32_e32 v64, v66
	v_mov_b32_e32 v65, v2
	v_mov_b32_e32 v2, v67
	v_mov_b32_e32 v66, v76
	v_mov_b32_e32 v67, v84
	v_mov_b32_e32 v84, v77
	v_mov_b32_e32 v76, v78
	v_mov_b32_e32 v77, v86
	v_mov_b32_e32 v86, v79
	v_mov_b32_e32 v78, v80
	v_mov_b32_e32 v79, v88
	v_mov_b32_e32 v88, v81
	v_mov_b32_e32 v80, v82
	v_mov_b32_e32 v81, v90
	v_mov_b32_e32 v90, v83
	s_waitcnt lgkmcnt(11)
	v_mov_b32_e32 v82, v128
	s_waitcnt lgkmcnt(9)
	v_mov_b32_e32 v83, v136
	v_mov_b32_e32 v136, v129
	v_mov_b32_e32 v128, v130
	v_mov_b32_e32 v129, v138
	v_mov_b32_e32 v138, v131
	v_mov_b32_e32 v130, v132
	s_waitcnt lgkmcnt(8)
	v_mov_b32_e32 v131, v4
	v_mov_b32_e32 v4, v133
	v_mov_b32_e32 v132, v134
	v_mov_b32_e32 v133, v6
	v_mov_b32_e32 v6, v135
	v_mov_b32_e32 v134, v92
	v_mov_b32_e32 v135, v100
	v_mov_b32_e32 v100, v93
	v_mov_b32_e32 v92, v94
	v_mov_b32_e32 v93, v102
	v_mov_b32_e32 v102, v95
	v_mov_b32_e32 v94, v96
	v_mov_b32_e32 v95, v104
	v_mov_b32_e32 v104, v97
	v_mov_b32_e32 v96, v98
	v_mov_b32_e32 v97, v106
	v_mov_b32_e32 v106, v99
	s_waitcnt lgkmcnt(7)
	v_mov_b32_e32 v98, v140
	s_waitcnt lgkmcnt(5)
	v_mov_b32_e32 v99, v148
	v_mov_b32_e32 v148, v141
	v_mov_b32_e32 v140, v142
	v_mov_b32_e32 v141, v150
	v_mov_b32_e32 v150, v143
	v_mov_b32_e32 v142, v144
	s_waitcnt lgkmcnt(4)
	v_mov_b32_e32 v143, v12
	v_mov_b32_e32 v12, v145
	v_mov_b32_e32 v144, v146
	v_mov_b32_e32 v145, v14
	v_mov_b32_e32 v14, v147
	s_waitcnt lgkmcnt(1)
	v_mov_b32_e32 v146, v156
	s_waitcnt lgkmcnt(0)
	v_mov_b32_e32 v147, v8
	v_mov_b32_e32 v8, v157
	v_mov_b32_e32 v156, v158
	v_mov_b32_e32 v157, v10
	v_mov_b32_e32 v10, v159
	global_load_dword v158, v[166:167], off
	global_load_dword v159, v[162:163], off
	v_add_co_u32_e32 v166, vcc, 0x2436000, v34
	s_waitcnt vmcnt(4)
	v_mov_b32_e32 v180, v161
	v_addc_co_u32_e32 v167, vcc, 0, v35, vcc
	v_add_co_u32_e32 v162, vcc, 0x243f000, v34
	global_load_dword v166, v[166:167], off
	s_nop 0
	v_addc_co_u32_e32 v163, vcc, 0, v35, vcc
	v_add_co_u32_e32 v170, vcc, 0x2448000, v34
	global_load_dword v167, v[162:163], off
	s_nop 0
	v_addc_co_u32_e32 v171, vcc, 0, v35, vcc
	v_add_co_u32_e32 v162, vcc, 0x2451000, v34
	v_pk_mul_f32 v[68:69], v[180:181], v[68:69] op_sel_hi:[0,1]
	s_nop 0
	v_addc_co_u32_e32 v163, vcc, 0, v35, vcc
	v_add_co_u32_e32 v172, vcc, 0x245a000, v34
	global_load_dword v170, v[170:171], off
	s_nop 0
	global_load_dword v171, v[162:163], off
	v_addc_co_u32_e32 v173, vcc, 0, v35, vcc
	v_add_co_u32_e32 v162, vcc, 0x2463000, v34
	v_pk_mul_f32 v[84:85], v[180:181], v[84:85] op_sel_hi:[0,1]
	s_nop 0
	v_addc_co_u32_e32 v163, vcc, 0, v35, vcc
	v_add_co_u32_e32 v174, vcc, 0x246c000, v34
	global_load_dword v172, v[172:173], off
	s_nop 0
	global_load_dword v173, v[162:163], off
	v_addc_co_u32_e32 v175, vcc, 0, v35, vcc
	v_add_co_u32_e32 v162, vcc, 0x2475000, v34
	v_pk_mul_f32 v[100:101], v[180:181], v[100:101] op_sel_hi:[0,1]
	s_nop 0
	v_addc_co_u32_e32 v163, vcc, 0, v35, vcc
	v_add_co_u32_e32 v176, vcc, 0x247e000, v34
	global_load_dword v174, v[174:175], off
	s_nop 0
	global_load_dword v20, v[162:163], off
	v_addc_co_u32_e32 v177, vcc, 0, v35, vcc
	v_add_co_u32_e32 v34, vcc, 0x2487000, v34
	v_pk_fma_f32 v[68:69], v[160:161], v[118:119], v[68:69] op_sel_hi:[0,1,1]
	s_nop 0
	v_addc_co_u32_e32 v35, vcc, 0, v35, vcc
	global_load_dword v162, v[176:177], off
	s_nop 0
	global_load_dword v34, v[34:35], off
	v_pk_fma_f32 v[66:67], v[160:161], v[66:67], v[84:85] op_sel_hi:[0,1,1]
	v_pk_fma_f32 v[84:85], v[160:161], v[134:135], v[100:101] op_sel_hi:[0,1,1]
	s_waitcnt vmcnt(12)
	v_mov_b32_e32 v118, v165
	v_pk_fma_f32 v[52:53], v[164:165], v[52:53], v[68:69] op_sel_hi:[0,1,1]
	v_pk_fma_f32 v[66:67], v[164:165], v[76:77], v[66:67] op_sel_hi:[0,1,1]
	v_pk_fma_f32 v[68:69], v[164:165], v[92:93], v[84:85] op_sel_hi:[0,1,1]
	v_pk_fma_f32 v[52:53], v[118:119], v[70:71], v[52:53] op_sel_hi:[0,1,1]
	v_pk_fma_f32 v[66:67], v[118:119], v[86:87], v[66:67] op_sel_hi:[0,1,1]
	v_pk_fma_f32 v[68:69], v[118:119], v[102:103], v[68:69] op_sel_hi:[0,1,1]
	v_pk_add_f32 v[32:33], v[32:33], v[52:53]
	v_pk_add_f32 v[30:31], v[30:31], v[66:67]
	v_pk_add_f32 v[28:29], v[28:29], v[68:69]
	v_mov_b32_e32 v182, v161
	v_mov_b32_e32 v176, v160
	v_mul_f32_e32 v178, v161, v109
	v_pk_fma_f32 v[108:109], v[160:161], v[108:109], v[178:179] op_sel_hi:[1,1,0]
	v_mov_b32_e32 v178, v164
	v_pk_fma_f32 v[108:109], v[164:165], v[110:111], v[108:109]
	v_mul_f32_e32 v110, v165, v111
	v_mov_b32_e32 v184, v165
	v_pk_add_f32 v[100:101], v[110:111], v[108:109] op_sel_hi:[0,1]
	s_add_u32 s4, s4, 0x90000
	s_addc_u32 s5, s5, 0
	s_add_i32 s6, s6, 64
	s_cmp_eq_u32 s4, 0x480000
	s_waitcnt vmcnt(11)
	v_mov_b32_e32 v177, v158
	s_waitcnt vmcnt(10)
	v_mov_b32_e32 v70, v159
	v_pk_mul_f32 v[52:53], v[70:71], v[72:73] op_sel_hi:[0,1]
	v_pk_mul_f32 v[66:67], v[70:71], v[88:89] op_sel_hi:[0,1]
	v_pk_mul_f32 v[68:69], v[70:71], v[104:105] op_sel_hi:[0,1]
	v_pk_fma_f32 v[52:53], v[158:159], v[54:55], v[52:53] op_sel_hi:[0,1,1]
	v_pk_fma_f32 v[66:67], v[158:159], v[78:79], v[66:67] op_sel_hi:[0,1,1]
	v_pk_fma_f32 v[68:69], v[158:159], v[94:95], v[68:69] op_sel_hi:[0,1,1]
	v_mul_f32_e32 v76, v159, v113
	v_mov_b32_e32 v183, v159
	v_pk_fma_f32 v[76:77], v[158:159], v[112:113], v[76:77] op_sel_hi:[1,1,0]
	v_pk_mul_f32 v[84:85], v[182:183], v[120:121]
	s_waitcnt vmcnt(9)
	v_mov_b32_e32 v179, v166
	s_waitcnt vmcnt(8)
	v_mov_b32_e32 v54, v167
	v_pk_fma_f32 v[52:53], v[166:167], v[56:57], v[52:53] op_sel_hi:[0,1,1]
	v_pk_fma_f32 v[56:57], v[166:167], v[80:81], v[66:67] op_sel_hi:[0,1,1]
	v_pk_fma_f32 v[66:67], v[166:167], v[96:97], v[68:69] op_sel_hi:[0,1,1]
	v_pk_fma_f32 v[52:53], v[54:55], v[74:75], v[52:53] op_sel_hi:[0,1,1]
	v_pk_fma_f32 v[56:57], v[54:55], v[90:91], v[56:57] op_sel_hi:[0,1,1]
	v_pk_fma_f32 v[54:55], v[54:55], v[106:107], v[66:67] op_sel_hi:[0,1,1]
	v_pk_add_f32 v[32:33], v[32:33], v[52:53]
	v_pk_add_f32 v[30:31], v[30:31], v[56:57]
	v_pk_add_f32 v[28:29], v[28:29], v[54:55]
	s_waitcnt vmcnt(6)
	v_mov_b32_e32 v74, v171
	v_pk_mul_f32 v[52:53], v[74:75], v[124:125] op_sel_hi:[0,1]
	v_pk_mul_f32 v[56:57], v[74:75], v[136:137] op_sel_hi:[0,1]
	v_pk_mul_f32 v[54:55], v[74:75], v[148:149] op_sel_hi:[0,1]
	v_pk_fma_f32 v[70:71], v[166:167], v[114:115], v[76:77]
	v_mul_f32_e32 v72, v167, v115
	v_pk_fma_f32 v[76:77], v[176:177], v[168:169], v[84:85]
	v_mov_b32_e32 v66, v171
	v_pk_fma_f32 v[52:53], v[170:171], v[58:59], v[52:53] op_sel_hi:[0,1,1]
	v_pk_fma_f32 v[56:57], v[170:171], v[82:83], v[56:57] op_sel_hi:[0,1,1]
	v_pk_fma_f32 v[54:55], v[170:171], v[98:99], v[54:55] op_sel_hi:[0,1,1]
	v_mov_b32_e32 v185, v167
	v_pk_add_f32 v[70:71], v[72:73], v[70:71] op_sel_hi:[0,1]
	v_pk_fma_f32 v[72:73], v[178:179], v[116:117], v[76:77]
	v_mov_b32_e32 v68, v170
	v_mul_f32_e32 v76, v171, v153
	s_waitcnt vmcnt(4)
	v_mov_b32_e32 v58, v173
	v_pk_fma_f32 v[52:53], v[172:173], v[60:61], v[52:53] op_sel_hi:[0,1,1]
	v_pk_fma_f32 v[56:57], v[172:173], v[128:129], v[56:57] op_sel_hi:[0,1,1]
	v_pk_fma_f32 v[54:55], v[172:173], v[140:141], v[54:55] op_sel_hi:[0,1,1]
	s_waitcnt vmcnt(2)
	v_pk_mul_f32 v[0:1], v[20:21], v[0:1] op_sel_hi:[0,1]
	v_pk_mul_f32 v[4:5], v[20:21], v[4:5] op_sel_hi:[0,1]
	v_mov_b32_e32 v67, v20
	v_mov_b32_e32 v69, v174
	v_pk_mul_f32 v[12:13], v[20:21], v[12:13] op_sel_hi:[0,1]
	v_pk_fma_f32 v[0:1], v[174:175], v[62:63], v[0:1] op_sel_hi:[0,1,1]
	v_pk_fma_f32 v[4:5], v[174:175], v[130:131], v[4:5] op_sel_hi:[0,1,1]
	v_pk_mul_f32 v[8:9], v[66:67], v[8:9]
	v_pk_fma_f32 v[72:73], v[184:185], v[122:123], v[72:73]
	v_pk_fma_f32 v[76:77], v[170:171], v[152:153], v[76:77] op_sel_hi:[1,1,0]
	v_mov_b32_e32 v74, v172
	v_pk_fma_f32 v[52:53], v[58:59], v[126:127], v[52:53] op_sel_hi:[0,1,1]
	v_pk_fma_f32 v[56:57], v[58:59], v[138:139], v[56:57] op_sel_hi:[0,1,1]
	v_pk_fma_f32 v[54:55], v[58:59], v[150:151], v[54:55] op_sel_hi:[0,1,1]
	v_mul_f32_e32 v58, v20, v17
	v_pk_fma_f32 v[12:13], v[174:175], v[142:143], v[12:13] op_sel_hi:[0,1,1]
	v_mov_b32_e32 v175, v20
	s_waitcnt vmcnt(1)
	v_mov_b32_e32 v75, v162
	v_pk_fma_f32 v[0:1], v[162:163], v[64:65], v[0:1] op_sel_hi:[0,1,1]
	v_pk_fma_f32 v[4:5], v[162:163], v[132:133], v[4:5] op_sel_hi:[0,1,1]
	v_pk_fma_f32 v[8:9], v[68:69], v[146:147], v[8:9]
	v_mov_b32_e32 v101, v72
	v_mov_b32_e32 v71, v73
	v_pk_fma_f32 v[72:73], v[172:173], v[154:155], v[76:77]
	v_mul_f32_e32 v76, v173, v155
	v_mov_b32_e32 v78, v173
	v_pk_add_f32 v[30:31], v[30:31], v[56:57]
	v_pk_fma_f32 v[12:13], v[162:163], v[144:145], v[12:13] op_sel_hi:[0,1,1]
	v_pk_fma_f32 v[16:17], v[174:175], v[16:17], v[58:59] op_sel_hi:[1,1,0]
	s_waitcnt vmcnt(0)
	v_mov_b32_e32 v163, v34
	v_mov_b32_e32 v79, v34
	v_pk_fma_f32 v[0:1], v[34:35], v[2:3], v[0:1] op_sel_hi:[0,1,1]
	v_pk_fma_f32 v[2:3], v[34:35], v[6:7], v[4:5] op_sel_hi:[0,1,1]
	v_pk_fma_f32 v[8:9], v[74:75], v[156:157], v[8:9]
	v_pk_add_f32 v[24:25], v[24:25], v[100:101]
	v_pk_add_f32 v[72:73], v[76:77], v[72:73] op_sel_hi:[0,1]
	v_pk_add_f32 v[32:33], v[32:33], v[52:53]
	v_mul_f32_e32 v20, v34, v19
	v_pk_fma_f32 v[6:7], v[162:163], v[18:19], v[16:17]
	v_pk_add_f32 v[30:31], v[30:31], v[2:3]
	v_pk_fma_f32 v[2:3], v[78:79], v[10:11], v[8:9]
	v_pk_add_f32 v[24:25], v[24:25], v[70:71]
	v_pk_add_f32 v[32:33], v[32:33], v[0:1]
	v_pk_add_f32 v[0:1], v[20:21], v[6:7] op_sel_hi:[0,1]
	v_mov_b32_e32 v73, v2
	v_pk_add_f32 v[28:29], v[28:29], v[54:55]
	v_pk_fma_f32 v[4:5], v[34:35], v[14:15], v[12:13] op_sel_hi:[0,1,1]
	v_mov_b32_e32 v1, v3
	v_pk_add_f32 v[2:3], v[24:25], v[72:73]
	v_pk_add_f32 v[28:29], v[28:29], v[4:5]
	v_pk_add_f32 v[24:25], v[2:3], v[0:1]
	s_cbranch_scc0 .LBB0_766
	s_lshl_b32 s4, s10, 3
	s_andn2_b32 s4, s4, 63
	v_add_u32_e32 v0, s4, v181
	v_ashrrev_i32_e32 v1, 31, v0
	v_lshl_add_u64 v[0:1], v[0:1], 2, s[0:1]
	v_add_co_u32_e32 v2, vcc, 0x240000, v0
	s_nop 1
	v_addc_co_u32_e32 v3, vcc, 0, v1, vcc
	global_store_dword v[2:3], v32, off nt
	v_add_co_u32_e32 v2, vcc, 0x249000, v0
	s_nop 1
	v_addc_co_u32_e32 v3, vcc, 0, v1, vcc
	global_store_dword v[2:3], v33, off nt
	v_add_co_u32_e32 v2, vcc, 0x252000, v0
	s_nop 1
	v_addc_co_u32_e32 v3, vcc, 0, v1, vcc
	global_store_dword v[2:3], v30, off nt
	v_add_co_u32_e32 v2, vcc, 0x25b000, v0
	s_nop 1
	v_addc_co_u32_e32 v3, vcc, 0, v1, vcc
	global_store_dword v[2:3], v31, off nt
	v_add_co_u32_e32 v2, vcc, 0x264000, v0
	s_nop 1
	v_addc_co_u32_e32 v3, vcc, 0, v1, vcc
	global_store_dword v[2:3], v28, off nt
	v_add_co_u32_e32 v2, vcc, 0x26d000, v0
	s_nop 1
	v_addc_co_u32_e32 v3, vcc, 0, v1, vcc
	global_store_dword v[2:3], v29, off nt
	v_add_co_u32_e32 v2, vcc, 0x276000, v0
	s_nop 1
	v_addc_co_u32_e32 v3, vcc, 0, v1, vcc
	v_add_co_u32_e32 v0, vcc, 0x27f000, v0
	global_store_dword v[2:3], v24, off nt
	s_nop 0
	v_addc_co_u32_e32 v1, vcc, 0, v1, vcc
	global_store_dword v[0:1], v25, off nt
	s_branch .LBB0_725

.LBB0_1074:
	v_lshl_or_b32 v128, s26, 8, v169
	v_lshl_add_u32 v150, s24, 8, v167
	v_ashrrev_i32_e32 v129, 31, v128
	v_mov_b64_e32 v[152:153], s[2:3]
	v_mad_i64_i32 v[130:131], s[28:29], v150, s51, v[152:153]
	v_lshlrev_b64 v[148:149], 1, v[128:129]
	v_lshl_add_u64 v[128:129], v[130:131], 0, v[148:149]
	global_load_dwordx4 v[174:177], v[128:129], off offset:2048
	global_load_dwordx4 v[178:181], v[128:129], off offset:2304
	v_or_b32_e32 v128, 16, v150
	v_mad_i64_i32 v[130:131], s[28:29], v128, s51, v[152:153]
	v_lshl_add_u64 v[130:131], v[130:131], 0, v[148:149]
	global_load_dwordx4 v[182:185], v[130:131], off offset:2048
	global_load_dwordx4 v[186:189], v[130:131], off offset:2304
	v_or_b32_e32 v198, 32, v150
	v_mad_i64_i32 v[190:191], s[28:29], v198, s51, v[152:153]
	v_lshl_add_u64 v[196:197], v[190:191], 0, v[148:149]
	global_load_dwordx4 v[190:193], v[196:197], off offset:2048
	v_ashrrev_i32_e32 v151, 31, v150
	v_or_b32_e32 v154, 48, v150
	v_ashrrev_i32_e32 v129, 31, v128
	v_lshlrev_b64 v[130:131], 11, v[150:151]
	v_mad_i64_i32 v[194:195], s[28:29], v154, s51, v[152:153]
	v_lshl_add_u64 v[130:131], s[4:5], 0, v[130:131]
	v_lshlrev_b64 v[128:129], 11, v[128:129]
	v_lshl_add_u64 v[200:201], v[194:195], 0, v[148:149]
	v_lshl_add_u64 v[210:211], v[130:131], 0, v[148:149]
	v_lshl_add_u64 v[212:213], s[4:5], 0, v[128:129]
	global_load_dwordx4 v[194:197], v[196:197], off offset:2304
	s_nop 0
	global_load_dwordx4 v[128:131], v[200:201], off offset:2048
	v_lshl_add_u64 v[212:213], v[212:213], 0, v[148:149]
	v_ashrrev_i32_e32 v199, 31, v198
	v_ashrrev_i32_e32 v155, 31, v154
	s_andn2_b64 vcc, exec, s[0:1]
	s_mov_b64 s[0:1], -1
	s_waitcnt vmcnt(0)
	v_lshlrev_b32_e32 v214, 16, v175
	v_and_b32_e32 v215, 0xffff0000, v175
	v_lshlrev_b32_e32 v216, 16, v174
	v_and_b32_e32 v217, 0xffff0000, v174
	v_lshlrev_b32_e32 v174, 16, v176
	v_and_b32_e32 v175, 0xffff0000, v176
	v_lshlrev_b32_e32 v176, 16, v177
	v_and_b32_e32 v177, 0xffff0000, v177
	v_lshlrev_b32_e32 v218, 16, v179
	v_and_b32_e32 v219, 0xffff0000, v179
	v_lshlrev_b32_e32 v220, 16, v178
	v_and_b32_e32 v221, 0xffff0000, v178
	v_lshlrev_b32_e32 v178, 16, v180
	v_and_b32_e32 v179, 0xffff0000, v180
	v_lshlrev_b32_e32 v180, 16, v181
	v_and_b32_e32 v181, 0xffff0000, v181
	v_lshlrev_b32_e32 v222, 16, v183
	v_and_b32_e32 v223, 0xffff0000, v183
	v_lshlrev_b32_e32 v224, 16, v182
	v_and_b32_e32 v225, 0xffff0000, v182
	v_lshlrev_b32_e32 v182, 16, v184
	v_and_b32_e32 v183, 0xffff0000, v184
	v_lshlrev_b32_e32 v184, 16, v185
	v_and_b32_e32 v185, 0xffff0000, v185
	v_pk_mul_f32 v[126:127], v[126:127], v[214:215]
	v_pk_mul_f32 v[124:125], v[124:125], v[216:217]
	v_pk_mul_f32 v[120:121], v[120:121], v[174:175]
	v_pk_mul_f32 v[122:123], v[122:123], v[176:177]
	v_pk_mul_f32 v[110:111], v[110:111], v[218:219]
	v_pk_mul_f32 v[108:109], v[108:109], v[220:221]
	v_pk_mul_f32 v[174:175], v[104:105], v[178:179]
	v_pk_mul_f32 v[176:177], v[106:107], v[180:181]
	v_pk_mul_f32 v[118:119], v[118:119], v[222:223]
	v_pk_mul_f32 v[116:117], v[116:117], v[224:225]
	v_pk_mul_f32 v[178:179], v[112:113], v[182:183]
	v_pk_mul_f32 v[180:181], v[114:115], v[184:185]
	v_cvt_pk_bf16_f32 v104, v124, v125
	v_cvt_pk_bf16_f32 v105, v126, v127
	v_cvt_pk_bf16_f32 v106, v120, v121
	v_cvt_pk_bf16_f32 v107, v122, v123
	v_lshlrev_b32_e32 v226, 16, v187
	v_and_b32_e32 v227, 0xffff0000, v187
	v_cvt_pk_bf16_f32 v108, v108, v109
	v_cvt_pk_bf16_f32 v109, v110, v111
	v_cvt_pk_bf16_f32 v110, v174, v175
	v_cvt_pk_bf16_f32 v111, v176, v177
	v_cvt_pk_bf16_f32 v112, v116, v117
	v_cvt_pk_bf16_f32 v113, v118, v119
	v_cvt_pk_bf16_f32 v114, v178, v179
	v_cvt_pk_bf16_f32 v115, v180, v181
	global_store_dwordx4 v[210:211], v[104:107], off nt
	global_store_dwordx4 v[210:211], v[108:111], off offset:256 nt
	global_store_dwordx4 v[212:213], v[112:115], off nt
	v_lshlrev_b32_e32 v104, 16, v186
	v_and_b32_e32 v105, 0xffff0000, v186
	v_pk_mul_f32 v[102:103], v[102:103], v[226:227]
	v_pk_mul_f32 v[100:101], v[100:101], v[104:105]
	global_load_dwordx4 v[104:107], v[200:201], off offset:2304
	v_cvt_pk_bf16_f32 v100, v100, v101
	v_cvt_pk_bf16_f32 v101, v102, v103
	v_lshlrev_b32_e32 v102, 16, v188
	v_and_b32_e32 v103, 0xffff0000, v188
	v_pk_mul_f32 v[96:97], v[96:97], v[102:103]
	v_add_u32_e32 v108, 0x80, v150
	v_cvt_pk_bf16_f32 v102, v96, v97
	v_lshlrev_b32_e32 v96, 16, v189
	v_and_b32_e32 v97, 0xffff0000, v189
	v_pk_mul_f32 v[96:97], v[98:99], v[96:97]
	v_lshlrev_b32_e32 v98, 16, v190
	v_and_b32_e32 v99, 0xffff0000, v190
	v_cvt_pk_bf16_f32 v103, v96, v97
	v_lshlrev_b32_e32 v96, 16, v191
	v_and_b32_e32 v97, 0xffff0000, v191
	v_pk_mul_f32 v[92:93], v[92:93], v[98:99]
	global_store_dwordx4 v[212:213], v[100:103], off offset:256 nt
	v_cvt_pk_bf16_f32 v98, v92, v93
	v_lshlrev_b32_e32 v92, 16, v192
	v_pk_mul_f32 v[100:101], v[94:95], v[96:97]
	v_mad_i64_i32 v[94:95], s[28:29], v108, s51, v[152:153]
	v_and_b32_e32 v93, 0xffff0000, v192
	v_lshl_add_u64 v[110:111], v[94:95], 0, v[148:149]
	v_pk_mul_f32 v[88:89], v[88:89], v[92:93]
	global_load_dwordx4 v[94:97], v[110:111], off offset:2048
	v_cvt_pk_bf16_f32 v99, v100, v101
	v_cvt_pk_bf16_f32 v100, v88, v89
	v_lshlrev_b32_e32 v88, 16, v193
	v_and_b32_e32 v89, 0xffff0000, v193
	v_lshlrev_b64 v[102:103], 11, v[198:199]
	v_pk_mul_f32 v[88:89], v[90:91], v[88:89]
	v_ashrrev_i32_e32 v109, 31, v108
	v_cvt_pk_bf16_f32 v101, v88, v89
	v_lshl_add_u64 v[88:89], s[4:5], 0, v[102:103]
	v_lshl_add_u64 v[92:93], v[88:89], 0, v[148:149]
	v_lshlrev_b32_e32 v88, 16, v195
	v_and_b32_e32 v89, 0xffff0000, v195
	v_pk_mul_f32 v[82:83], v[82:83], v[88:89]
	v_lshlrev_b32_e32 v88, 16, v194
	v_and_b32_e32 v89, 0xffff0000, v194
	v_pk_mul_f32 v[80:81], v[80:81], v[88:89]
	global_load_dwordx4 v[88:91], v[110:111], off offset:2304
	v_cvt_pk_bf16_f32 v80, v80, v81
	v_cvt_pk_bf16_f32 v81, v82, v83
	v_lshlrev_b32_e32 v82, 16, v196
	v_and_b32_e32 v83, 0xffff0000, v196
	v_pk_mul_f32 v[76:77], v[76:77], v[82:83]
	global_store_dwordx4 v[92:93], v[98:101], off nt
	v_cvt_pk_bf16_f32 v82, v76, v77
	v_lshlrev_b32_e32 v76, 16, v197
	v_and_b32_e32 v77, 0xffff0000, v197
	v_pk_mul_f32 v[76:77], v[78:79], v[76:77]
	s_nop 0
	v_cvt_pk_bf16_f32 v83, v76, v77
	v_lshlrev_b32_e32 v76, 16, v129
	v_and_b32_e32 v77, 0xffff0000, v129
	v_pk_mul_f32 v[78:79], v[86:87], v[76:77]
	v_lshlrev_b32_e32 v76, 16, v128
	v_and_b32_e32 v77, 0xffff0000, v128
	v_pk_mul_f32 v[76:77], v[84:85], v[76:77]
	v_add_u32_e32 v84, 0x90, v150
	global_store_dwordx4 v[92:93], v[80:83], off offset:256 nt
	v_cvt_pk_bf16_f32 v76, v76, v77
	v_cvt_pk_bf16_f32 v77, v78, v79
	v_mad_i64_i32 v[80:81], s[28:29], v84, s51, v[152:153]
	v_lshl_add_u64 v[86:87], v[80:81], 0, v[148:149]
	global_load_dwordx4 v[80:83], v[86:87], off offset:2048
	v_lshlrev_b32_e32 v78, 16, v130
	v_and_b32_e32 v79, 0xffff0000, v130
	v_pk_mul_f32 v[72:73], v[72:73], v[78:79]
	v_lshlrev_b64 v[92:93], 11, v[154:155]
	v_cvt_pk_bf16_f32 v78, v72, v73
	v_lshlrev_b32_e32 v72, 16, v131
	v_and_b32_e32 v73, 0xffff0000, v131
	v_pk_mul_f32 v[72:73], v[74:75], v[72:73]
	v_ashrrev_i32_e32 v85, 31, v84
	v_cvt_pk_bf16_f32 v79, v72, v73
	v_lshl_add_u64 v[72:73], s[4:5], 0, v[92:93]
	v_lshl_add_u64 v[92:93], v[72:73], 0, v[148:149]
	s_waitcnt vmcnt(6)
	v_lshlrev_b32_e32 v72, 16, v105
	v_and_b32_e32 v73, 0xffff0000, v105
	v_pk_mul_f32 v[70:71], v[70:71], v[72:73]
	v_lshlrev_b32_e32 v72, 16, v104
	v_and_b32_e32 v73, 0xffff0000, v104
	v_pk_mul_f32 v[68:69], v[68:69], v[72:73]
	global_load_dwordx4 v[72:75], v[86:87], off offset:2304
	v_cvt_pk_bf16_f32 v68, v68, v69
	v_cvt_pk_bf16_f32 v69, v70, v71
	v_lshlrev_b32_e32 v70, 16, v106
	v_and_b32_e32 v71, 0xffff0000, v106
	v_pk_mul_f32 v[64:65], v[64:65], v[70:71]
	global_store_dwordx4 v[92:93], v[76:79], off nt
	v_cvt_pk_bf16_f32 v70, v64, v65
	v_lshlrev_b32_e32 v64, 16, v107
	v_and_b32_e32 v65, 0xffff0000, v107
	v_pk_mul_f32 v[64:65], v[66:67], v[64:65]
	v_add_u32_e32 v76, 0xa0, v150
	v_cvt_pk_bf16_f32 v71, v64, v65
	global_store_dwordx4 v[92:93], v[68:71], off offset:256 nt
	v_ashrrev_i32_e32 v77, 31, v76
	s_waitcnt vmcnt(7)
	v_lshlrev_b32_e32 v64, 16, v95
	v_and_b32_e32 v65, 0xffff0000, v95
	v_pk_mul_f32 v[68:69], v[62:63], v[64:65]
	v_lshlrev_b32_e32 v66, 16, v94
	v_mad_i64_i32 v[62:63], s[28:29], v76, s51, v[152:153]
	v_and_b32_e32 v67, 0xffff0000, v94
	v_lshl_add_u64 v[78:79], v[62:63], 0, v[148:149]
	v_pk_mul_f32 v[60:61], v[60:61], v[66:67]
	global_load_dwordx4 v[62:65], v[78:79], off offset:2048
	v_cvt_pk_bf16_f32 v66, v60, v61
	v_lshlrev_b32_e32 v60, 16, v96
	v_and_b32_e32 v61, 0xffff0000, v96
	v_pk_mul_f32 v[56:57], v[56:57], v[60:61]
	v_cvt_pk_bf16_f32 v67, v68, v69
	v_cvt_pk_bf16_f32 v68, v56, v57
	v_lshlrev_b32_e32 v56, 16, v97
	v_and_b32_e32 v57, 0xffff0000, v97
	v_lshlrev_b64 v[70:71], 11, v[108:109]
	v_pk_mul_f32 v[56:57], v[58:59], v[56:57]
	s_waitcnt vmcnt(7)
	v_lshlrev_b32_e32 v58, 16, v88
	v_cvt_pk_bf16_f32 v69, v56, v57
	v_lshl_add_u64 v[56:57], s[4:5], 0, v[70:71]
	v_lshl_add_u64 v[70:71], v[56:57], 0, v[148:149]
	v_lshlrev_b32_e32 v56, 16, v89
	v_and_b32_e32 v57, 0xffff0000, v89
	v_and_b32_e32 v59, 0xffff0000, v88
	v_pk_mul_f32 v[60:61], v[54:55], v[56:57]
	global_load_dwordx4 v[54:57], v[78:79], off offset:2304
	v_pk_mul_f32 v[52:53], v[52:53], v[58:59]
	v_cvt_pk_bf16_f32 v59, v60, v61
	v_cvt_pk_bf16_f32 v58, v52, v53
	v_lshlrev_b32_e32 v52, 16, v90
	v_and_b32_e32 v53, 0xffff0000, v90
	v_pk_mul_f32 v[44:45], v[44:45], v[52:53]
	v_add_u32_e32 v52, 0xb0, v150
	v_cvt_pk_bf16_f32 v60, v44, v45
	v_lshlrev_b32_e32 v44, 16, v91
	v_and_b32_e32 v45, 0xffff0000, v91
	v_pk_mul_f32 v[44:45], v[46:47], v[44:45]
	global_store_dwordx4 v[70:71], v[66:69], off nt
	v_cvt_pk_bf16_f32 v61, v44, v45
	v_mad_i64_i32 v[44:45], s[28:29], v52, s51, v[152:153]
	v_lshl_add_u64 v[66:67], v[44:45], 0, v[148:149]
	global_store_dwordx4 v[70:71], v[58:61], off offset:256 nt
	global_load_dwordx4 v[44:47], v[66:67], off offset:2048
	v_ashrrev_i32_e32 v53, 31, v52
	s_waitcnt vmcnt(8)
	v_lshlrev_b32_e32 v60, 16, v81
	v_and_b32_e32 v61, 0xffff0000, v81
	v_pk_mul_f32 v[50:51], v[50:51], v[60:61]
	v_lshlrev_b32_e32 v60, 16, v80
	v_and_b32_e32 v61, 0xffff0000, v80
	v_pk_mul_f32 v[48:49], v[48:49], v[60:61]
	v_lshlrev_b64 v[58:59], 11, v[84:85]
	v_cvt_pk_bf16_f32 v48, v48, v49
	v_cvt_pk_bf16_f32 v49, v50, v51
	v_lshlrev_b32_e32 v50, 16, v82
	v_and_b32_e32 v51, 0xffff0000, v82
	v_pk_mul_f32 v[40:41], v[40:41], v[50:51]
	v_lshl_add_u64 v[58:59], s[4:5], 0, v[58:59]
	v_cvt_pk_bf16_f32 v50, v40, v41
	v_lshlrev_b32_e32 v40, 16, v83
	v_and_b32_e32 v41, 0xffff0000, v83
	v_pk_mul_f32 v[40:41], v[42:43], v[40:41]
	v_lshl_add_u64 v[58:59], v[58:59], 0, v[148:149]
	v_cvt_pk_bf16_f32 v51, v40, v41
	global_load_dwordx4 v[40:43], v[66:67], off offset:2304
	s_nop 0
	global_store_dwordx4 v[58:59], v[48:51], off nt
	s_waitcnt vmcnt(9)
	s_nop 0
	v_lshlrev_b32_e32 v48, 16, v73
	v_and_b32_e32 v49, 0xffff0000, v73
	v_pk_mul_f32 v[38:39], v[38:39], v[48:49]
	v_lshlrev_b32_e32 v48, 16, v72
	v_and_b32_e32 v49, 0xffff0000, v72
	v_pk_mul_f32 v[36:37], v[36:37], v[48:49]
	s_nop 0
	v_cvt_pk_bf16_f32 v36, v36, v37
	v_cvt_pk_bf16_f32 v37, v38, v39
	v_lshlrev_b32_e32 v38, 16, v74
	v_and_b32_e32 v39, 0xffff0000, v74
	v_pk_mul_f32 v[28:29], v[28:29], v[38:39]
	s_nop 0
	v_cvt_pk_bf16_f32 v38, v28, v29
	v_lshlrev_b32_e32 v28, 16, v75
	v_and_b32_e32 v29, 0xffff0000, v75
	v_pk_mul_f32 v[28:29], v[30:31], v[28:29]
	s_nop 0
	v_cvt_pk_bf16_f32 v39, v28, v29
	s_waitcnt vmcnt(6)
	v_lshlrev_b32_e32 v28, 16, v63
	v_and_b32_e32 v29, 0xffff0000, v63
	v_pk_mul_f32 v[30:31], v[34:35], v[28:29]
	v_lshlrev_b32_e32 v28, 16, v62
	v_and_b32_e32 v29, 0xffff0000, v62
	v_pk_mul_f32 v[28:29], v[32:33], v[28:29]
	global_store_dwordx4 v[58:59], v[36:39], off offset:256 nt
	v_cvt_pk_bf16_f32 v28, v28, v29
	v_cvt_pk_bf16_f32 v29, v30, v31
	v_lshlrev_b32_e32 v30, 16, v64
	v_and_b32_e32 v31, 0xffff0000, v64
	v_pk_mul_f32 v[24:25], v[24:25], v[30:31]
	v_lshlrev_b64 v[36:37], 11, v[76:77]
	v_cvt_pk_bf16_f32 v30, v24, v25
	v_lshlrev_b32_e32 v24, 16, v65
	v_and_b32_e32 v25, 0xffff0000, v65
	v_pk_mul_f32 v[24:25], v[26:27], v[24:25]
	s_waitcnt vmcnt(6)
	v_lshlrev_b32_e32 v26, 16, v55
	v_and_b32_e32 v27, 0xffff0000, v55
	v_pk_mul_f32 v[22:23], v[22:23], v[26:27]
	v_lshlrev_b32_e32 v26, 16, v54
	v_and_b32_e32 v27, 0xffff0000, v54
	v_pk_mul_f32 v[20:21], v[20:21], v[26:27]
	v_cvt_pk_bf16_f32 v31, v24, v25
	v_cvt_pk_bf16_f32 v20, v20, v21
	v_cvt_pk_bf16_f32 v21, v22, v23
	v_lshlrev_b32_e32 v22, 16, v56
	v_and_b32_e32 v23, 0xffff0000, v56
	v_pk_mul_f32 v[12:13], v[12:13], v[22:23]
	v_lshl_add_u64 v[24:25], s[4:5], 0, v[36:37]
	v_cvt_pk_bf16_f32 v22, v12, v13
	v_lshlrev_b32_e32 v12, 16, v57
	v_and_b32_e32 v13, 0xffff0000, v57
	v_pk_mul_f32 v[12:13], v[14:15], v[12:13]
	v_lshl_add_u64 v[24:25], v[24:25], 0, v[148:149]
	v_cvt_pk_bf16_f32 v23, v12, v13
	s_waitcnt vmcnt(3)
	v_lshlrev_b32_e32 v12, 16, v45
	v_and_b32_e32 v13, 0xffff0000, v45
	v_pk_mul_f32 v[14:15], v[18:19], v[12:13]
	v_lshlrev_b32_e32 v12, 16, v44
	v_and_b32_e32 v13, 0xffff0000, v44
	v_pk_mul_f32 v[12:13], v[16:17], v[12:13]
	global_store_dwordx4 v[24:25], v[20:23], off offset:256 nt
	v_cvt_pk_bf16_f32 v12, v12, v13
	v_cvt_pk_bf16_f32 v13, v14, v15
	v_lshlrev_b32_e32 v14, 16, v46
	v_and_b32_e32 v15, 0xffff0000, v46
	v_pk_mul_f32 v[8:9], v[8:9], v[14:15]
	v_lshlrev_b64 v[20:21], 11, v[52:53]
	v_cvt_pk_bf16_f32 v14, v8, v9
	v_lshlrev_b32_e32 v8, 16, v47
	v_and_b32_e32 v9, 0xffff0000, v47
	v_pk_mul_f32 v[8:9], v[10:11], v[8:9]
	global_store_dwordx4 v[24:25], v[28:31], off nt
	v_cvt_pk_bf16_f32 v15, v8, v9
	v_lshl_add_u64 v[8:9], s[4:5], 0, v[20:21]
	s_waitcnt vmcnt(4)
	v_lshlrev_b32_e32 v10, 16, v40
	v_and_b32_e32 v11, 0xffff0000, v40
	v_pk_mul_f32 v[4:5], v[4:5], v[10:11]
	v_lshlrev_b32_e32 v10, 16, v41
	v_and_b32_e32 v11, 0xffff0000, v41
	v_pk_mul_f32 v[6:7], v[6:7], v[10:11]
	v_cvt_pk_bf16_f32 v4, v4, v5
	v_cvt_pk_bf16_f32 v5, v6, v7
	v_lshlrev_b32_e32 v6, 16, v42
	v_and_b32_e32 v7, 0xffff0000, v42
	v_pk_mul_f32 v[0:1], v[0:1], v[6:7]
	v_lshl_add_u64 v[8:9], v[8:9], 0, v[148:149]
	v_cvt_pk_bf16_f32 v6, v0, v1
	v_lshlrev_b32_e32 v0, 16, v43
	v_and_b32_e32 v1, 0xffff0000, v43
	v_pk_mul_f32 v[0:1], v[2:3], v[0:1]
	global_store_dwordx4 v[8:9], v[12:15], off nt
	v_cvt_pk_bf16_f32 v7, v0, v1
	global_store_dwordx4 v[8:9], v[4:7], off offset:256 nt
	s_cbranch_vccnz .LBB0_1063
	s_andn2_b64 vcc, exec, s[10:11]
	s_cbranch_vccnz .LBB0_1062
	s_barrier
	s_branch .LBB0_1062

.LBB0_1098:
	v_lshl_add_u32 v144, s22, 8, v152
	v_lshl_or_b32 v150, s24, 8, v154
	v_mov_b64_e32 v[148:149], s[2:3]
	v_ashrrev_i32_e32 v151, 31, v150
	v_mad_i64_i32 v[146:147], s[26:27], v144, s49, v[148:149]
	v_lshl_add_u64 v[162:163], v[146:147], 0, s[12:13]
	v_lshlrev_b64 v[146:147], 1, v[150:151]
	v_ashrrev_i32_e32 v145, 31, v144
	v_or_b32_e32 v150, 0x80, v150
	v_lshlrev_b64 v[164:165], 11, v[144:145]
	v_ashrrev_i32_e32 v151, 31, v150
	v_lshl_add_u64 v[164:165], s[4:5], 0, v[164:165]
	v_lshlrev_b64 v[150:151], 1, v[150:151]
	v_lshl_add_u64 v[158:159], v[162:163], 0, v[146:147]
	v_lshl_add_u64 v[174:175], v[164:165], 0, v[146:147]
	v_lshl_add_u64 v[162:163], v[162:163], 0, v[150:151]
	global_load_dwordx4 v[158:161], v[158:159], off
	v_or_b32_e32 v166, 16, v144
	global_load_dwordx2 v[176:177], v[174:175], off sc1
	global_load_dwordx2 v[178:179], v[174:175], off offset:8 sc1
	s_nop 0
	global_load_dwordx4 v[162:165], v[162:163], off
	s_nop 0
	global_load_dwordx2 v[180:181], v[174:175], off offset:256 sc1
	global_load_dwordx2 v[182:183], v[174:175], off offset:264 sc1
	v_ashrrev_i32_e32 v167, 31, v166
	v_mad_i64_i32 v[168:169], s[26:27], v166, s49, v[148:149]
	v_lshl_add_u64 v[170:171], v[168:169], 0, s[12:13]
	v_lshlrev_b64 v[166:167], 11, v[166:167]
	v_lshl_add_u64 v[172:173], s[4:5], 0, v[166:167]
	v_lshl_add_u64 v[166:167], v[170:171], 0, v[146:147]
	global_load_dwordx4 v[166:169], v[166:167], off
	v_lshl_add_u64 v[184:185], v[172:173], 0, v[146:147]
	global_load_dwordx2 v[186:187], v[184:185], off sc1
	global_load_dwordx2 v[188:189], v[184:185], off offset:8 sc1
	v_lshl_add_u64 v[170:171], v[170:171], 0, v[150:151]
	global_load_dwordx4 v[170:173], v[170:171], off
	s_nop 0
	global_load_dwordx2 v[190:191], v[184:185], off offset:256 sc1
	global_load_dwordx2 v[192:193], v[184:185], off offset:264 sc1
	s_andn2_b64 vcc, exec, s[0:1]
	s_mov_b64 s[0:1], -1
	s_waitcnt vmcnt(0)
	v_lshlrev_b32_e32 v196, 16, v161
	v_and_b32_e32 v161, 0xffff0000, v161
	v_lshlrev_b32_e32 v207, 16, v164
	v_and_b32_e32 v164, 0xffff0000, v164
	v_lshlrev_b32_e32 v210, 16, v182
	v_and_b32_e32 v182, 0xffff0000, v182
	v_fmac_f32_e32 v210, v108, v207
	v_fmac_f32_e32 v182, v109, v164
	v_lshlrev_b32_e32 v108, 16, v165
	v_lshlrev_b32_e32 v109, 16, v183
	v_fmac_f32_e32 v109, v110, v108
	v_and_b32_e32 v108, 0xffff0000, v165
	v_and_b32_e32 v110, 0xffff0000, v183
	v_lshlrev_b32_e32 v200, 16, v179
	v_and_b32_e32 v179, 0xffff0000, v179
	v_fmac_f32_e32 v110, v111, v108
	v_fmac_f32_e32 v179, v123, v161
	v_cvt_pk_bf16_f32 v123, v109, v110
	v_and_b32_e32 v108, 0xffff0000, v167
	v_and_b32_e32 v109, 0xffff0000, v187
	v_fmac_f32_e32 v109, v115, v108
	v_lshlrev_b32_e32 v108, 16, v167
	v_lshlrev_b32_e32 v110, 16, v187
	v_fmac_f32_e32 v110, v114, v108
	v_and_b32_e32 v108, 0xffff0000, v166
	v_and_b32_e32 v111, 0xffff0000, v186
	v_fmac_f32_e32 v111, v113, v108
	v_lshlrev_b32_e32 v108, 16, v166
	v_lshlrev_b32_e32 v113, 16, v186
	v_fmac_f32_e32 v113, v112, v108
	v_cvt_pk_bf16_f32 v108, v113, v111
	v_cvt_pk_bf16_f32 v109, v110, v109
	v_lshlrev_b32_e32 v110, 16, v168
	v_lshlrev_b32_e32 v111, 16, v188
	v_fmac_f32_e32 v111, v104, v110
	v_and_b32_e32 v104, 0xffff0000, v168
	v_and_b32_e32 v110, 0xffff0000, v188
	v_fmac_f32_e32 v110, v105, v104
	v_lshlrev_b32_e32 v104, 16, v169
	v_lshlrev_b32_e32 v105, 16, v189
	v_fmac_f32_e32 v105, v106, v104
	v_and_b32_e32 v104, 0xffff0000, v169
	v_and_b32_e32 v106, 0xffff0000, v189
	v_fmac_f32_e32 v106, v107, v104
	v_cvt_pk_bf16_f32 v110, v111, v110
	v_cvt_pk_bf16_f32 v111, v105, v106
	v_and_b32_e32 v104, 0xffff0000, v171
	v_and_b32_e32 v105, 0xffff0000, v191
	v_fmac_f32_e32 v105, v103, v104
	v_lshlrev_b32_e32 v103, 16, v171
	v_lshlrev_b32_e32 v104, 16, v191
	v_fmac_f32_e32 v104, v102, v103
	v_and_b32_e32 v102, 0xffff0000, v170
	v_and_b32_e32 v103, 0xffff0000, v190
	v_fmac_f32_e32 v103, v101, v102
	v_lshlrev_b32_e32 v101, 16, v170
	v_lshlrev_b32_e32 v102, 16, v190
	v_fmac_f32_e32 v102, v100, v101
	v_cvt_pk_bf16_f32 v100, v102, v103
	v_lshlrev_b32_e32 v102, 16, v172
	v_lshlrev_b32_e32 v103, 16, v192
	v_fmac_f32_e32 v103, v96, v102
	v_and_b32_e32 v96, 0xffff0000, v172
	v_and_b32_e32 v102, 0xffff0000, v192
	v_fmac_f32_e32 v102, v97, v96
	v_lshlrev_b32_e32 v96, 16, v173
	v_lshlrev_b32_e32 v97, 16, v193
	v_fmac_f32_e32 v97, v98, v96
	v_and_b32_e32 v96, 0xffff0000, v173
	v_and_b32_e32 v98, 0xffff0000, v193
	v_and_b32_e32 v145, 0xffff0000, v159
	v_lshlrev_b32_e32 v159, 16, v159
	v_and_b32_e32 v194, 0xffff0000, v158
	v_lshlrev_b32_e32 v158, 16, v158
	v_lshlrev_b32_e32 v195, 16, v160
	v_and_b32_e32 v160, 0xffff0000, v160
	v_and_b32_e32 v197, 0xffff0000, v177
	v_lshlrev_b32_e32 v177, 16, v177
	v_and_b32_e32 v198, 0xffff0000, v176
	v_lshlrev_b32_e32 v176, 16, v176
	v_lshlrev_b32_e32 v199, 16, v178
	v_and_b32_e32 v178, 0xffff0000, v178
	v_fmac_f32_e32 v98, v99, v96
	v_or_b32_e32 v96, 32, v144
	v_and_b32_e32 v201, 0xffff0000, v163
	v_and_b32_e32 v204, 0xffff0000, v181
	v_lshlrev_b32_e32 v163, 16, v163
	v_lshlrev_b32_e32 v181, 16, v181
	v_and_b32_e32 v205, 0xffff0000, v162
	v_and_b32_e32 v206, 0xffff0000, v180
	v_lshlrev_b32_e32 v162, 16, v162
	v_lshlrev_b32_e32 v180, 16, v180
	v_fmac_f32_e32 v197, v127, v145
	v_fmac_f32_e32 v177, v126, v159
	v_fmac_f32_e32 v198, v125, v194
	v_fmac_f32_e32 v176, v124, v158
	v_fmac_f32_e32 v199, v120, v195
	v_fmac_f32_e32 v178, v121, v160
	v_fmac_f32_e32 v200, v122, v196
	v_cvt_pk_bf16_f32 v101, v104, v105
	v_cvt_pk_bf16_f32 v102, v103, v102
	v_cvt_pk_bf16_f32 v103, v97, v98
	v_ashrrev_i32_e32 v97, 31, v96
	v_mad_i64_i32 v[98:99], s[26:27], v96, s49, v[148:149]
	v_fmac_f32_e32 v204, v119, v201
	v_fmac_f32_e32 v181, v118, v163
	v_fmac_f32_e32 v206, v117, v205
	v_fmac_f32_e32 v180, v116, v162
	v_cvt_pk_bf16_f32 v116, v176, v198
	v_cvt_pk_bf16_f32 v117, v177, v197
	v_cvt_pk_bf16_f32 v118, v199, v178
	v_cvt_pk_bf16_f32 v119, v200, v179
	global_store_dwordx4 v[184:185], v[100:103], off offset:256 nt
	v_lshlrev_b64 v[96:97], 11, v[96:97]
	v_cvt_pk_bf16_f32 v120, v180, v206
	v_lshl_add_u64 v[100:101], v[98:99], 0, s[12:13]
	v_cvt_pk_bf16_f32 v121, v181, v204
	v_cvt_pk_bf16_f32 v122, v210, v182
	global_store_dwordx4 v[174:175], v[116:119], off nt
	global_store_dwordx4 v[184:185], v[108:111], off nt
	v_lshl_add_u64 v[102:103], s[4:5], 0, v[96:97]
	v_lshl_add_u64 v[96:97], v[100:101], 0, v[146:147]
	global_store_dwordx4 v[174:175], v[120:123], off offset:256 nt
	global_load_dwordx4 v[96:99], v[96:97], off
	v_lshl_add_u64 v[112:113], v[102:103], 0, v[146:147]
	global_load_dwordx2 v[114:115], v[112:113], off sc1
	global_load_dwordx2 v[116:117], v[112:113], off offset:8 sc1
	v_lshl_add_u64 v[100:101], v[100:101], 0, v[150:151]
	global_load_dwordx4 v[100:103], v[100:101], off
	s_nop 0
	global_load_dwordx2 v[118:119], v[112:113], off offset:256 sc1
	global_load_dwordx2 v[120:121], v[112:113], off offset:264 sc1
	v_or_b32_e32 v104, 48, v144
	v_ashrrev_i32_e32 v105, 31, v104
	v_mad_i64_i32 v[106:107], s[26:27], v104, s49, v[148:149]
	v_lshl_add_u64 v[108:109], v[106:107], 0, s[12:13]
	v_lshlrev_b64 v[104:105], 11, v[104:105]
	v_lshl_add_u64 v[110:111], s[4:5], 0, v[104:105]
	v_lshl_add_u64 v[104:105], v[108:109], 0, v[146:147]
	global_load_dwordx4 v[104:107], v[104:105], off
	v_lshl_add_u64 v[122:123], v[110:111], 0, v[146:147]
	global_load_dwordx2 v[124:125], v[122:123], off sc1
	global_load_dwordx2 v[126:127], v[122:123], off offset:8 sc1
	v_lshl_add_u64 v[108:109], v[108:109], 0, v[150:151]
	global_load_dwordx4 v[108:111], v[108:109], off
	s_nop 0
	global_load_dwordx2 v[158:159], v[122:123], off offset:256 sc1
	global_load_dwordx2 v[160:161], v[122:123], off offset:264 sc1
	s_waitcnt vmcnt(11)
	v_and_b32_e32 v145, 0xffff0000, v97
	s_waitcnt vmcnt(10)
	v_and_b32_e32 v162, 0xffff0000, v115
	v_fmac_f32_e32 v162, v95, v145
	v_lshlrev_b32_e32 v95, 16, v97
	v_lshlrev_b32_e32 v97, 16, v115
	v_fmac_f32_e32 v97, v94, v95
	v_and_b32_e32 v94, 0xffff0000, v96
	v_and_b32_e32 v95, 0xffff0000, v114
	v_fmac_f32_e32 v95, v93, v94
	v_lshlrev_b32_e32 v93, 16, v96
	v_lshlrev_b32_e32 v94, 16, v114
	v_fmac_f32_e32 v94, v92, v93
	v_cvt_pk_bf16_f32 v92, v94, v95
	v_lshlrev_b32_e32 v94, 16, v98
	s_waitcnt vmcnt(9)
	v_lshlrev_b32_e32 v95, 16, v116
	v_fmac_f32_e32 v95, v88, v94
	v_and_b32_e32 v88, 0xffff0000, v98
	v_and_b32_e32 v94, 0xffff0000, v116
	v_fmac_f32_e32 v94, v89, v88
	v_lshlrev_b32_e32 v88, 16, v99
	v_lshlrev_b32_e32 v89, 16, v117
	v_fmac_f32_e32 v89, v90, v88
	v_and_b32_e32 v88, 0xffff0000, v99
	v_and_b32_e32 v90, 0xffff0000, v117
	v_fmac_f32_e32 v90, v91, v88
	v_cvt_pk_bf16_f32 v94, v95, v94
	v_cvt_pk_bf16_f32 v95, v89, v90
	s_waitcnt vmcnt(8)
	v_and_b32_e32 v88, 0xffff0000, v101
	s_waitcnt vmcnt(7)
	v_and_b32_e32 v89, 0xffff0000, v119
	v_fmac_f32_e32 v89, v87, v88
	v_lshlrev_b32_e32 v87, 16, v101
	v_lshlrev_b32_e32 v88, 16, v119
	v_fmac_f32_e32 v88, v86, v87
	v_and_b32_e32 v86, 0xffff0000, v100
	v_and_b32_e32 v87, 0xffff0000, v118
	v_fmac_f32_e32 v87, v85, v86
	v_lshlrev_b32_e32 v85, 16, v100
	v_lshlrev_b32_e32 v86, 16, v118
	v_fmac_f32_e32 v86, v84, v85
	v_cvt_pk_bf16_f32 v84, v86, v87
	v_lshlrev_b32_e32 v86, 16, v102
	s_waitcnt vmcnt(6)
	v_lshlrev_b32_e32 v87, 16, v120
	v_fmac_f32_e32 v87, v76, v86
	v_and_b32_e32 v76, 0xffff0000, v102
	v_and_b32_e32 v86, 0xffff0000, v120
	v_fmac_f32_e32 v86, v77, v76
	v_lshlrev_b32_e32 v76, 16, v103
	v_lshlrev_b32_e32 v77, 16, v121
	v_fmac_f32_e32 v77, v78, v76
	v_and_b32_e32 v76, 0xffff0000, v103
	v_and_b32_e32 v78, 0xffff0000, v121
	v_fmac_f32_e32 v78, v79, v76
	v_cvt_pk_bf16_f32 v86, v87, v86
	v_cvt_pk_bf16_f32 v87, v77, v78
	s_waitcnt vmcnt(5)
	v_and_b32_e32 v76, 0xffff0000, v105
	s_waitcnt vmcnt(4)
	v_and_b32_e32 v77, 0xffff0000, v125
	v_fmac_f32_e32 v77, v83, v76
	v_lshlrev_b32_e32 v76, 16, v105
	v_lshlrev_b32_e32 v78, 16, v125
	v_fmac_f32_e32 v78, v82, v76
	v_and_b32_e32 v76, 0xffff0000, v104
	v_and_b32_e32 v79, 0xffff0000, v124
	v_fmac_f32_e32 v79, v81, v76
	v_lshlrev_b32_e32 v76, 16, v104
	v_lshlrev_b32_e32 v81, 16, v124
	v_fmac_f32_e32 v81, v80, v76
	v_cvt_pk_bf16_f32 v76, v81, v79
	v_cvt_pk_bf16_f32 v77, v78, v77
	v_lshlrev_b32_e32 v78, 16, v106
	s_waitcnt vmcnt(3)
	v_lshlrev_b32_e32 v79, 16, v126
	v_fmac_f32_e32 v79, v72, v78
	v_and_b32_e32 v72, 0xffff0000, v106
	v_and_b32_e32 v78, 0xffff0000, v126
	v_fmac_f32_e32 v78, v73, v72
	v_lshlrev_b32_e32 v72, 16, v107
	v_lshlrev_b32_e32 v73, 16, v127
	v_fmac_f32_e32 v73, v74, v72
	v_and_b32_e32 v72, 0xffff0000, v107
	v_and_b32_e32 v74, 0xffff0000, v127
	v_fmac_f32_e32 v74, v75, v72
	v_cvt_pk_bf16_f32 v78, v79, v78
	v_cvt_pk_bf16_f32 v79, v73, v74
	s_waitcnt vmcnt(2)
	v_and_b32_e32 v72, 0xffff0000, v109
	s_waitcnt vmcnt(1)
	v_and_b32_e32 v73, 0xffff0000, v159
	v_fmac_f32_e32 v73, v71, v72
	v_lshlrev_b32_e32 v71, 16, v109
	v_lshlrev_b32_e32 v72, 16, v159
	v_fmac_f32_e32 v72, v70, v71
	v_and_b32_e32 v70, 0xffff0000, v108
	v_and_b32_e32 v71, 0xffff0000, v158
	v_fmac_f32_e32 v71, v69, v70
	v_lshlrev_b32_e32 v69, 16, v108
	v_lshlrev_b32_e32 v70, 16, v158
	v_fmac_f32_e32 v70, v68, v69
	v_cvt_pk_bf16_f32 v68, v70, v71
	v_lshlrev_b32_e32 v70, 16, v110
	s_waitcnt vmcnt(0)
	v_lshlrev_b32_e32 v71, 16, v160
	v_fmac_f32_e32 v71, v64, v70
	v_and_b32_e32 v64, 0xffff0000, v110
	v_and_b32_e32 v70, 0xffff0000, v160
	v_fmac_f32_e32 v70, v65, v64
	v_lshlrev_b32_e32 v64, 16, v111
	v_lshlrev_b32_e32 v65, 16, v161
	v_fmac_f32_e32 v65, v66, v64
	v_and_b32_e32 v64, 0xffff0000, v111
	v_and_b32_e32 v66, 0xffff0000, v161
	v_fmac_f32_e32 v66, v67, v64
	v_add_u32_e32 v64, 0x80, v144
	v_cvt_pk_bf16_f32 v69, v72, v73
	v_cvt_pk_bf16_f32 v70, v71, v70
	v_cvt_pk_bf16_f32 v71, v65, v66
	v_ashrrev_i32_e32 v65, 31, v64
	v_mad_i64_i32 v[66:67], s[26:27], v64, s49, v[148:149]
	v_cvt_pk_bf16_f32 v93, v97, v162
	global_store_dwordx4 v[122:123], v[68:71], off offset:256 nt
	v_lshlrev_b64 v[64:65], 11, v[64:65]
	global_store_dwordx4 v[112:113], v[92:95], off nt
	v_lshl_add_u64 v[68:69], v[66:67], 0, s[12:13]
	v_cvt_pk_bf16_f32 v85, v88, v89
	global_store_dwordx4 v[122:123], v[76:79], off nt
	v_lshl_add_u64 v[70:71], s[4:5], 0, v[64:65]
	v_lshl_add_u64 v[64:65], v[68:69], 0, v[146:147]
	global_store_dwordx4 v[112:113], v[84:87], off offset:256 nt
	global_load_dwordx4 v[64:67], v[64:65], off
	v_lshl_add_u64 v[80:81], v[70:71], 0, v[146:147]
	global_load_dwordx2 v[82:83], v[80:81], off sc1
	global_load_dwordx2 v[84:85], v[80:81], off offset:8 sc1
	v_lshl_add_u64 v[68:69], v[68:69], 0, v[150:151]
	global_load_dwordx4 v[68:71], v[68:69], off
	s_nop 0
	global_load_dwordx2 v[86:87], v[80:81], off offset:256 sc1
	global_load_dwordx2 v[88:89], v[80:81], off offset:264 sc1
	v_add_u32_e32 v72, 0x90, v144
	v_ashrrev_i32_e32 v73, 31, v72
	v_mad_i64_i32 v[74:75], s[26:27], v72, s49, v[148:149]
	v_lshl_add_u64 v[76:77], v[74:75], 0, s[12:13]
	v_lshlrev_b64 v[72:73], 11, v[72:73]
	v_lshl_add_u64 v[78:79], s[4:5], 0, v[72:73]
	v_lshl_add_u64 v[72:73], v[76:77], 0, v[146:147]
	global_load_dwordx4 v[72:75], v[72:73], off
	v_lshl_add_u64 v[90:91], v[78:79], 0, v[146:147]
	global_load_dwordx2 v[92:93], v[90:91], off sc1
	global_load_dwordx2 v[94:95], v[90:91], off offset:8 sc1
	v_lshl_add_u64 v[76:77], v[76:77], 0, v[150:151]
	global_load_dwordx4 v[76:79], v[76:77], off
	s_nop 0
	global_load_dwordx2 v[96:97], v[90:91], off offset:256 sc1
	global_load_dwordx2 v[98:99], v[90:91], off offset:264 sc1
	s_waitcnt vmcnt(11)
	v_and_b32_e32 v100, 0xffff0000, v65
	s_waitcnt vmcnt(10)
	v_and_b32_e32 v101, 0xffff0000, v83
	v_fmac_f32_e32 v101, v63, v100
	v_lshlrev_b32_e32 v63, 16, v65
	v_lshlrev_b32_e32 v65, 16, v83
	v_fmac_f32_e32 v65, v62, v63
	v_and_b32_e32 v62, 0xffff0000, v64
	v_and_b32_e32 v63, 0xffff0000, v82
	v_fmac_f32_e32 v63, v61, v62
	v_lshlrev_b32_e32 v61, 16, v64
	v_lshlrev_b32_e32 v62, 16, v82
	v_fmac_f32_e32 v62, v60, v61
	v_cvt_pk_bf16_f32 v60, v62, v63
	v_lshlrev_b32_e32 v62, 16, v66
	s_waitcnt vmcnt(9)
	v_lshlrev_b32_e32 v63, 16, v84
	v_fmac_f32_e32 v63, v56, v62
	v_and_b32_e32 v56, 0xffff0000, v66
	v_and_b32_e32 v62, 0xffff0000, v84
	v_fmac_f32_e32 v62, v57, v56
	v_lshlrev_b32_e32 v56, 16, v67
	v_lshlrev_b32_e32 v57, 16, v85
	v_fmac_f32_e32 v57, v58, v56
	v_and_b32_e32 v56, 0xffff0000, v67
	v_and_b32_e32 v58, 0xffff0000, v85
	v_fmac_f32_e32 v58, v59, v56
	v_cvt_pk_bf16_f32 v62, v63, v62
	v_cvt_pk_bf16_f32 v63, v57, v58
	s_waitcnt vmcnt(8)
	v_and_b32_e32 v56, 0xffff0000, v69
	s_waitcnt vmcnt(7)
	v_and_b32_e32 v57, 0xffff0000, v87
	v_fmac_f32_e32 v57, v55, v56
	v_lshlrev_b32_e32 v55, 16, v69
	v_lshlrev_b32_e32 v56, 16, v87
	v_fmac_f32_e32 v56, v54, v55
	v_and_b32_e32 v54, 0xffff0000, v68
	v_and_b32_e32 v55, 0xffff0000, v86
	v_fmac_f32_e32 v55, v53, v54
	v_lshlrev_b32_e32 v53, 16, v68
	v_lshlrev_b32_e32 v54, 16, v86
	v_fmac_f32_e32 v54, v52, v53
	v_cvt_pk_bf16_f32 v52, v54, v55
	v_lshlrev_b32_e32 v54, 16, v70
	s_waitcnt vmcnt(6)
	v_lshlrev_b32_e32 v55, 16, v88
	v_fmac_f32_e32 v55, v44, v54
	v_and_b32_e32 v44, 0xffff0000, v70
	v_and_b32_e32 v54, 0xffff0000, v88
	v_fmac_f32_e32 v54, v45, v44
	v_lshlrev_b32_e32 v44, 16, v71
	v_lshlrev_b32_e32 v45, 16, v89
	v_fmac_f32_e32 v45, v46, v44
	v_and_b32_e32 v44, 0xffff0000, v71
	v_and_b32_e32 v46, 0xffff0000, v89
	v_fmac_f32_e32 v46, v47, v44
	v_cvt_pk_bf16_f32 v54, v55, v54
	v_cvt_pk_bf16_f32 v55, v45, v46
	s_waitcnt vmcnt(5)
	v_and_b32_e32 v44, 0xffff0000, v73
	s_waitcnt vmcnt(4)
	v_and_b32_e32 v45, 0xffff0000, v93
	v_fmac_f32_e32 v45, v51, v44
	v_lshlrev_b32_e32 v44, 16, v73
	v_lshlrev_b32_e32 v46, 16, v93
	v_fmac_f32_e32 v46, v50, v44
	v_and_b32_e32 v44, 0xffff0000, v72
	v_and_b32_e32 v47, 0xffff0000, v92
	v_fmac_f32_e32 v47, v49, v44
	v_lshlrev_b32_e32 v44, 16, v72
	v_lshlrev_b32_e32 v49, 16, v92
	v_fmac_f32_e32 v49, v48, v44
	v_cvt_pk_bf16_f32 v44, v49, v47
	v_cvt_pk_bf16_f32 v45, v46, v45
	v_lshlrev_b32_e32 v46, 16, v74
	s_waitcnt vmcnt(3)
	v_lshlrev_b32_e32 v47, 16, v94
	v_fmac_f32_e32 v47, v40, v46
	v_and_b32_e32 v40, 0xffff0000, v74
	v_and_b32_e32 v46, 0xffff0000, v94
	v_fmac_f32_e32 v46, v41, v40
	v_lshlrev_b32_e32 v40, 16, v75
	v_lshlrev_b32_e32 v41, 16, v95
	v_fmac_f32_e32 v41, v42, v40
	v_and_b32_e32 v40, 0xffff0000, v75
	v_and_b32_e32 v42, 0xffff0000, v95
	v_fmac_f32_e32 v42, v43, v40
	v_cvt_pk_bf16_f32 v46, v47, v46
	v_cvt_pk_bf16_f32 v47, v41, v42
	s_waitcnt vmcnt(2)
	v_and_b32_e32 v40, 0xffff0000, v77
	s_waitcnt vmcnt(1)
	v_and_b32_e32 v41, 0xffff0000, v97
	v_fmac_f32_e32 v41, v39, v40
	v_lshlrev_b32_e32 v39, 16, v77
	v_lshlrev_b32_e32 v40, 16, v97
	v_fmac_f32_e32 v40, v38, v39
	v_and_b32_e32 v38, 0xffff0000, v76
	v_and_b32_e32 v39, 0xffff0000, v96
	v_fmac_f32_e32 v39, v37, v38
	v_lshlrev_b32_e32 v37, 16, v76
	v_lshlrev_b32_e32 v38, 16, v96
	v_fmac_f32_e32 v38, v36, v37
	v_cvt_pk_bf16_f32 v36, v38, v39
	v_lshlrev_b32_e32 v38, 16, v78
	s_waitcnt vmcnt(0)
	v_lshlrev_b32_e32 v39, 16, v98
	v_fmac_f32_e32 v39, v32, v38
	v_and_b32_e32 v32, 0xffff0000, v78
	v_and_b32_e32 v38, 0xffff0000, v98
	v_fmac_f32_e32 v38, v33, v32
	v_lshlrev_b32_e32 v32, 16, v79
	v_lshlrev_b32_e32 v33, 16, v99
	v_fmac_f32_e32 v33, v34, v32
	v_and_b32_e32 v32, 0xffff0000, v79
	v_and_b32_e32 v34, 0xffff0000, v99
	v_fmac_f32_e32 v34, v35, v32
	v_add_u32_e32 v32, 0xa0, v144
	v_cvt_pk_bf16_f32 v37, v40, v41
	v_cvt_pk_bf16_f32 v38, v39, v38
	v_cvt_pk_bf16_f32 v39, v33, v34
	v_ashrrev_i32_e32 v33, 31, v32
	v_mad_i64_i32 v[34:35], s[26:27], v32, s49, v[148:149]
	v_cvt_pk_bf16_f32 v61, v65, v101
	global_store_dwordx4 v[90:91], v[36:39], off offset:256 nt
	v_lshlrev_b64 v[32:33], 11, v[32:33]
	global_store_dwordx4 v[80:81], v[60:63], off nt
	v_lshl_add_u64 v[36:37], v[34:35], 0, s[12:13]
	v_cvt_pk_bf16_f32 v53, v56, v57
	global_store_dwordx4 v[90:91], v[44:47], off nt
	v_lshl_add_u64 v[38:39], s[4:5], 0, v[32:33]
	v_lshl_add_u64 v[32:33], v[36:37], 0, v[146:147]
	global_store_dwordx4 v[80:81], v[52:55], off offset:256 nt
	global_load_dwordx4 v[32:35], v[32:33], off
	v_lshl_add_u64 v[48:49], v[38:39], 0, v[146:147]
	global_load_dwordx2 v[50:51], v[48:49], off sc1
	global_load_dwordx2 v[52:53], v[48:49], off offset:8 sc1
	v_lshl_add_u64 v[36:37], v[36:37], 0, v[150:151]
	global_load_dwordx4 v[36:39], v[36:37], off
	s_nop 0
	global_load_dwordx2 v[54:55], v[48:49], off offset:256 sc1
	global_load_dwordx2 v[56:57], v[48:49], off offset:264 sc1
	v_add_u32_e32 v40, 0xb0, v144
	v_ashrrev_i32_e32 v41, 31, v40
	v_mad_i64_i32 v[42:43], s[26:27], v40, s49, v[148:149]
	v_lshl_add_u64 v[44:45], v[42:43], 0, s[12:13]
	v_lshlrev_b64 v[40:41], 11, v[40:41]
	v_lshl_add_u64 v[46:47], s[4:5], 0, v[40:41]
	v_lshl_add_u64 v[40:41], v[44:45], 0, v[146:147]
	global_load_dwordx4 v[40:43], v[40:41], off
	v_lshl_add_u64 v[58:59], v[46:47], 0, v[146:147]
	global_load_dwordx2 v[60:61], v[58:59], off sc1
	global_load_dwordx2 v[62:63], v[58:59], off offset:8 sc1
	v_lshl_add_u64 v[44:45], v[44:45], 0, v[150:151]
	global_load_dwordx4 v[44:47], v[44:45], off
	s_nop 0
	global_load_dwordx2 v[64:65], v[58:59], off offset:256 sc1
	global_load_dwordx2 v[66:67], v[58:59], off offset:264 sc1
	s_waitcnt vmcnt(11)
	v_and_b32_e32 v68, 0xffff0000, v33
	s_waitcnt vmcnt(10)
	v_and_b32_e32 v69, 0xffff0000, v51
	v_fmac_f32_e32 v69, v31, v68
	v_lshlrev_b32_e32 v31, 16, v33
	v_lshlrev_b32_e32 v33, 16, v51
	v_fmac_f32_e32 v33, v30, v31
	v_and_b32_e32 v30, 0xffff0000, v32
	v_and_b32_e32 v31, 0xffff0000, v50
	v_fmac_f32_e32 v31, v29, v30
	v_lshlrev_b32_e32 v29, 16, v32
	v_lshlrev_b32_e32 v30, 16, v50
	v_fmac_f32_e32 v30, v28, v29
	v_cvt_pk_bf16_f32 v28, v30, v31
	v_lshlrev_b32_e32 v30, 16, v34
	s_waitcnt vmcnt(9)
	v_lshlrev_b32_e32 v31, 16, v52
	v_fmac_f32_e32 v31, v24, v30
	v_and_b32_e32 v24, 0xffff0000, v34
	v_and_b32_e32 v30, 0xffff0000, v52
	v_fmac_f32_e32 v30, v25, v24
	v_lshlrev_b32_e32 v24, 16, v35
	v_lshlrev_b32_e32 v25, 16, v53
	v_fmac_f32_e32 v25, v26, v24
	v_and_b32_e32 v24, 0xffff0000, v35
	v_and_b32_e32 v26, 0xffff0000, v53
	v_fmac_f32_e32 v26, v27, v24
	v_cvt_pk_bf16_f32 v30, v31, v30
	v_cvt_pk_bf16_f32 v31, v25, v26
	s_waitcnt vmcnt(8)
	v_and_b32_e32 v24, 0xffff0000, v37
	s_waitcnt vmcnt(7)
	v_and_b32_e32 v25, 0xffff0000, v55
	v_fmac_f32_e32 v25, v23, v24
	v_lshlrev_b32_e32 v23, 16, v37
	v_lshlrev_b32_e32 v24, 16, v55
	v_fmac_f32_e32 v24, v22, v23
	v_and_b32_e32 v22, 0xffff0000, v36
	v_and_b32_e32 v23, 0xffff0000, v54
	v_fmac_f32_e32 v23, v21, v22
	v_lshlrev_b32_e32 v21, 16, v36
	v_lshlrev_b32_e32 v22, 16, v54
	v_fmac_f32_e32 v22, v20, v21
	v_cvt_pk_bf16_f32 v20, v22, v23
	v_lshlrev_b32_e32 v22, 16, v38
	s_waitcnt vmcnt(6)
	v_lshlrev_b32_e32 v23, 16, v56
	v_fmac_f32_e32 v23, v12, v22
	v_and_b32_e32 v12, 0xffff0000, v38
	v_and_b32_e32 v22, 0xffff0000, v56
	v_fmac_f32_e32 v22, v13, v12
	v_lshlrev_b32_e32 v12, 16, v39
	v_lshlrev_b32_e32 v13, 16, v57
	v_fmac_f32_e32 v13, v14, v12
	v_and_b32_e32 v12, 0xffff0000, v39
	v_and_b32_e32 v14, 0xffff0000, v57
	v_fmac_f32_e32 v14, v15, v12
	v_cvt_pk_bf16_f32 v22, v23, v22
	v_cvt_pk_bf16_f32 v23, v13, v14
	s_waitcnt vmcnt(5)
	v_and_b32_e32 v12, 0xffff0000, v41
	s_waitcnt vmcnt(4)
	v_and_b32_e32 v13, 0xffff0000, v61
	v_fmac_f32_e32 v13, v19, v12
	v_lshlrev_b32_e32 v12, 16, v41
	v_lshlrev_b32_e32 v14, 16, v61
	v_fmac_f32_e32 v14, v18, v12
	v_and_b32_e32 v12, 0xffff0000, v40
	v_and_b32_e32 v15, 0xffff0000, v60
	v_fmac_f32_e32 v15, v17, v12
	v_lshlrev_b32_e32 v12, 16, v40
	v_lshlrev_b32_e32 v17, 16, v60
	v_fmac_f32_e32 v17, v16, v12
	v_cvt_pk_bf16_f32 v12, v17, v15
	v_cvt_pk_bf16_f32 v13, v14, v13
	v_lshlrev_b32_e32 v14, 16, v42
	s_waitcnt vmcnt(3)
	v_lshlrev_b32_e32 v15, 16, v62
	v_fmac_f32_e32 v15, v8, v14
	v_and_b32_e32 v8, 0xffff0000, v42
	v_and_b32_e32 v14, 0xffff0000, v62
	v_fmac_f32_e32 v14, v9, v8
	v_lshlrev_b32_e32 v8, 16, v43
	v_lshlrev_b32_e32 v9, 16, v63
	v_fmac_f32_e32 v9, v10, v8
	v_and_b32_e32 v8, 0xffff0000, v43
	v_and_b32_e32 v10, 0xffff0000, v63
	v_fmac_f32_e32 v10, v11, v8
	v_cvt_pk_bf16_f32 v14, v15, v14
	v_cvt_pk_bf16_f32 v15, v9, v10
	s_waitcnt vmcnt(2)
	v_lshlrev_b32_e32 v8, 16, v44
	s_waitcnt vmcnt(1)
	v_lshlrev_b32_e32 v9, 16, v64
	v_fmac_f32_e32 v9, v4, v8
	v_and_b32_e32 v4, 0xffff0000, v44
	v_and_b32_e32 v8, 0xffff0000, v64
	v_fmac_f32_e32 v8, v5, v4
	v_cvt_pk_bf16_f32 v4, v9, v8
	v_lshlrev_b32_e32 v5, 16, v45
	v_lshlrev_b32_e32 v8, 16, v65
	v_fmac_f32_e32 v8, v6, v5
	v_and_b32_e32 v5, 0xffff0000, v45
	v_and_b32_e32 v6, 0xffff0000, v65
	v_fmac_f32_e32 v6, v7, v5
	v_cvt_pk_bf16_f32 v5, v8, v6
	v_lshlrev_b32_e32 v6, 16, v46
	s_waitcnt vmcnt(0)
	v_lshlrev_b32_e32 v7, 16, v66
	v_fmac_f32_e32 v7, v0, v6
	v_and_b32_e32 v0, 0xffff0000, v46
	v_and_b32_e32 v6, 0xffff0000, v66
	v_fmac_f32_e32 v6, v1, v0
	v_lshlrev_b32_e32 v0, 16, v47
	v_lshlrev_b32_e32 v1, 16, v67
	v_fmac_f32_e32 v1, v2, v0
	v_and_b32_e32 v0, 0xffff0000, v47
	v_and_b32_e32 v2, 0xffff0000, v67
	v_fmac_f32_e32 v2, v3, v0
	v_cvt_pk_bf16_f32 v29, v33, v69
	v_cvt_pk_bf16_f32 v21, v24, v25
	v_cvt_pk_bf16_f32 v6, v7, v6
	v_cvt_pk_bf16_f32 v7, v1, v2
	global_store_dwordx4 v[48:49], v[28:31], off nt
	global_store_dwordx4 v[48:49], v[20:23], off offset:256 nt
	global_store_dwordx4 v[58:59], v[12:15], off nt
	global_store_dwordx4 v[58:59], v[4:7], off offset:256 nt
	s_cbranch_vccnz .LBB0_1087
	s_andn2_b64 vcc, exec, s[6:7]
	s_cbranch_vccnz .LBB0_1086
	s_barrier
	s_branch .LBB0_1086

.LBB0_1741:
	s_cmp_gt_u32 s2, 16
	s_cbranch_scc0 .LBB0_1745
	s_and_saveexec_b64 s[0:1], s[16:17]
	s_cbranch_execz .LBB0_1744
	v_mul_f32_e32 v128, 0xbfb8aa3b, v124
	v_mul_f32_e32 v129, 0xbfb8aa3b, v125
	v_mul_f32_e32 v130, 0xbfb8aa3b, v126
	v_mul_f32_e32 v131, 0xbfb8aa3b, v127
	v_exp_f32_e32 v128, v128
	v_exp_f32_e32 v129, v129
	v_exp_f32_e32 v130, v130
	v_exp_f32_e32 v131, v131
	v_add_f32_e32 v128, 1.0, v128
	v_add_f32_e32 v129, 1.0, v129
	v_add_f32_e32 v130, 1.0, v130
	v_add_f32_e32 v131, 1.0, v131
	v_rcp_f32_e32 v128, v128
	v_rcp_f32_e32 v129, v129
	v_rcp_f32_e32 v130, v130
	v_rcp_f32_e32 v131, v131
	v_mad_i64_i32 v[136:137], s[6:7], v214, s58, v[184:185]
	v_or_b32_e32 v132, 16, v214
	global_store_dwordx4 v[136:137], v[128:131], off nt
	v_mad_i64_i32 v[138:139], s[6:7], v132, s58, v[184:185]
	s_nop 0
	v_mul_f32_e32 v128, 0xbfb8aa3b, v116
	v_mul_f32_e32 v129, 0xbfb8aa3b, v117
	v_mul_f32_e32 v130, 0xbfb8aa3b, v118
	v_mul_f32_e32 v131, 0xbfb8aa3b, v119
	v_exp_f32_e32 v128, v128
	v_exp_f32_e32 v129, v129
	v_exp_f32_e32 v130, v130
	v_exp_f32_e32 v131, v131
	v_add_f32_e32 v128, 1.0, v128
	v_add_f32_e32 v129, 1.0, v129
	v_add_f32_e32 v130, 1.0, v130
	v_add_f32_e32 v131, 1.0, v131
	v_rcp_f32_e32 v128, v128
	v_rcp_f32_e32 v129, v129
	v_rcp_f32_e32 v130, v130
	v_rcp_f32_e32 v131, v131
	v_mul_f32_e32 v132, 0xbfb8aa3b, v108
	v_mul_f32_e32 v133, 0xbfb8aa3b, v109
	v_exp_f32_e32 v132, v132
	global_store_dwordx4 v[138:139], v[128:131], off nt
	v_exp_f32_e32 v133, v133
	v_add_u32_e32 v144, 0x90, v214
	v_mul_f32_e32 v130, 0xbfb8aa3b, v110
	v_mul_f32_e32 v131, 0xbfb8aa3b, v111
	v_exp_f32_e32 v130, v130
	v_exp_f32_e32 v131, v131
	v_add_f32_e32 v128, 1.0, v132
	v_add_f32_e32 v129, 1.0, v133
	v_add_f32_e32 v130, 1.0, v130
	v_add_f32_e32 v131, 1.0, v131
	v_rcp_f32_e32 v128, v128
	v_rcp_f32_e32 v129, v129
	v_rcp_f32_e32 v130, v130
	v_rcp_f32_e32 v131, v131
	v_or_b32_e32 v132, 32, v214
	v_mad_i64_i32 v[140:141], s[6:7], v132, s58, v[184:185]
	global_store_dwordx4 v[140:141], v[128:131], off nt
	v_or_b32_e32 v132, 48, v214
	v_mad_i64_i32 v[142:143], s[6:7], v132, s58, v[184:185]
	v_mul_f32_e32 v128, 0xbfb8aa3b, v100
	v_mul_f32_e32 v129, 0xbfb8aa3b, v101
	v_mul_f32_e32 v130, 0xbfb8aa3b, v102
	v_mul_f32_e32 v131, 0xbfb8aa3b, v103
	v_exp_f32_e32 v128, v128
	v_exp_f32_e32 v129, v129
	v_exp_f32_e32 v130, v130
	v_exp_f32_e32 v131, v131
	v_add_f32_e32 v128, 1.0, v128
	v_add_f32_e32 v129, 1.0, v129
	v_add_f32_e32 v130, 1.0, v130
	v_add_f32_e32 v131, 1.0, v131
	v_rcp_f32_e32 v128, v128
	v_rcp_f32_e32 v129, v129
	v_rcp_f32_e32 v130, v130
	v_rcp_f32_e32 v131, v131
	v_mul_f32_e32 v132, 0xbfb8aa3b, v92
	v_exp_f32_e32 v132, v132
	v_mul_f32_e32 v133, 0xbfb8aa3b, v93
	v_exp_f32_e32 v133, v133
	global_store_dwordx4 v[142:143], v[128:131], off nt
	v_mul_f32_e32 v145, 0xbfb8aa3b, v77
	v_exp_f32_e32 v145, v145
	v_mul_f32_e32 v129, 0xbfb8aa3b, v94
	v_add_f32_e32 v128, 1.0, v132
	v_exp_f32_e32 v129, v129
	v_mul_f32_e32 v131, 0xbfb8aa3b, v95
	v_rcp_f32_e32 v130, v128
	v_add_f32_e32 v128, 1.0, v133
	v_exp_f32_e32 v133, v131
	v_rcp_f32_e32 v131, v128
	v_add_f32_e32 v128, 1.0, v129
	v_rcp_f32_e32 v132, v128
	v_add_f32_e32 v128, 1.0, v133
	v_rcp_f32_e32 v133, v128
	v_add_u32_e32 v128, 0x80, v214
	v_mad_i64_i32 v[128:129], s[6:7], v128, s58, v[184:185]
	global_store_dwordx4 v[128:129], v[130:133], off nt
	v_mul_f32_e32 v146, 0xbfb8aa3b, v66
	v_mul_f32_e32 v147, 0xbfb8aa3b, v67
	v_mul_f32_e32 v130, 0xbfb8aa3b, v84
	v_exp_f32_e32 v130, v130
	v_mul_f32_e32 v131, 0xbfb8aa3b, v85
	v_exp_f32_e32 v131, v131
	v_mul_f32_e32 v133, 0xbfb8aa3b, v87
	v_add_f32_e32 v130, 1.0, v130
	v_rcp_f32_e32 v132, v130
	v_add_f32_e32 v130, 1.0, v131
	v_mul_f32_e32 v131, 0xbfb8aa3b, v86
	v_exp_f32_e32 v131, v131
	v_exp_f32_e32 v135, v133
	v_rcp_f32_e32 v133, v130
	v_exp_f32_e32 v146, v146
	v_add_f32_e32 v130, 1.0, v131
	v_rcp_f32_e32 v134, v130
	v_add_f32_e32 v130, 1.0, v135
	v_rcp_f32_e32 v135, v130
	v_mad_i64_i32 v[130:131], s[6:7], v144, s58, v[184:185]
	v_mul_f32_e32 v144, 0xbfb8aa3b, v76
	global_store_dwordx4 v[130:131], v[132:135], off nt
	v_exp_f32_e32 v144, v144
	v_exp_f32_e32 v147, v147
	v_mul_f32_e32 v134, 0xbfb8aa3b, v78
	v_mul_f32_e32 v135, 0xbfb8aa3b, v79
	v_exp_f32_e32 v134, v134
	v_exp_f32_e32 v135, v135
	v_add_f32_e32 v132, 1.0, v144
	v_add_f32_e32 v133, 1.0, v145
	v_add_f32_e32 v134, 1.0, v134
	v_add_f32_e32 v135, 1.0, v135
	v_rcp_f32_e32 v132, v132
	v_rcp_f32_e32 v133, v133
	v_rcp_f32_e32 v134, v134
	v_rcp_f32_e32 v135, v135
	v_add_u32_e32 v144, 0xa0, v214
	v_mad_i64_i32 v[148:149], s[6:7], v144, s58, v[184:185]
	global_store_dwordx4 v[148:149], v[132:135], off nt
	v_add_u32_e32 v144, 0xb0, v214
	v_mad_i64_i32 v[150:151], s[6:7], v144, s58, v[184:185]
	v_mul_f32_e32 v132, 0xbfb8aa3b, v68
	v_mul_f32_e32 v133, 0xbfb8aa3b, v69
	v_mul_f32_e32 v134, 0xbfb8aa3b, v70
	v_mul_f32_e32 v135, 0xbfb8aa3b, v71
	v_exp_f32_e32 v132, v132
	v_exp_f32_e32 v133, v133
	v_exp_f32_e32 v134, v134
	v_exp_f32_e32 v135, v135
	v_add_f32_e32 v132, 1.0, v132
	v_add_f32_e32 v133, 1.0, v133
	v_add_f32_e32 v134, 1.0, v134
	v_add_f32_e32 v135, 1.0, v135
	v_rcp_f32_e32 v132, v132
	v_rcp_f32_e32 v133, v133
	v_rcp_f32_e32 v134, v134
	v_rcp_f32_e32 v135, v135
	v_mul_f32_e32 v144, 0xbfb8aa3b, v120
	v_mul_f32_e32 v145, 0xbfb8aa3b, v121
	v_exp_f32_e32 v144, v144
	global_store_dwordx4 v[150:151], v[132:135], off nt
	v_exp_f32_e32 v145, v145
	v_add_f32_e32 v146, 1.0, v146
	v_mul_f32_e32 v134, 0xbfb8aa3b, v122
	v_mul_f32_e32 v135, 0xbfb8aa3b, v123
	v_exp_f32_e32 v134, v134
	v_exp_f32_e32 v135, v135
	v_add_f32_e32 v132, 1.0, v144
	v_add_f32_e32 v133, 1.0, v145
	v_add_f32_e32 v134, 1.0, v134
	v_add_f32_e32 v135, 1.0, v135
	v_rcp_f32_e32 v132, v132
	v_rcp_f32_e32 v133, v133
	v_rcp_f32_e32 v134, v134
	v_rcp_f32_e32 v135, v135
	v_mul_f32_e32 v144, 0xbfb8aa3b, v112
	v_mul_f32_e32 v145, 0xbfb8aa3b, v113
	v_exp_f32_e32 v144, v144
	global_store_dwordx4 v[136:137], v[132:135], off offset:16 nt
	v_exp_f32_e32 v145, v145
	v_mul_f32_e32 v136, 0xbfb8aa3b, v104
	v_mul_f32_e32 v134, 0xbfb8aa3b, v114
	v_mul_f32_e32 v135, 0xbfb8aa3b, v115
	v_exp_f32_e32 v134, v134
	v_exp_f32_e32 v135, v135
	v_add_f32_e32 v132, 1.0, v144
	v_add_f32_e32 v133, 1.0, v145
	v_add_f32_e32 v134, 1.0, v134
	v_add_f32_e32 v135, 1.0, v135
	v_rcp_f32_e32 v132, v132
	v_rcp_f32_e32 v133, v133
	v_rcp_f32_e32 v134, v134
	v_rcp_f32_e32 v135, v135
	v_mul_f32_e32 v137, 0xbfb8aa3b, v105
	v_exp_f32_e32 v136, v136
	v_exp_f32_e32 v137, v137
	global_store_dwordx4 v[138:139], v[132:135], off offset:16 nt
	v_mul_f32_e32 v138, 0xbfb8aa3b, v82
	v_mul_f32_e32 v139, 0xbfb8aa3b, v83
	v_mul_f32_e32 v134, 0xbfb8aa3b, v106
	v_mul_f32_e32 v135, 0xbfb8aa3b, v107
	v_exp_f32_e32 v134, v134
	v_exp_f32_e32 v135, v135
	v_add_f32_e32 v132, 1.0, v136
	v_add_f32_e32 v133, 1.0, v137
	v_add_f32_e32 v134, 1.0, v134
	v_add_f32_e32 v135, 1.0, v135
	v_rcp_f32_e32 v132, v132
	v_rcp_f32_e32 v133, v133
	v_rcp_f32_e32 v134, v134
	v_rcp_f32_e32 v135, v135
	v_mul_f32_e32 v136, 0xbfb8aa3b, v96
	v_mul_f32_e32 v137, 0xbfb8aa3b, v97
	v_exp_f32_e32 v136, v136
	global_store_dwordx4 v[140:141], v[132:135], off offset:16 nt
	v_exp_f32_e32 v137, v137
	v_exp_f32_e32 v138, v138
	v_mul_f32_e32 v134, 0xbfb8aa3b, v98
	v_mul_f32_e32 v135, 0xbfb8aa3b, v99
	v_exp_f32_e32 v134, v134
	v_exp_f32_e32 v135, v135
	v_add_f32_e32 v132, 1.0, v136
	v_add_f32_e32 v133, 1.0, v137
	v_add_f32_e32 v134, 1.0, v134
	v_add_f32_e32 v135, 1.0, v135
	v_rcp_f32_e32 v132, v132
	v_rcp_f32_e32 v133, v133
	v_rcp_f32_e32 v134, v134
	v_rcp_f32_e32 v135, v135
	v_mul_f32_e32 v136, 0xbfb8aa3b, v88
	v_mul_f32_e32 v137, 0xbfb8aa3b, v89
	v_exp_f32_e32 v136, v136
	v_exp_f32_e32 v137, v137
	global_store_dwordx4 v[142:143], v[132:135], off offset:16 nt
	v_exp_f32_e32 v139, v139
	v_mul_f32_e32 v140, 0xbfb8aa3b, v72
	v_mul_f32_e32 v134, 0xbfb8aa3b, v90
	v_mul_f32_e32 v135, 0xbfb8aa3b, v91
	v_add_f32_e32 v132, 1.0, v136
	v_add_f32_e32 v133, 1.0, v137
	v_exp_f32_e32 v134, v134
	v_exp_f32_e32 v135, v135
	v_mul_f32_e32 v136, 0xbfb8aa3b, v80
	v_mul_f32_e32 v137, 0xbfb8aa3b, v81
	v_exp_f32_e32 v136, v136
	v_exp_f32_e32 v137, v137
	v_mul_f32_e32 v141, 0xbfb8aa3b, v73
	v_mul_f32_e32 v142, 0xbfb8aa3b, v74
	v_mul_f32_e32 v143, 0xbfb8aa3b, v75
	v_exp_f32_e32 v140, v140
	v_exp_f32_e32 v141, v141
	v_exp_f32_e32 v142, v142
	v_exp_f32_e32 v143, v143
	v_mul_f32_e32 v144, 0xbfb8aa3b, v64
	v_mul_f32_e32 v145, 0xbfb8aa3b, v65
	v_exp_f32_e32 v144, v144
	v_exp_f32_e32 v145, v145
	v_add_f32_e32 v134, 1.0, v134
	v_add_f32_e32 v135, 1.0, v135
	v_rcp_f32_e32 v132, v132
	v_rcp_f32_e32 v133, v133
	v_rcp_f32_e32 v134, v134
	v_rcp_f32_e32 v135, v135
	v_add_f32_e32 v136, 1.0, v136
	v_add_f32_e32 v137, 1.0, v137
	v_add_f32_e32 v138, 1.0, v138
	v_add_f32_e32 v139, 1.0, v139
	v_rcp_f32_e32 v136, v136
	v_rcp_f32_e32 v137, v137
	v_rcp_f32_e32 v138, v138
	v_rcp_f32_e32 v139, v139
	v_add_f32_e32 v140, 1.0, v140
	v_add_f32_e32 v141, 1.0, v141
	v_add_f32_e32 v142, 1.0, v142
	v_add_f32_e32 v143, 1.0, v143
	v_rcp_f32_e32 v140, v140
	v_rcp_f32_e32 v141, v141
	v_rcp_f32_e32 v142, v142
	v_rcp_f32_e32 v143, v143
	v_add_f32_e32 v144, 1.0, v144
	v_add_f32_e32 v145, 1.0, v145
	v_add_f32_e32 v147, 1.0, v147
	v_rcp_f32_e32 v144, v144
	v_rcp_f32_e32 v145, v145
	v_rcp_f32_e32 v146, v146
	v_rcp_f32_e32 v147, v147
	global_store_dwordx4 v[128:129], v[132:135], off offset:16 nt
	global_store_dwordx4 v[130:131], v[136:139], off offset:16 nt
	global_store_dwordx4 v[148:149], v[140:143], off offset:16 nt
	global_store_dwordx4 v[150:151], v[144:147], off offset:16 nt

.LBB0_1754:
	v_cvt_pk_bf16_f32 v128, v128, v129
	v_cvt_pk_bf16_f32 v129, v130, v131
	v_cvt_pk_bf16_f32 v130, v132, v133
	v_mov_b64_e32 v[132:133], s[10:11]
	v_lshl_add_u32 v176, s2, 8, v201
	v_mad_i64_i32 v[132:133], s[6:7], v214, s59, v[132:133]
	v_cvt_pk_bf16_f32 v131, v134, v135
	v_lshl_add_u64 v[136:137], v[176:177], 1, v[132:133]
	s_and_b64 vcc, exec, s[0:1]
	s_mov_b64 s[6:7], -1
	global_store_dwordx4 v[136:137], v[128:131], off nt
	s_cbranch_vccnz .LBB0_1758
	s_nop 0
	v_mul_f32_e32 v128, 0xbfb8aa3b, v116
	v_mul_f32_e32 v129, 0xbfb8aa3b, v117
	v_mul_f32_e32 v130, 0xbfb8aa3b, v118
	v_mul_f32_e32 v131, 0xbfb8aa3b, v119
	v_exp_f32_e32 v128, v128
	v_exp_f32_e32 v129, v129
	v_exp_f32_e32 v130, v130
	v_exp_f32_e32 v131, v131
	v_add_f32_e32 v128, 1.0, v128
	v_add_f32_e32 v129, 1.0, v129
	v_add_f32_e32 v130, 1.0, v130
	v_add_f32_e32 v131, 1.0, v131
	v_rcp_f32_e32 v128, v128
	v_rcp_f32_e32 v129, v129
	v_rcp_f32_e32 v130, v130
	v_rcp_f32_e32 v131, v131
	s_cbranch_execz .LBB0_1759

.LBB0_1762:
	v_cvt_pk_bf16_f32 v128, v128, v129
	v_cvt_pk_bf16_f32 v129, v130, v131
	v_cvt_pk_bf16_f32 v130, v132, v133
	v_cvt_pk_bf16_f32 v131, v134, v135
	v_or_b32_e32 v134, 16, v214
	v_mov_b64_e32 v[132:133], s[10:11]
	v_mad_i64_i32 v[132:133], s[6:7], v134, s59, v[132:133]
	v_lshl_add_u64 v[138:139], v[176:177], 1, v[132:133]
	s_and_b64 vcc, exec, s[0:1]
	s_mov_b64 s[6:7], -1
	global_store_dwordx4 v[138:139], v[128:131], off nt
	s_cbranch_vccnz .LBB0_1766
	s_nop 0
	v_mul_f32_e32 v128, 0xbfb8aa3b, v108
	v_mul_f32_e32 v129, 0xbfb8aa3b, v109
	v_mul_f32_e32 v130, 0xbfb8aa3b, v110
	v_mul_f32_e32 v131, 0xbfb8aa3b, v111
	v_exp_f32_e32 v128, v128
	v_exp_f32_e32 v129, v129
	v_exp_f32_e32 v130, v130
	v_exp_f32_e32 v131, v131
	v_add_f32_e32 v128, 1.0, v128
	v_add_f32_e32 v129, 1.0, v129
	v_add_f32_e32 v130, 1.0, v130
	v_add_f32_e32 v131, 1.0, v131
	v_rcp_f32_e32 v128, v128
	v_rcp_f32_e32 v129, v129
	v_rcp_f32_e32 v130, v130
	v_rcp_f32_e32 v131, v131
	s_cbranch_execz .LBB0_1767

.LBB0_1770:
	v_cvt_pk_bf16_f32 v128, v128, v129
	v_cvt_pk_bf16_f32 v129, v130, v131
	v_cvt_pk_bf16_f32 v130, v132, v133
	v_cvt_pk_bf16_f32 v131, v134, v135
	v_or_b32_e32 v134, 32, v214
	v_mov_b64_e32 v[132:133], s[10:11]
	v_mad_i64_i32 v[132:133], s[6:7], v134, s59, v[132:133]
	v_lshl_add_u64 v[140:141], v[176:177], 1, v[132:133]
	s_and_b64 vcc, exec, s[0:1]
	s_mov_b64 s[6:7], -1
	global_store_dwordx4 v[140:141], v[128:131], off nt
	s_cbranch_vccnz .LBB0_1774
	s_nop 0
	v_mul_f32_e32 v128, 0xbfb8aa3b, v100
	v_mul_f32_e32 v129, 0xbfb8aa3b, v101
	v_mul_f32_e32 v130, 0xbfb8aa3b, v102
	v_mul_f32_e32 v131, 0xbfb8aa3b, v103
	v_exp_f32_e32 v128, v128
	v_exp_f32_e32 v129, v129
	v_exp_f32_e32 v130, v130
	v_exp_f32_e32 v131, v131
	v_add_f32_e32 v128, 1.0, v128
	v_add_f32_e32 v129, 1.0, v129
	v_add_f32_e32 v130, 1.0, v130
	v_add_f32_e32 v131, 1.0, v131
	v_rcp_f32_e32 v128, v128
	v_rcp_f32_e32 v129, v129
	v_rcp_f32_e32 v130, v130
	v_rcp_f32_e32 v131, v131
	s_cbranch_execz .LBB0_1775

.LBB0_1778:
	v_cvt_pk_bf16_f32 v128, v128, v129
	v_cvt_pk_bf16_f32 v129, v130, v131
	v_cvt_pk_bf16_f32 v130, v132, v133
	v_cvt_pk_bf16_f32 v131, v134, v135
	v_or_b32_e32 v134, 48, v214
	v_mov_b64_e32 v[132:133], s[10:11]
	v_mad_i64_i32 v[132:133], s[6:7], v134, s59, v[132:133]
	v_lshl_add_u64 v[142:143], v[176:177], 1, v[132:133]
	s_and_b64 vcc, exec, s[0:1]
	s_mov_b64 s[6:7], -1
	global_store_dwordx4 v[142:143], v[128:131], off nt
	s_cbranch_vccnz .LBB0_1782
	s_nop 0
	v_mul_f32_e32 v128, 0xbfb8aa3b, v92
	v_mul_f32_e32 v129, 0xbfb8aa3b, v93
	v_mul_f32_e32 v130, 0xbfb8aa3b, v94
	v_mul_f32_e32 v131, 0xbfb8aa3b, v95
	v_exp_f32_e32 v128, v128
	v_exp_f32_e32 v129, v129
	v_exp_f32_e32 v130, v130
	v_exp_f32_e32 v131, v131
	v_add_f32_e32 v128, 1.0, v128
	v_add_f32_e32 v129, 1.0, v129
	v_add_f32_e32 v130, 1.0, v130
	v_add_f32_e32 v131, 1.0, v131
	v_rcp_f32_e32 v128, v128
	v_rcp_f32_e32 v129, v129
	v_rcp_f32_e32 v130, v130
	v_rcp_f32_e32 v131, v131
	s_cbranch_execz .LBB0_1783

.LBB0_1786:
	v_cvt_pk_bf16_f32 v128, v128, v129
	v_cvt_pk_bf16_f32 v129, v130, v131
	v_add_u32_e32 v144, 0x80, v214
	v_cvt_pk_bf16_f32 v130, v132, v133
	v_mov_b64_e32 v[132:133], s[10:11]
	v_mad_i64_i32 v[132:133], s[6:7], v144, s59, v[132:133]
	v_cvt_pk_bf16_f32 v131, v134, v135
	v_lshl_add_u64 v[144:145], v[176:177], 1, v[132:133]
	s_and_b64 vcc, exec, s[0:1]
	s_mov_b64 s[6:7], -1
	global_store_dwordx4 v[144:145], v[128:131], off nt
	s_cbranch_vccnz .LBB0_1790
	s_nop 0
	v_mul_f32_e32 v128, 0xbfb8aa3b, v84
	v_mul_f32_e32 v129, 0xbfb8aa3b, v85
	v_mul_f32_e32 v130, 0xbfb8aa3b, v86
	v_mul_f32_e32 v131, 0xbfb8aa3b, v87
	v_exp_f32_e32 v128, v128
	v_exp_f32_e32 v129, v129
	v_exp_f32_e32 v130, v130
	v_exp_f32_e32 v131, v131
	v_add_f32_e32 v128, 1.0, v128
	v_add_f32_e32 v129, 1.0, v129
	v_add_f32_e32 v130, 1.0, v130
	v_add_f32_e32 v131, 1.0, v131
	v_rcp_f32_e32 v128, v128
	v_rcp_f32_e32 v129, v129
	v_rcp_f32_e32 v130, v130
	v_rcp_f32_e32 v131, v131
	s_cbranch_execz .LBB0_1791

.LBB0_1794:
	v_cvt_pk_bf16_f32 v128, v128, v129
	v_cvt_pk_bf16_f32 v129, v130, v131
	v_cvt_pk_bf16_f32 v130, v132, v133
	v_cvt_pk_bf16_f32 v131, v134, v135
	v_add_u32_e32 v134, 0x90, v214
	v_mov_b64_e32 v[132:133], s[10:11]
	v_mad_i64_i32 v[132:133], s[6:7], v134, s59, v[132:133]
	v_lshl_add_u64 v[146:147], v[176:177], 1, v[132:133]
	s_and_b64 vcc, exec, s[0:1]
	s_mov_b64 s[6:7], -1
	global_store_dwordx4 v[146:147], v[128:131], off nt
	s_cbranch_vccnz .LBB0_1798
	s_nop 0
	v_mul_f32_e32 v128, 0xbfb8aa3b, v76
	v_mul_f32_e32 v129, 0xbfb8aa3b, v77
	v_mul_f32_e32 v130, 0xbfb8aa3b, v78
	v_mul_f32_e32 v131, 0xbfb8aa3b, v79
	v_exp_f32_e32 v128, v128
	v_exp_f32_e32 v129, v129
	v_exp_f32_e32 v130, v130
	v_exp_f32_e32 v131, v131
	v_add_f32_e32 v128, 1.0, v128
	v_add_f32_e32 v129, 1.0, v129
	v_add_f32_e32 v130, 1.0, v130
	v_add_f32_e32 v131, 1.0, v131
	v_rcp_f32_e32 v128, v128
	v_rcp_f32_e32 v129, v129
	v_rcp_f32_e32 v130, v130
	v_rcp_f32_e32 v131, v131
	s_cbranch_execz .LBB0_1799

.LBB0_1802:
	v_cvt_pk_bf16_f32 v128, v128, v129
	v_cvt_pk_bf16_f32 v129, v130, v131
	v_cvt_pk_bf16_f32 v130, v132, v133
	v_cvt_pk_bf16_f32 v131, v134, v135
	v_add_u32_e32 v134, 0xa0, v214
	v_mov_b64_e32 v[132:133], s[10:11]
	v_mad_i64_i32 v[132:133], s[6:7], v134, s59, v[132:133]
	v_lshl_add_u64 v[148:149], v[176:177], 1, v[132:133]
	s_and_b64 vcc, exec, s[0:1]
	s_mov_b64 s[6:7], -1
	global_store_dwordx4 v[148:149], v[128:131], off nt
	s_cbranch_vccnz .LBB0_1806
	s_nop 0
	v_mul_f32_e32 v128, 0xbfb8aa3b, v68
	v_mul_f32_e32 v129, 0xbfb8aa3b, v69
	v_mul_f32_e32 v130, 0xbfb8aa3b, v70
	v_mul_f32_e32 v131, 0xbfb8aa3b, v71
	v_exp_f32_e32 v128, v128
	v_exp_f32_e32 v129, v129
	v_exp_f32_e32 v130, v130
	v_exp_f32_e32 v131, v131
	v_add_f32_e32 v128, 1.0, v128
	v_add_f32_e32 v129, 1.0, v129
	v_add_f32_e32 v130, 1.0, v130
	v_add_f32_e32 v131, 1.0, v131
	v_rcp_f32_e32 v128, v128
	v_rcp_f32_e32 v129, v129
	v_rcp_f32_e32 v130, v130
	v_rcp_f32_e32 v131, v131
	s_cbranch_execz .LBB0_1807

.LBB0_1810:
	v_cvt_pk_bf16_f32 v128, v128, v129
	v_cvt_pk_bf16_f32 v129, v130, v131
	v_cvt_pk_bf16_f32 v130, v132, v133
	v_cvt_pk_bf16_f32 v131, v134, v135
	v_add_u32_e32 v134, 0xb0, v214
	v_mov_b64_e32 v[132:133], s[10:11]
	v_mad_i64_i32 v[132:133], s[6:7], v134, s59, v[132:133]
	v_lshl_add_u64 v[150:151], v[176:177], 1, v[132:133]
	s_and_b64 vcc, exec, s[0:1]
	s_mov_b64 s[6:7], -1
	global_store_dwordx4 v[150:151], v[128:131], off nt
	s_cbranch_vccnz .LBB0_1814
	s_nop 0
	v_mul_f32_e32 v128, 0xbfb8aa3b, v60
	v_mul_f32_e32 v129, 0xbfb8aa3b, v61
	v_mul_f32_e32 v130, 0xbfb8aa3b, v62
	v_mul_f32_e32 v131, 0xbfb8aa3b, v63
	v_exp_f32_e32 v128, v128
	v_exp_f32_e32 v129, v129
	v_exp_f32_e32 v130, v130
	v_exp_f32_e32 v131, v131
	v_add_f32_e32 v128, 1.0, v128
	v_add_f32_e32 v129, 1.0, v129
	v_add_f32_e32 v130, 1.0, v130
	v_add_f32_e32 v131, 1.0, v131
	v_rcp_f32_e32 v128, v128
	v_rcp_f32_e32 v129, v129
	v_rcp_f32_e32 v130, v130
	v_rcp_f32_e32 v131, v131
	s_cbranch_execz .LBB0_1815

.LBB0_1818:
	v_cvt_pk_bf16_f32 v128, v128, v129
	v_cvt_pk_bf16_f32 v129, v130, v131
	v_cvt_pk_bf16_f32 v130, v132, v133
	v_cvt_pk_bf16_f32 v131, v134, v135
	s_and_b64 vcc, exec, s[0:1]
	s_mov_b64 s[6:7], -1
	global_store_dwordx4 v[136:137], v[128:131], off offset:256 nt
	s_cbranch_vccnz .LBB0_1822
	s_nop 0
	v_mul_f32_e32 v128, 0xbfb8aa3b, v52
	v_mul_f32_e32 v129, 0xbfb8aa3b, v53
	v_mul_f32_e32 v130, 0xbfb8aa3b, v54
	v_mul_f32_e32 v131, 0xbfb8aa3b, v55
	v_exp_f32_e32 v128, v128
	v_exp_f32_e32 v129, v129
	v_exp_f32_e32 v130, v130
	v_exp_f32_e32 v131, v131
	v_add_f32_e32 v128, 1.0, v128
	v_add_f32_e32 v129, 1.0, v129
	v_add_f32_e32 v130, 1.0, v130
	v_add_f32_e32 v131, 1.0, v131
	v_rcp_f32_e32 v128, v128
	v_rcp_f32_e32 v129, v129
	v_rcp_f32_e32 v130, v130
	v_rcp_f32_e32 v131, v131
	s_cbranch_execz .LBB0_1823

.LBB0_1826:
	v_cvt_pk_bf16_f32 v128, v128, v129
	v_cvt_pk_bf16_f32 v129, v130, v131
	v_cvt_pk_bf16_f32 v130, v132, v133
	v_cvt_pk_bf16_f32 v131, v134, v135
	s_and_b64 vcc, exec, s[0:1]
	s_mov_b64 s[6:7], -1
	global_store_dwordx4 v[138:139], v[128:131], off offset:256 nt
	s_cbranch_vccnz .LBB0_1830
	s_nop 0
	v_mul_f32_e32 v128, 0xbfb8aa3b, v44
	v_mul_f32_e32 v129, 0xbfb8aa3b, v45
	v_mul_f32_e32 v130, 0xbfb8aa3b, v46
	v_mul_f32_e32 v131, 0xbfb8aa3b, v47
	v_exp_f32_e32 v128, v128
	v_exp_f32_e32 v129, v129
	v_exp_f32_e32 v130, v130
	v_exp_f32_e32 v131, v131
	v_add_f32_e32 v128, 1.0, v128
	v_add_f32_e32 v129, 1.0, v129
	v_add_f32_e32 v130, 1.0, v130
	v_add_f32_e32 v131, 1.0, v131
	v_rcp_f32_e32 v128, v128
	v_rcp_f32_e32 v129, v129
	v_rcp_f32_e32 v130, v130
	v_rcp_f32_e32 v131, v131
	s_cbranch_execz .LBB0_1831

.LBB0_1834:
	v_cvt_pk_bf16_f32 v128, v128, v129
	v_cvt_pk_bf16_f32 v129, v130, v131
	v_cvt_pk_bf16_f32 v130, v132, v133
	v_cvt_pk_bf16_f32 v131, v134, v135
	s_and_b64 vcc, exec, s[0:1]
	s_mov_b64 s[6:7], -1
	global_store_dwordx4 v[140:141], v[128:131], off offset:256 nt
	s_cbranch_vccnz .LBB0_1838
	s_nop 0
	v_mul_f32_e32 v128, 0xbfb8aa3b, v36
	v_mul_f32_e32 v129, 0xbfb8aa3b, v37
	v_mul_f32_e32 v130, 0xbfb8aa3b, v38
	v_mul_f32_e32 v131, 0xbfb8aa3b, v39
	v_exp_f32_e32 v128, v128
	v_exp_f32_e32 v129, v129
	v_exp_f32_e32 v130, v130
	v_exp_f32_e32 v131, v131
	v_add_f32_e32 v128, 1.0, v128
	v_add_f32_e32 v129, 1.0, v129
	v_add_f32_e32 v130, 1.0, v130
	v_add_f32_e32 v131, 1.0, v131
	v_rcp_f32_e32 v128, v128
	v_rcp_f32_e32 v129, v129
	v_rcp_f32_e32 v130, v130
	v_rcp_f32_e32 v131, v131
	s_cbranch_execz .LBB0_1839

.LBB0_1842:
	v_cvt_pk_bf16_f32 v128, v128, v129
	v_cvt_pk_bf16_f32 v129, v130, v131
	v_cvt_pk_bf16_f32 v130, v132, v133
	v_cvt_pk_bf16_f32 v131, v134, v135
	s_and_b64 vcc, exec, s[0:1]
	s_mov_b64 s[6:7], -1
	global_store_dwordx4 v[142:143], v[128:131], off offset:256 nt
	s_cbranch_vccnz .LBB0_1846
	s_nop 0
	v_mul_f32_e32 v128, 0xbfb8aa3b, v28
	v_mul_f32_e32 v129, 0xbfb8aa3b, v29
	v_mul_f32_e32 v130, 0xbfb8aa3b, v30
	v_mul_f32_e32 v131, 0xbfb8aa3b, v31
	v_exp_f32_e32 v128, v128
	v_exp_f32_e32 v129, v129
	v_exp_f32_e32 v130, v130
	v_exp_f32_e32 v131, v131
	v_add_f32_e32 v128, 1.0, v128
	v_add_f32_e32 v129, 1.0, v129
	v_add_f32_e32 v130, 1.0, v130
	v_add_f32_e32 v131, 1.0, v131
	v_rcp_f32_e32 v128, v128
	v_rcp_f32_e32 v129, v129
	v_rcp_f32_e32 v130, v130
	v_rcp_f32_e32 v131, v131
	s_cbranch_execz .LBB0_1847

.LBB0_1850:
	v_cvt_pk_bf16_f32 v128, v128, v129
	v_cvt_pk_bf16_f32 v129, v130, v131
	v_cvt_pk_bf16_f32 v130, v132, v133
	v_cvt_pk_bf16_f32 v131, v134, v135
	s_and_b64 vcc, exec, s[0:1]
	s_mov_b64 s[6:7], -1
	global_store_dwordx4 v[144:145], v[128:131], off offset:256 nt
	s_cbranch_vccnz .LBB0_1854
	s_nop 0
	v_mul_f32_e32 v128, 0xbfb8aa3b, v20
	v_mul_f32_e32 v129, 0xbfb8aa3b, v21
	v_mul_f32_e32 v130, 0xbfb8aa3b, v22
	v_mul_f32_e32 v131, 0xbfb8aa3b, v23
	v_exp_f32_e32 v128, v128
	v_exp_f32_e32 v129, v129
	v_exp_f32_e32 v130, v130
	v_exp_f32_e32 v131, v131
	v_add_f32_e32 v128, 1.0, v128
	v_add_f32_e32 v129, 1.0, v129
	v_add_f32_e32 v130, 1.0, v130
	v_add_f32_e32 v131, 1.0, v131
	v_rcp_f32_e32 v128, v128
	v_rcp_f32_e32 v129, v129
	v_rcp_f32_e32 v130, v130
	v_rcp_f32_e32 v131, v131
	s_cbranch_execz .LBB0_1855

.LBB0_1858:
	v_cvt_pk_bf16_f32 v128, v128, v129
	v_cvt_pk_bf16_f32 v129, v130, v131
	v_cvt_pk_bf16_f32 v130, v132, v133
	v_cvt_pk_bf16_f32 v131, v134, v135
	s_and_b64 vcc, exec, s[0:1]
	s_mov_b64 s[6:7], -1
	global_store_dwordx4 v[146:147], v[128:131], off offset:256 nt
	s_cbranch_vccnz .LBB0_1862
	s_nop 0
	v_mul_f32_e32 v128, 0xbfb8aa3b, v12
	v_mul_f32_e32 v129, 0xbfb8aa3b, v13
	v_mul_f32_e32 v130, 0xbfb8aa3b, v14
	v_mul_f32_e32 v131, 0xbfb8aa3b, v15
	v_exp_f32_e32 v128, v128
	v_exp_f32_e32 v129, v129
	v_exp_f32_e32 v130, v130
	v_exp_f32_e32 v131, v131
	v_add_f32_e32 v128, 1.0, v128
	v_add_f32_e32 v129, 1.0, v129
	v_add_f32_e32 v130, 1.0, v130
	v_add_f32_e32 v131, 1.0, v131
	v_rcp_f32_e32 v128, v128
	v_rcp_f32_e32 v129, v129
	v_rcp_f32_e32 v130, v130
	v_rcp_f32_e32 v131, v131
	s_cbranch_execz .LBB0_1863

.LBB0_1866:
	v_cvt_pk_bf16_f32 v128, v128, v129
	v_cvt_pk_bf16_f32 v129, v130, v131
	v_cvt_pk_bf16_f32 v130, v132, v133
	v_cvt_pk_bf16_f32 v131, v134, v135
	s_and_b64 vcc, exec, s[0:1]
	s_mov_b64 s[6:7], -1
	global_store_dwordx4 v[148:149], v[128:131], off offset:256 nt
	s_cbranch_vccnz .LBB0_1870
	s_nop 0
	v_mul_f32_e32 v128, 0xbfb8aa3b, v4
	v_mul_f32_e32 v129, 0xbfb8aa3b, v5
	v_mul_f32_e32 v130, 0xbfb8aa3b, v6
	v_mul_f32_e32 v131, 0xbfb8aa3b, v7
	v_exp_f32_e32 v128, v128
	v_exp_f32_e32 v129, v129
	v_exp_f32_e32 v130, v130
	v_exp_f32_e32 v131, v131
	v_add_f32_e32 v128, 1.0, v128
	v_add_f32_e32 v129, 1.0, v129
	v_add_f32_e32 v130, 1.0, v130
	v_add_f32_e32 v131, 1.0, v131
	v_rcp_f32_e32 v128, v128
	v_rcp_f32_e32 v129, v129
	v_rcp_f32_e32 v130, v130
	v_rcp_f32_e32 v131, v131
	s_cbranch_execz .LBB0_1871

.LBB0_1888:
	v_cndmask_b32_e64 v198, 1.0, v213, s[6:7]
	v_lshlrev_b32_e32 v176, 1, v178
	v_pk_mul_f32 v[122:123], v[198:199], v[122:123] op_sel_hi:[0,1]
	v_pk_mul_f32 v[120:121], v[198:199], v[120:121] op_sel_hi:[0,1]
	v_lshl_add_u64 v[196:197], s[28:29], 0, v[176:177]
	v_pk_mul_f32 v[126:127], v[198:199], v[126:127] op_sel_hi:[0,1]
	v_pk_mul_f32 v[124:125], v[198:199], v[124:125] op_sel_hi:[0,1]
	v_cvt_pk_bf16_f32 v120, v120, v121
	v_cvt_pk_bf16_f32 v121, v122, v123
	v_mad_i64_i32 v[122:123], s[6:7], s26, v214, 0
	v_cvt_pk_bf16_f32 v124, v124, v125
	v_cvt_pk_bf16_f32 v125, v126, v127
	v_lshl_add_u64 v[122:123], v[122:123], 1, v[196:197]
	s_and_b64 vcc, exec, s[0:1]
	s_mov_b64 s[6:7], -1
	global_store_dwordx2 v[122:123], v[124:125], off nt
	global_store_dwordx2 v[122:123], v[120:121], off offset:64 nt
	s_cbranch_vccnz .LBB0_1893
	s_cmp_lt_i32 s2, 4
	s_cbranch_scc1 .LBB0_1891
	s_cmp_eq_u32 s2, 4
	s_cselect_b64 s[6:7], -1, 0
	s_cbranch_execz .LBB0_1892
	s_branch .LBB0_1893

.LBB0_1895:
	v_mov_b32_e32 v199, v198
	v_mov_b32_e32 v122, v198
	v_mov_b32_e32 v123, v198
	v_or_b32_e32 v120, 16, v214
	v_pk_mul_f32 v[114:115], v[122:123], v[114:115]
	v_pk_mul_f32 v[112:113], v[198:199], v[112:113]
	v_pk_mul_f32 v[118:119], v[122:123], v[118:119]
	v_pk_mul_f32 v[116:117], v[198:199], v[116:117]
	v_cvt_pk_bf16_f32 v112, v112, v113
	v_cvt_pk_bf16_f32 v113, v114, v115
	v_mad_i64_i32 v[114:115], s[6:7], s26, v120, 0
	v_cvt_pk_bf16_f32 v116, v116, v117
	v_cvt_pk_bf16_f32 v117, v118, v119
	v_lshl_add_u64 v[114:115], v[114:115], 1, v[196:197]
	s_and_b64 vcc, exec, s[0:1]
	s_mov_b64 s[6:7], -1
	global_store_dwordx2 v[114:115], v[116:117], off nt
	global_store_dwordx2 v[114:115], v[112:113], off offset:64 nt
	s_cbranch_vccnz .LBB0_1900
	s_cmp_lt_i32 s2, 4
	s_cbranch_scc1 .LBB0_1898
	s_cmp_eq_u32 s2, 4
	s_cselect_b64 s[6:7], -1, 0
	s_cbranch_execz .LBB0_1899
	s_branch .LBB0_1900

.LBB0_1902:
	v_mov_b32_e32 v114, v198
	v_mov_b32_e32 v115, v198
	v_or_b32_e32 v112, 32, v214
	v_pk_mul_f32 v[106:107], v[114:115], v[106:107]
	v_pk_mul_f32 v[104:105], v[198:199], v[104:105]
	v_pk_mul_f32 v[110:111], v[114:115], v[110:111]
	v_pk_mul_f32 v[108:109], v[198:199], v[108:109]
	v_cvt_pk_bf16_f32 v104, v104, v105
	v_cvt_pk_bf16_f32 v105, v106, v107
	v_mad_i64_i32 v[106:107], s[6:7], s26, v112, 0
	v_cvt_pk_bf16_f32 v108, v108, v109
	v_cvt_pk_bf16_f32 v109, v110, v111
	v_lshl_add_u64 v[106:107], v[106:107], 1, v[196:197]
	s_and_b64 vcc, exec, s[0:1]
	s_mov_b64 s[6:7], -1
	global_store_dwordx2 v[106:107], v[108:109], off nt
	global_store_dwordx2 v[106:107], v[104:105], off offset:64 nt
	s_cbranch_vccnz .LBB0_1907
	s_cmp_lt_i32 s2, 4
	s_cbranch_scc1 .LBB0_1905
	s_cmp_eq_u32 s2, 4
	s_cselect_b64 s[6:7], -1, 0
	s_cbranch_execz .LBB0_1906
	s_branch .LBB0_1907

.LBB0_1909:
	v_mov_b32_e32 v106, v198
	v_mov_b32_e32 v107, v198
	v_or_b32_e32 v104, 48, v214
	v_pk_mul_f32 v[98:99], v[106:107], v[98:99]
	v_pk_mul_f32 v[96:97], v[198:199], v[96:97]
	v_pk_mul_f32 v[102:103], v[106:107], v[102:103]
	v_pk_mul_f32 v[100:101], v[198:199], v[100:101]
	v_cvt_pk_bf16_f32 v96, v96, v97
	v_cvt_pk_bf16_f32 v97, v98, v99
	v_mad_i64_i32 v[98:99], s[6:7], s26, v104, 0
	v_cvt_pk_bf16_f32 v100, v100, v101
	v_cvt_pk_bf16_f32 v101, v102, v103
	v_lshl_add_u64 v[98:99], v[98:99], 1, v[196:197]
	s_and_b64 vcc, exec, s[0:1]
	s_mov_b64 s[6:7], -1
	global_store_dwordx2 v[98:99], v[100:101], off nt
	global_store_dwordx2 v[98:99], v[96:97], off offset:64 nt
	s_cbranch_vccnz .LBB0_1914
	s_cmp_lt_i32 s2, 4
	s_cbranch_scc1 .LBB0_1912
	s_cmp_eq_u32 s2, 4
	s_cselect_b64 s[6:7], -1, 0
	s_cbranch_execz .LBB0_1913
	s_branch .LBB0_1914

.LBB0_1923:
	v_mov_b32_e32 v98, v198
	v_mov_b32_e32 v99, v198
	v_add_u32_e32 v97, 0x80, v214
	v_pk_mul_f32 v[90:91], v[98:99], v[90:91]
	v_pk_mul_f32 v[88:89], v[198:199], v[88:89]
	v_pk_mul_f32 v[94:95], v[98:99], v[94:95]
	v_pk_mul_f32 v[92:93], v[198:199], v[92:93]
	v_cvt_pk_bf16_f32 v88, v88, v89
	v_cvt_pk_bf16_f32 v89, v90, v91
	v_mad_i64_i32 v[90:91], s[6:7], s26, v97, 0
	v_cvt_pk_bf16_f32 v92, v92, v93
	v_cvt_pk_bf16_f32 v93, v94, v95
	v_lshl_add_u64 v[90:91], v[90:91], 1, v[196:197]
	s_and_b64 vcc, exec, s[0:1]
	s_mov_b64 s[6:7], -1
	global_store_dwordx2 v[90:91], v[92:93], off nt
	global_store_dwordx2 v[90:91], v[88:89], off offset:64 nt
	s_cbranch_vccnz .LBB0_1928
	s_cmp_lt_i32 s2, 4
	s_cbranch_scc1 .LBB0_1926
	s_cmp_eq_u32 s2, 4
	s_cselect_b64 s[6:7], -1, 0
	s_cbranch_execz .LBB0_1927
	s_branch .LBB0_1928

.LBB0_1930:
	v_mov_b32_e32 v90, v198
	v_mov_b32_e32 v91, v198
	v_add_u32_e32 v88, 0x90, v214
	v_pk_mul_f32 v[82:83], v[90:91], v[82:83]
	v_pk_mul_f32 v[80:81], v[198:199], v[80:81]
	v_pk_mul_f32 v[86:87], v[90:91], v[86:87]
	v_pk_mul_f32 v[84:85], v[198:199], v[84:85]
	v_cvt_pk_bf16_f32 v80, v80, v81
	v_cvt_pk_bf16_f32 v81, v82, v83
	v_mad_i64_i32 v[82:83], s[6:7], s26, v88, 0
	v_cvt_pk_bf16_f32 v84, v84, v85
	v_cvt_pk_bf16_f32 v85, v86, v87
	v_lshl_add_u64 v[82:83], v[82:83], 1, v[196:197]
	s_and_b64 vcc, exec, s[0:1]
	s_mov_b64 s[6:7], -1
	global_store_dwordx2 v[82:83], v[84:85], off nt
	global_store_dwordx2 v[82:83], v[80:81], off offset:64 nt
	s_cbranch_vccnz .LBB0_1935
	s_cmp_lt_i32 s2, 4
	s_cbranch_scc1 .LBB0_1933
	s_cmp_eq_u32 s2, 4
	s_cselect_b64 s[6:7], -1, 0
	s_cbranch_execz .LBB0_1934
	s_branch .LBB0_1935

.LBB0_1937:
	v_mov_b32_e32 v82, v198
	v_mov_b32_e32 v83, v198
	v_add_u32_e32 v80, 0xa0, v214
	v_pk_mul_f32 v[74:75], v[82:83], v[74:75]
	v_pk_mul_f32 v[72:73], v[198:199], v[72:73]
	v_pk_mul_f32 v[78:79], v[82:83], v[78:79]
	v_pk_mul_f32 v[76:77], v[198:199], v[76:77]
	v_cvt_pk_bf16_f32 v72, v72, v73
	v_cvt_pk_bf16_f32 v73, v74, v75
	v_mad_i64_i32 v[74:75], s[6:7], s26, v80, 0
	v_cvt_pk_bf16_f32 v76, v76, v77
	v_cvt_pk_bf16_f32 v77, v78, v79
	v_lshl_add_u64 v[74:75], v[74:75], 1, v[196:197]
	s_and_b64 vcc, exec, s[0:1]
	s_mov_b64 s[0:1], -1
	global_store_dwordx2 v[74:75], v[76:77], off nt
	global_store_dwordx2 v[74:75], v[72:73], off offset:64 nt
	s_cbranch_vccnz .LBB0_1942
	s_cmp_lt_i32 s2, 4
	s_cbranch_scc1 .LBB0_1940
	s_cmp_eq_u32 s2, 4
	s_cselect_b64 s[0:1], -1, 0
	s_cbranch_execz .LBB0_1941
	s_branch .LBB0_1942

.LBB0_1944:
	v_mov_b32_e32 v74, v198
	v_mov_b32_e32 v75, v198
	v_add_u32_e32 v72, 0xb0, v214
	v_pk_mul_f32 v[66:67], v[74:75], v[66:67]
	v_pk_mul_f32 v[64:65], v[198:199], v[64:65]
	s_or_b32 s21, s19, 2
	v_cvt_pk_bf16_f32 v64, v64, v65
	v_cvt_pk_bf16_f32 v65, v66, v67
	v_mad_i64_i32 v[66:67], s[0:1], s26, v72, 0
	s_cmp_lt_i32 s21, 8
	v_pk_mul_f32 v[70:71], v[74:75], v[70:71]
	v_pk_mul_f32 v[68:69], v[198:199], v[68:69]
	s_cselect_b64 s[0:1], -1, 0
	v_cvt_pk_bf16_f32 v68, v68, v69
	v_cvt_pk_bf16_f32 v69, v70, v71
	v_lshl_add_u64 v[66:67], v[66:67], 1, v[196:197]
	s_mov_b64 s[6:7], -1
	s_and_b64 vcc, exec, s[0:1]
	global_store_dwordx2 v[66:67], v[68:69], off nt
	global_store_dwordx2 v[66:67], v[64:65], off offset:64 nt
	s_cbranch_vccnz .LBB0_1953
	s_lshl_b32 s2, s19, 6
	s_addk_i32 s2, 0xfe80
	s_lshl_b64 s[6:7], s[2:3], 1
	s_add_u32 s28, s48, s6
	s_addc_u32 s29, s49, s7
	s_mov_b64 s[26:27], 0x300
	s_cbranch_execz .LBB0_1954

.LBB0_1948:
	s_waitcnt vmcnt(0)
	v_pk_mul_f32 v[74:75], v[58:59], v[150:151]
	v_pk_mul_f32 v[76:77], v[56:57], v[148:149]
	v_pk_mul_f32 v[68:69], v[58:59], v[146:147]
	v_pk_mul_f32 v[70:71], v[56:57], v[144:145]
	v_pk_fma_f32 v[74:75], v[62:63], v[146:147], v[74:75]
	v_pk_fma_f32 v[76:77], v[60:61], v[144:145], v[76:77]
	v_cndmask_b32_e64 v66, 1.0, v213, s[0:1]
	v_pk_fma_f32 v[68:69], v[62:63], v[150:151], v[68:69] neg_lo:[0,0,1] neg_hi:[0,0,1]
	v_pk_fma_f32 v[70:71], v[60:61], v[148:149], v[70:71] neg_lo:[0,0,1] neg_hi:[0,0,1]
	v_cndmask_b32_e64 v59, v59, v75, s[0:1]
	v_cndmask_b32_e64 v58, v58, v74, s[0:1]
	v_cndmask_b32_e64 v57, v57, v77, s[0:1]
	v_cndmask_b32_e64 v56, v56, v76, s[0:1]
	v_cndmask_b32_e64 v63, v63, v69, s[0:1]
	v_cndmask_b32_e64 v62, v62, v68, s[0:1]
	v_cndmask_b32_e64 v61, v61, v71, s[0:1]
	v_cndmask_b32_e64 v60, v60, v70, s[0:1]
	v_pk_mul_f32 v[58:59], v[66:67], v[58:59] op_sel_hi:[0,1]
	v_pk_mul_f32 v[56:57], v[66:67], v[56:57] op_sel_hi:[0,1]
	v_lshl_add_u64 v[64:65], s[28:29], 0, v[176:177]
	v_pk_mul_f32 v[62:63], v[66:67], v[62:63] op_sel_hi:[0,1]
	v_pk_mul_f32 v[60:61], v[66:67], v[60:61] op_sel_hi:[0,1]
	v_cvt_pk_bf16_f32 v56, v56, v57
	v_cvt_pk_bf16_f32 v57, v58, v59
	v_mad_i64_i32 v[58:59], s[28:29], s26, v214, 0
	v_cvt_pk_bf16_f32 v60, v60, v61
	v_cvt_pk_bf16_f32 v61, v62, v63
	v_lshl_add_u64 v[58:59], v[58:59], 1, v[64:65]
	global_store_dwordx2 v[58:59], v[60:61], off nt
	global_store_dwordx2 v[58:59], v[56:57], off offset:64 nt
	v_pk_mul_f32 v[60:61], v[50:51], v[142:143]
	v_pk_mul_f32 v[62:63], v[48:49], v[140:141]
	v_pk_mul_f32 v[56:57], v[50:51], v[138:139]
	v_pk_mul_f32 v[58:59], v[48:49], v[136:137]
	v_pk_fma_f32 v[60:61], v[54:55], v[138:139], v[60:61]
	v_pk_fma_f32 v[62:63], v[52:53], v[136:137], v[62:63]
	v_pk_fma_f32 v[56:57], v[54:55], v[142:143], v[56:57] neg_lo:[0,0,1] neg_hi:[0,0,1]
	v_pk_fma_f32 v[58:59], v[52:53], v[140:141], v[58:59] neg_lo:[0,0,1] neg_hi:[0,0,1]
	v_cndmask_b32_e64 v49, v49, v63, s[0:1]
	v_cndmask_b32_e64 v48, v48, v62, s[0:1]
	v_cndmask_b32_e64 v51, v51, v61, s[0:1]
	v_cndmask_b32_e64 v50, v50, v60, s[0:1]
	v_cndmask_b32_e64 v53, v53, v59, s[0:1]
	v_cndmask_b32_e64 v52, v52, v58, s[0:1]
	v_cndmask_b32_e64 v55, v55, v57, s[0:1]
	v_cndmask_b32_e64 v54, v54, v56, s[0:1]
	v_pk_mul_f32 v[50:51], v[66:67], v[50:51] op_sel_hi:[0,1]
	v_pk_mul_f32 v[48:49], v[66:67], v[48:49] op_sel_hi:[0,1]
	v_pk_mul_f32 v[54:55], v[66:67], v[54:55] op_sel_hi:[0,1]
	v_pk_mul_f32 v[52:53], v[66:67], v[52:53] op_sel_hi:[0,1]
	v_cvt_pk_bf16_f32 v48, v48, v49
	v_cvt_pk_bf16_f32 v49, v50, v51
	v_mad_i64_i32 v[50:51], s[28:29], s26, v120, 0
	v_cvt_pk_bf16_f32 v52, v52, v53
	v_cvt_pk_bf16_f32 v53, v54, v55
	v_lshl_add_u64 v[50:51], v[50:51], 1, v[64:65]
	global_store_dwordx2 v[50:51], v[52:53], off nt
	global_store_dwordx2 v[50:51], v[48:49], off offset:64 nt
	v_pk_mul_f32 v[52:53], v[42:43], v[134:135]
	v_pk_mul_f32 v[54:55], v[40:41], v[132:133]
	v_pk_mul_f32 v[48:49], v[42:43], v[130:131]
	v_pk_mul_f32 v[50:51], v[40:41], v[128:129]
	v_pk_fma_f32 v[52:53], v[46:47], v[130:131], v[52:53]
	v_pk_fma_f32 v[54:55], v[44:45], v[128:129], v[54:55]
	v_pk_fma_f32 v[48:49], v[46:47], v[134:135], v[48:49] neg_lo:[0,0,1] neg_hi:[0,0,1]
	v_pk_fma_f32 v[50:51], v[44:45], v[132:133], v[50:51] neg_lo:[0,0,1] neg_hi:[0,0,1]
	v_cndmask_b32_e64 v41, v41, v55, s[0:1]
	v_cndmask_b32_e64 v40, v40, v54, s[0:1]
	v_cndmask_b32_e64 v43, v43, v53, s[0:1]
	v_cndmask_b32_e64 v42, v42, v52, s[0:1]
	v_cndmask_b32_e64 v45, v45, v51, s[0:1]
	v_cndmask_b32_e64 v44, v44, v50, s[0:1]
	v_cndmask_b32_e64 v47, v47, v49, s[0:1]
	v_cndmask_b32_e64 v46, v46, v48, s[0:1]
	v_pk_mul_f32 v[42:43], v[66:67], v[42:43] op_sel_hi:[0,1]
	v_pk_mul_f32 v[40:41], v[66:67], v[40:41] op_sel_hi:[0,1]
	v_pk_mul_f32 v[46:47], v[66:67], v[46:47] op_sel_hi:[0,1]
	v_pk_mul_f32 v[44:45], v[66:67], v[44:45] op_sel_hi:[0,1]
	v_cvt_pk_bf16_f32 v40, v40, v41
	v_cvt_pk_bf16_f32 v41, v42, v43
	v_mad_i64_i32 v[42:43], s[28:29], s26, v112, 0
	v_cvt_pk_bf16_f32 v44, v44, v45
	v_cvt_pk_bf16_f32 v45, v46, v47
	v_lshl_add_u64 v[42:43], v[42:43], 1, v[64:65]
	global_store_dwordx2 v[42:43], v[44:45], off nt
	global_store_dwordx2 v[42:43], v[40:41], off offset:64 nt
	v_pk_mul_f32 v[44:45], v[34:35], v[158:159]
	v_pk_mul_f32 v[46:47], v[32:33], v[156:157]
	v_pk_mul_f32 v[40:41], v[34:35], v[154:155]
	v_pk_mul_f32 v[42:43], v[32:33], v[152:153]
	v_pk_fma_f32 v[44:45], v[38:39], v[154:155], v[44:45]
	v_pk_fma_f32 v[46:47], v[36:37], v[152:153], v[46:47]
	v_pk_fma_f32 v[40:41], v[38:39], v[158:159], v[40:41] neg_lo:[0,0,1] neg_hi:[0,0,1]
	v_pk_fma_f32 v[42:43], v[36:37], v[156:157], v[42:43] neg_lo:[0,0,1] neg_hi:[0,0,1]
	v_cndmask_b32_e64 v33, v33, v47, s[0:1]
	v_cndmask_b32_e64 v32, v32, v46, s[0:1]
	v_cndmask_b32_e64 v35, v35, v45, s[0:1]
	v_cndmask_b32_e64 v34, v34, v44, s[0:1]
	v_cndmask_b32_e64 v37, v37, v43, s[0:1]
	v_cndmask_b32_e64 v36, v36, v42, s[0:1]
	v_cndmask_b32_e64 v39, v39, v41, s[0:1]
	v_cndmask_b32_e64 v38, v38, v40, s[0:1]
	v_pk_mul_f32 v[34:35], v[66:67], v[34:35] op_sel_hi:[0,1]
	v_pk_mul_f32 v[32:33], v[66:67], v[32:33] op_sel_hi:[0,1]
	v_pk_mul_f32 v[38:39], v[66:67], v[38:39] op_sel_hi:[0,1]
	v_pk_mul_f32 v[36:37], v[66:67], v[36:37] op_sel_hi:[0,1]
	v_cvt_pk_bf16_f32 v32, v32, v33
	v_cvt_pk_bf16_f32 v33, v34, v35
	v_mad_i64_i32 v[34:35], s[28:29], s26, v104, 0
	v_cvt_pk_bf16_f32 v36, v36, v37
	v_cvt_pk_bf16_f32 v37, v38, v39
	v_lshl_add_u64 v[34:35], v[34:35], 1, v[64:65]
	s_and_b64 vcc, exec, s[6:7]
	global_store_dwordx2 v[34:35], v[36:37], off nt
	global_store_dwordx2 v[34:35], v[32:33], off offset:64 nt
	s_cbranch_vccnz .LBB0_1950
	v_lshlrev_b32_e32 v176, 2, v96
	v_lshl_add_u64 v[32:33], v[180:181], 0, v[176:177]
	v_lshl_add_u64 v[34:35], v[182:183], 0, v[176:177]
	global_load_dwordx4 v[148:151], v[32:33], off
	global_load_dwordx4 v[140:143], v[32:33], off offset:2048
	global_load_dwordx4 v[144:147], v[34:35], off
	global_load_dwordx4 v[136:139], v[34:35], off offset:2048
	v_or_b32_e32 v32, 0x1000, v176
	v_mov_b32_e32 v33, v177
	v_lshl_add_u64 v[34:35], v[180:181], 0, v[32:33]
	v_lshl_add_u64 v[32:33], v[182:183], 0, v[32:33]
	v_or_b32_e32 v176, 0x1800, v176
	global_load_dwordx4 v[132:135], v[34:35], off
	global_load_dwordx4 v[128:131], v[32:33], off
	v_lshl_add_u64 v[32:33], v[180:181], 0, v[176:177]
	v_lshl_add_u64 v[34:35], v[182:183], 0, v[176:177]
	global_load_dwordx4 v[156:159], v[32:33], off
	global_load_dwordx4 v[152:155], v[34:35], off
.LBB0_1950:
	s_waitcnt vmcnt(5)
	v_pk_mul_f32 v[32:33], v[26:27], v[146:147]
	v_pk_mul_f32 v[36:37], v[26:27], v[150:151]
	v_pk_mul_f32 v[38:39], v[24:25], v[148:149]
	v_pk_mul_f32 v[34:35], v[24:25], v[144:145]
	v_pk_fma_f32 v[32:33], v[30:31], v[150:151], v[32:33] neg_lo:[0,0,1] neg_hi:[0,0,1]
	v_pk_fma_f32 v[36:37], v[30:31], v[146:147], v[36:37]
	v_pk_fma_f32 v[38:39], v[28:29], v[144:145], v[38:39]
	v_mov_b32_e32 v67, v66
	v_pk_fma_f32 v[34:35], v[28:29], v[148:149], v[34:35] neg_lo:[0,0,1] neg_hi:[0,0,1]
	v_cndmask_b32_e64 v25, v25, v39, s[0:1]
	v_cndmask_b32_e64 v24, v24, v38, s[0:1]
	v_cndmask_b32_e64 v27, v27, v37, s[0:1]
	v_cndmask_b32_e64 v26, v26, v36, s[0:1]
	v_cndmask_b32_e64 v31, v31, v33, s[0:1]
	v_cndmask_b32_e64 v30, v30, v32, s[0:1]
	v_mov_b32_e32 v32, v66
	v_mov_b32_e32 v33, v66
	v_cndmask_b32_e64 v29, v29, v35, s[0:1]
	v_cndmask_b32_e64 v28, v28, v34, s[0:1]
	v_pk_mul_f32 v[26:27], v[32:33], v[26:27]
	v_pk_mul_f32 v[24:25], v[66:67], v[24:25]
	v_pk_mul_f32 v[30:31], v[32:33], v[30:31]
	v_pk_mul_f32 v[28:29], v[66:67], v[28:29]
	v_cvt_pk_bf16_f32 v24, v24, v25
	v_cvt_pk_bf16_f32 v25, v26, v27
	v_mad_i64_i32 v[26:27], s[6:7], s26, v97, 0
	v_cvt_pk_bf16_f32 v28, v28, v29
	v_cvt_pk_bf16_f32 v29, v30, v31
	v_lshl_add_u64 v[26:27], v[26:27], 1, v[64:65]
	global_store_dwordx2 v[26:27], v[28:29], off nt
	global_store_dwordx2 v[26:27], v[24:25], off offset:64 nt
	v_pk_mul_f32 v[28:29], v[18:19], v[142:143]
	v_pk_mul_f32 v[30:31], v[16:17], v[140:141]
	s_waitcnt vmcnt(6)
	v_pk_mul_f32 v[24:25], v[18:19], v[138:139]
	v_pk_mul_f32 v[26:27], v[16:17], v[136:137]
	v_pk_fma_f32 v[28:29], v[22:23], v[138:139], v[28:29]
	v_pk_fma_f32 v[30:31], v[20:21], v[136:137], v[30:31]
	v_pk_fma_f32 v[24:25], v[22:23], v[142:143], v[24:25] neg_lo:[0,0,1] neg_hi:[0,0,1]
	v_pk_fma_f32 v[26:27], v[20:21], v[140:141], v[26:27] neg_lo:[0,0,1] neg_hi:[0,0,1]
	v_cndmask_b32_e64 v17, v17, v31, s[0:1]
	v_cndmask_b32_e64 v16, v16, v30, s[0:1]
	v_cndmask_b32_e64 v19, v19, v29, s[0:1]
	v_cndmask_b32_e64 v18, v18, v28, s[0:1]
	v_cndmask_b32_e64 v21, v21, v27, s[0:1]
	v_cndmask_b32_e64 v20, v20, v26, s[0:1]
	v_cndmask_b32_e64 v23, v23, v25, s[0:1]
	v_cndmask_b32_e64 v22, v22, v24, s[0:1]
	v_pk_mul_f32 v[18:19], v[32:33], v[18:19]
	v_pk_mul_f32 v[16:17], v[66:67], v[16:17]
	v_pk_mul_f32 v[22:23], v[32:33], v[22:23]
	v_pk_mul_f32 v[20:21], v[66:67], v[20:21]
	v_cvt_pk_bf16_f32 v16, v16, v17
	v_cvt_pk_bf16_f32 v17, v18, v19
	v_mad_i64_i32 v[18:19], s[6:7], s26, v88, 0
	v_cvt_pk_bf16_f32 v20, v20, v21
	v_cvt_pk_bf16_f32 v21, v22, v23
	v_lshl_add_u64 v[18:19], v[18:19], 1, v[64:65]
	global_store_dwordx2 v[18:19], v[20:21], off nt
	global_store_dwordx2 v[18:19], v[16:17], off offset:64 nt
	s_waitcnt vmcnt(7)
	v_pk_mul_f32 v[20:21], v[10:11], v[134:135]
	v_pk_mul_f32 v[22:23], v[8:9], v[132:133]
	s_waitcnt vmcnt(6)
	v_pk_mul_f32 v[16:17], v[10:11], v[130:131]
	v_pk_mul_f32 v[18:19], v[8:9], v[128:129]
	v_pk_fma_f32 v[20:21], v[14:15], v[130:131], v[20:21]
	v_pk_fma_f32 v[22:23], v[12:13], v[128:129], v[22:23]
	v_pk_fma_f32 v[16:17], v[14:15], v[134:135], v[16:17] neg_lo:[0,0,1] neg_hi:[0,0,1]
	v_pk_fma_f32 v[18:19], v[12:13], v[132:133], v[18:19] neg_lo:[0,0,1] neg_hi:[0,0,1]
	v_cndmask_b32_e64 v9, v9, v23, s[0:1]
	v_cndmask_b32_e64 v8, v8, v22, s[0:1]
	v_cndmask_b32_e64 v11, v11, v21, s[0:1]
	v_cndmask_b32_e64 v10, v10, v20, s[0:1]
	v_cndmask_b32_e64 v13, v13, v19, s[0:1]
	v_cndmask_b32_e64 v12, v12, v18, s[0:1]
	v_cndmask_b32_e64 v15, v15, v17, s[0:1]
	v_cndmask_b32_e64 v14, v14, v16, s[0:1]
	v_pk_mul_f32 v[10:11], v[32:33], v[10:11]
	v_pk_mul_f32 v[8:9], v[66:67], v[8:9]
	v_pk_mul_f32 v[14:15], v[32:33], v[14:15]
	v_pk_mul_f32 v[12:13], v[66:67], v[12:13]
	v_cvt_pk_bf16_f32 v8, v8, v9
	v_cvt_pk_bf16_f32 v9, v10, v11
	v_mad_i64_i32 v[10:11], s[6:7], s26, v80, 0
	v_cvt_pk_bf16_f32 v12, v12, v13
	v_cvt_pk_bf16_f32 v13, v14, v15
	v_lshl_add_u64 v[10:11], v[10:11], 1, v[64:65]
	global_store_dwordx2 v[10:11], v[12:13], off nt
	global_store_dwordx2 v[10:11], v[8:9], off offset:64 nt
	s_waitcnt vmcnt(7)
	v_pk_mul_f32 v[12:13], v[2:3], v[158:159]
	v_pk_mul_f32 v[14:15], v[0:1], v[156:157]
	s_waitcnt vmcnt(6)
	v_pk_mul_f32 v[8:9], v[2:3], v[154:155]
	v_pk_mul_f32 v[10:11], v[0:1], v[152:153]
	v_pk_fma_f32 v[12:13], v[6:7], v[154:155], v[12:13]
	v_pk_fma_f32 v[14:15], v[4:5], v[152:153], v[14:15]
	v_pk_fma_f32 v[8:9], v[6:7], v[158:159], v[8:9] neg_lo:[0,0,1] neg_hi:[0,0,1]
	v_pk_fma_f32 v[10:11], v[4:5], v[156:157], v[10:11] neg_lo:[0,0,1] neg_hi:[0,0,1]
	v_cndmask_b32_e64 v1, v1, v15, s[0:1]
	v_cndmask_b32_e64 v0, v0, v14, s[0:1]
	v_cndmask_b32_e64 v3, v3, v13, s[0:1]
	v_cndmask_b32_e64 v2, v2, v12, s[0:1]
	v_cndmask_b32_e64 v5, v5, v11, s[0:1]
	v_cndmask_b32_e64 v4, v4, v10, s[0:1]
	v_cndmask_b32_e64 v7, v7, v9, s[0:1]
	v_cndmask_b32_e64 v6, v6, v8, s[0:1]
	v_pk_mul_f32 v[2:3], v[32:33], v[2:3]
	v_pk_mul_f32 v[0:1], v[66:67], v[0:1]
	v_pk_mul_f32 v[6:7], v[32:33], v[6:7]
	v_pk_mul_f32 v[4:5], v[66:67], v[4:5]
	v_cvt_pk_bf16_f32 v0, v0, v1
	v_cvt_pk_bf16_f32 v1, v2, v3
	v_mad_i64_i32 v[2:3], s[0:1], s26, v72, 0
	v_cvt_pk_bf16_f32 v4, v4, v5
	v_cvt_pk_bf16_f32 v5, v6, v7
	v_lshl_add_u64 v[2:3], v[2:3], 1, v[64:65]
	global_store_dwordx2 v[2:3], v[4:5], off nt
	global_store_dwordx2 v[2:3], v[0:1], off offset:64 nt
	s_andn2_b64 vcc, exec, s[4:5]
	s_mov_b64 s[0:1], -1
	s_cbranch_vccnz .LBB0_1725

.LBB0_2261:
	v_lshl_or_b32 v128, s26, 8, v169
	v_lshl_add_u32 v150, s24, 8, v167
	v_ashrrev_i32_e32 v129, 31, v128
	v_mov_b64_e32 v[152:153], s[2:3]
	v_mad_i64_i32 v[130:131], s[28:29], v150, s51, v[152:153]
	v_lshlrev_b64 v[148:149], 1, v[128:129]
	v_lshl_add_u64 v[128:129], v[130:131], 0, v[148:149]
	global_load_dwordx4 v[174:177], v[128:129], off offset:2048
	global_load_dwordx4 v[178:181], v[128:129], off offset:2304
	v_or_b32_e32 v128, 16, v150
	v_mad_i64_i32 v[130:131], s[28:29], v128, s51, v[152:153]
	v_lshl_add_u64 v[130:131], v[130:131], 0, v[148:149]
	global_load_dwordx4 v[182:185], v[130:131], off offset:2048
	global_load_dwordx4 v[186:189], v[130:131], off offset:2304
	v_or_b32_e32 v198, 32, v150
	v_mad_i64_i32 v[190:191], s[28:29], v198, s51, v[152:153]
	v_lshl_add_u64 v[196:197], v[190:191], 0, v[148:149]
	global_load_dwordx4 v[190:193], v[196:197], off offset:2048
	v_ashrrev_i32_e32 v151, 31, v150
	v_or_b32_e32 v154, 48, v150
	v_ashrrev_i32_e32 v129, 31, v128
	v_lshlrev_b64 v[130:131], 11, v[150:151]
	v_mad_i64_i32 v[194:195], s[28:29], v154, s51, v[152:153]
	v_lshl_add_u64 v[130:131], s[4:5], 0, v[130:131]
	v_lshlrev_b64 v[128:129], 11, v[128:129]
	v_lshl_add_u64 v[200:201], v[194:195], 0, v[148:149]
	v_lshl_add_u64 v[204:205], v[130:131], 0, v[148:149]
	v_lshl_add_u64 v[206:207], s[4:5], 0, v[128:129]
	global_load_dwordx4 v[194:197], v[196:197], off offset:2304
	s_nop 0
	global_load_dwordx4 v[128:131], v[200:201], off offset:2048
	v_lshl_add_u64 v[206:207], v[206:207], 0, v[148:149]
	v_ashrrev_i32_e32 v199, 31, v198
	v_ashrrev_i32_e32 v155, 31, v154
	s_andn2_b64 vcc, exec, s[0:1]
	s_mov_b64 s[0:1], -1
	s_waitcnt vmcnt(0)
	v_lshlrev_b32_e32 v210, 16, v175
	v_and_b32_e32 v211, 0xffff0000, v175
	v_lshlrev_b32_e32 v212, 16, v174
	v_and_b32_e32 v213, 0xffff0000, v174
	v_lshlrev_b32_e32 v174, 16, v176
	v_and_b32_e32 v175, 0xffff0000, v176
	v_lshlrev_b32_e32 v176, 16, v177
	v_and_b32_e32 v177, 0xffff0000, v177
	v_lshlrev_b32_e32 v214, 16, v179
	v_and_b32_e32 v215, 0xffff0000, v179
	v_lshlrev_b32_e32 v216, 16, v178
	v_and_b32_e32 v217, 0xffff0000, v178
	v_lshlrev_b32_e32 v178, 16, v180
	v_and_b32_e32 v179, 0xffff0000, v180
	v_lshlrev_b32_e32 v180, 16, v181
	v_and_b32_e32 v181, 0xffff0000, v181
	v_lshlrev_b32_e32 v218, 16, v183
	v_and_b32_e32 v219, 0xffff0000, v183
	v_lshlrev_b32_e32 v220, 16, v182
	v_and_b32_e32 v221, 0xffff0000, v182
	v_lshlrev_b32_e32 v182, 16, v184
	v_and_b32_e32 v183, 0xffff0000, v184
	v_lshlrev_b32_e32 v184, 16, v185
	v_and_b32_e32 v185, 0xffff0000, v185
	v_pk_mul_f32 v[126:127], v[126:127], v[210:211]
	v_pk_mul_f32 v[124:125], v[124:125], v[212:213]
	v_pk_mul_f32 v[120:121], v[120:121], v[174:175]
	v_pk_mul_f32 v[122:123], v[122:123], v[176:177]
	v_pk_mul_f32 v[110:111], v[110:111], v[214:215]
	v_pk_mul_f32 v[108:109], v[108:109], v[216:217]
	v_pk_mul_f32 v[174:175], v[104:105], v[178:179]
	v_pk_mul_f32 v[176:177], v[106:107], v[180:181]
	v_pk_mul_f32 v[118:119], v[118:119], v[218:219]
	v_pk_mul_f32 v[116:117], v[116:117], v[220:221]
	v_pk_mul_f32 v[178:179], v[112:113], v[182:183]
	v_pk_mul_f32 v[180:181], v[114:115], v[184:185]
	v_cvt_pk_bf16_f32 v104, v124, v125
	v_cvt_pk_bf16_f32 v105, v126, v127
	v_cvt_pk_bf16_f32 v106, v120, v121
	v_cvt_pk_bf16_f32 v107, v122, v123
	v_lshlrev_b32_e32 v222, 16, v187
	v_and_b32_e32 v223, 0xffff0000, v187
	v_cvt_pk_bf16_f32 v108, v108, v109
	v_cvt_pk_bf16_f32 v109, v110, v111
	v_cvt_pk_bf16_f32 v110, v174, v175
	v_cvt_pk_bf16_f32 v111, v176, v177
	v_cvt_pk_bf16_f32 v112, v116, v117
	v_cvt_pk_bf16_f32 v113, v118, v119
	v_cvt_pk_bf16_f32 v114, v178, v179
	v_cvt_pk_bf16_f32 v115, v180, v181
	global_store_dwordx4 v[204:205], v[104:107], off nt
	global_store_dwordx4 v[204:205], v[108:111], off offset:256 nt
	global_store_dwordx4 v[206:207], v[112:115], off nt
	v_lshlrev_b32_e32 v104, 16, v186
	v_and_b32_e32 v105, 0xffff0000, v186
	v_pk_mul_f32 v[102:103], v[102:103], v[222:223]
	v_pk_mul_f32 v[100:101], v[100:101], v[104:105]
	global_load_dwordx4 v[104:107], v[200:201], off offset:2304
	v_cvt_pk_bf16_f32 v100, v100, v101
	v_cvt_pk_bf16_f32 v101, v102, v103
	v_lshlrev_b32_e32 v102, 16, v188
	v_and_b32_e32 v103, 0xffff0000, v188
	v_pk_mul_f32 v[96:97], v[96:97], v[102:103]
	v_add_u32_e32 v108, 0x80, v150
	v_cvt_pk_bf16_f32 v102, v96, v97
	v_lshlrev_b32_e32 v96, 16, v189
	v_and_b32_e32 v97, 0xffff0000, v189
	v_pk_mul_f32 v[96:97], v[98:99], v[96:97]
	v_lshlrev_b32_e32 v98, 16, v190
	v_and_b32_e32 v99, 0xffff0000, v190
	v_cvt_pk_bf16_f32 v103, v96, v97
	v_lshlrev_b32_e32 v96, 16, v191
	v_and_b32_e32 v97, 0xffff0000, v191
	v_pk_mul_f32 v[92:93], v[92:93], v[98:99]
	global_store_dwordx4 v[206:207], v[100:103], off offset:256 nt
	v_cvt_pk_bf16_f32 v98, v92, v93
	v_lshlrev_b32_e32 v92, 16, v192
	v_pk_mul_f32 v[100:101], v[94:95], v[96:97]
	v_mad_i64_i32 v[94:95], s[28:29], v108, s51, v[152:153]
	v_and_b32_e32 v93, 0xffff0000, v192
	v_lshl_add_u64 v[110:111], v[94:95], 0, v[148:149]
	v_pk_mul_f32 v[88:89], v[88:89], v[92:93]
	global_load_dwordx4 v[94:97], v[110:111], off offset:2048
	v_cvt_pk_bf16_f32 v99, v100, v101
	v_cvt_pk_bf16_f32 v100, v88, v89
	v_lshlrev_b32_e32 v88, 16, v193
	v_and_b32_e32 v89, 0xffff0000, v193
	v_lshlrev_b64 v[102:103], 11, v[198:199]
	v_pk_mul_f32 v[88:89], v[90:91], v[88:89]
	v_ashrrev_i32_e32 v109, 31, v108
	v_cvt_pk_bf16_f32 v101, v88, v89
	v_lshl_add_u64 v[88:89], s[4:5], 0, v[102:103]
	v_lshl_add_u64 v[92:93], v[88:89], 0, v[148:149]
	v_lshlrev_b32_e32 v88, 16, v195
	v_and_b32_e32 v89, 0xffff0000, v195
	v_pk_mul_f32 v[82:83], v[82:83], v[88:89]
	v_lshlrev_b32_e32 v88, 16, v194
	v_and_b32_e32 v89, 0xffff0000, v194
	v_pk_mul_f32 v[80:81], v[80:81], v[88:89]
	global_load_dwordx4 v[88:91], v[110:111], off offset:2304
	v_cvt_pk_bf16_f32 v80, v80, v81
	v_cvt_pk_bf16_f32 v81, v82, v83
	v_lshlrev_b32_e32 v82, 16, v196
	v_and_b32_e32 v83, 0xffff0000, v196
	v_pk_mul_f32 v[76:77], v[76:77], v[82:83]
	global_store_dwordx4 v[92:93], v[98:101], off nt
	v_cvt_pk_bf16_f32 v82, v76, v77
	v_lshlrev_b32_e32 v76, 16, v197
	v_and_b32_e32 v77, 0xffff0000, v197
	v_pk_mul_f32 v[76:77], v[78:79], v[76:77]
	s_nop 0
	v_cvt_pk_bf16_f32 v83, v76, v77
	v_lshlrev_b32_e32 v76, 16, v129
	v_and_b32_e32 v77, 0xffff0000, v129
	v_pk_mul_f32 v[78:79], v[86:87], v[76:77]
	v_lshlrev_b32_e32 v76, 16, v128
	v_and_b32_e32 v77, 0xffff0000, v128
	v_pk_mul_f32 v[76:77], v[84:85], v[76:77]
	v_add_u32_e32 v84, 0x90, v150
	global_store_dwordx4 v[92:93], v[80:83], off offset:256 nt
	v_cvt_pk_bf16_f32 v76, v76, v77
	v_cvt_pk_bf16_f32 v77, v78, v79
	v_mad_i64_i32 v[80:81], s[28:29], v84, s51, v[152:153]
	v_lshl_add_u64 v[86:87], v[80:81], 0, v[148:149]
	global_load_dwordx4 v[80:83], v[86:87], off offset:2048
	v_lshlrev_b32_e32 v78, 16, v130
	v_and_b32_e32 v79, 0xffff0000, v130
	v_pk_mul_f32 v[72:73], v[72:73], v[78:79]
	v_lshlrev_b64 v[92:93], 11, v[154:155]
	v_cvt_pk_bf16_f32 v78, v72, v73
	v_lshlrev_b32_e32 v72, 16, v131
	v_and_b32_e32 v73, 0xffff0000, v131
	v_pk_mul_f32 v[72:73], v[74:75], v[72:73]
	v_ashrrev_i32_e32 v85, 31, v84
	v_cvt_pk_bf16_f32 v79, v72, v73
	v_lshl_add_u64 v[72:73], s[4:5], 0, v[92:93]
	v_lshl_add_u64 v[92:93], v[72:73], 0, v[148:149]
	s_waitcnt vmcnt(6)
	v_lshlrev_b32_e32 v72, 16, v105
	v_and_b32_e32 v73, 0xffff0000, v105
	v_pk_mul_f32 v[70:71], v[70:71], v[72:73]
	v_lshlrev_b32_e32 v72, 16, v104
	v_and_b32_e32 v73, 0xffff0000, v104
	v_pk_mul_f32 v[68:69], v[68:69], v[72:73]
	global_load_dwordx4 v[72:75], v[86:87], off offset:2304
	v_cvt_pk_bf16_f32 v68, v68, v69
	v_cvt_pk_bf16_f32 v69, v70, v71
	v_lshlrev_b32_e32 v70, 16, v106
	v_and_b32_e32 v71, 0xffff0000, v106
	v_pk_mul_f32 v[64:65], v[64:65], v[70:71]
	global_store_dwordx4 v[92:93], v[76:79], off nt
	v_cvt_pk_bf16_f32 v70, v64, v65
	v_lshlrev_b32_e32 v64, 16, v107
	v_and_b32_e32 v65, 0xffff0000, v107
	v_pk_mul_f32 v[64:65], v[66:67], v[64:65]
	v_add_u32_e32 v76, 0xa0, v150
	v_cvt_pk_bf16_f32 v71, v64, v65
	global_store_dwordx4 v[92:93], v[68:71], off offset:256 nt
	v_ashrrev_i32_e32 v77, 31, v76
	s_waitcnt vmcnt(7)
	v_lshlrev_b32_e32 v64, 16, v95
	v_and_b32_e32 v65, 0xffff0000, v95
	v_pk_mul_f32 v[68:69], v[62:63], v[64:65]
	v_lshlrev_b32_e32 v66, 16, v94
	v_mad_i64_i32 v[62:63], s[28:29], v76, s51, v[152:153]
	v_and_b32_e32 v67, 0xffff0000, v94
	v_lshl_add_u64 v[78:79], v[62:63], 0, v[148:149]
	v_pk_mul_f32 v[60:61], v[60:61], v[66:67]
	global_load_dwordx4 v[62:65], v[78:79], off offset:2048
	v_cvt_pk_bf16_f32 v66, v60, v61
	v_lshlrev_b32_e32 v60, 16, v96
	v_and_b32_e32 v61, 0xffff0000, v96
	v_pk_mul_f32 v[56:57], v[56:57], v[60:61]
	v_cvt_pk_bf16_f32 v67, v68, v69
	v_cvt_pk_bf16_f32 v68, v56, v57
	v_lshlrev_b32_e32 v56, 16, v97
	v_and_b32_e32 v57, 0xffff0000, v97
	v_lshlrev_b64 v[70:71], 11, v[108:109]
	v_pk_mul_f32 v[56:57], v[58:59], v[56:57]
	s_waitcnt vmcnt(7)
	v_lshlrev_b32_e32 v58, 16, v88
	v_cvt_pk_bf16_f32 v69, v56, v57
	v_lshl_add_u64 v[56:57], s[4:5], 0, v[70:71]
	v_lshl_add_u64 v[70:71], v[56:57], 0, v[148:149]
	v_lshlrev_b32_e32 v56, 16, v89
	v_and_b32_e32 v57, 0xffff0000, v89
	v_and_b32_e32 v59, 0xffff0000, v88
	v_pk_mul_f32 v[60:61], v[54:55], v[56:57]
	global_load_dwordx4 v[54:57], v[78:79], off offset:2304
	v_pk_mul_f32 v[52:53], v[52:53], v[58:59]
	v_cvt_pk_bf16_f32 v59, v60, v61
	v_cvt_pk_bf16_f32 v58, v52, v53
	v_lshlrev_b32_e32 v52, 16, v90
	v_and_b32_e32 v53, 0xffff0000, v90
	v_pk_mul_f32 v[44:45], v[44:45], v[52:53]
	v_add_u32_e32 v52, 0xb0, v150
	v_cvt_pk_bf16_f32 v60, v44, v45
	v_lshlrev_b32_e32 v44, 16, v91
	v_and_b32_e32 v45, 0xffff0000, v91
	v_pk_mul_f32 v[44:45], v[46:47], v[44:45]
	global_store_dwordx4 v[70:71], v[66:69], off nt
	v_cvt_pk_bf16_f32 v61, v44, v45
	v_mad_i64_i32 v[44:45], s[28:29], v52, s51, v[152:153]
	v_lshl_add_u64 v[66:67], v[44:45], 0, v[148:149]
	global_store_dwordx4 v[70:71], v[58:61], off offset:256 nt
	global_load_dwordx4 v[44:47], v[66:67], off offset:2048
	v_ashrrev_i32_e32 v53, 31, v52
	s_waitcnt vmcnt(8)
	v_lshlrev_b32_e32 v60, 16, v81
	v_and_b32_e32 v61, 0xffff0000, v81
	v_pk_mul_f32 v[50:51], v[50:51], v[60:61]
	v_lshlrev_b32_e32 v60, 16, v80
	v_and_b32_e32 v61, 0xffff0000, v80
	v_pk_mul_f32 v[48:49], v[48:49], v[60:61]
	v_lshlrev_b64 v[58:59], 11, v[84:85]
	v_cvt_pk_bf16_f32 v48, v48, v49
	v_cvt_pk_bf16_f32 v49, v50, v51
	v_lshlrev_b32_e32 v50, 16, v82
	v_and_b32_e32 v51, 0xffff0000, v82
	v_pk_mul_f32 v[40:41], v[40:41], v[50:51]
	v_lshl_add_u64 v[58:59], s[4:5], 0, v[58:59]
	v_cvt_pk_bf16_f32 v50, v40, v41
	v_lshlrev_b32_e32 v40, 16, v83
	v_and_b32_e32 v41, 0xffff0000, v83
	v_pk_mul_f32 v[40:41], v[42:43], v[40:41]
	v_lshl_add_u64 v[58:59], v[58:59], 0, v[148:149]
	v_cvt_pk_bf16_f32 v51, v40, v41
	global_load_dwordx4 v[40:43], v[66:67], off offset:2304
	s_nop 0
	global_store_dwordx4 v[58:59], v[48:51], off nt
	s_waitcnt vmcnt(9)
	s_nop 0
	v_lshlrev_b32_e32 v48, 16, v73
	v_and_b32_e32 v49, 0xffff0000, v73
	v_pk_mul_f32 v[38:39], v[38:39], v[48:49]
	v_lshlrev_b32_e32 v48, 16, v72
	v_and_b32_e32 v49, 0xffff0000, v72
	v_pk_mul_f32 v[36:37], v[36:37], v[48:49]
	s_nop 0
	v_cvt_pk_bf16_f32 v36, v36, v37
	v_cvt_pk_bf16_f32 v37, v38, v39
	v_lshlrev_b32_e32 v38, 16, v74
	v_and_b32_e32 v39, 0xffff0000, v74
	v_pk_mul_f32 v[28:29], v[28:29], v[38:39]
	s_nop 0
	v_cvt_pk_bf16_f32 v38, v28, v29
	v_lshlrev_b32_e32 v28, 16, v75
	v_and_b32_e32 v29, 0xffff0000, v75
	v_pk_mul_f32 v[28:29], v[30:31], v[28:29]
	s_nop 0
	v_cvt_pk_bf16_f32 v39, v28, v29
	s_waitcnt vmcnt(6)
	v_lshlrev_b32_e32 v28, 16, v63
	v_and_b32_e32 v29, 0xffff0000, v63
	v_pk_mul_f32 v[30:31], v[34:35], v[28:29]
	v_lshlrev_b32_e32 v28, 16, v62
	v_and_b32_e32 v29, 0xffff0000, v62
	v_pk_mul_f32 v[28:29], v[32:33], v[28:29]
	global_store_dwordx4 v[58:59], v[36:39], off offset:256 nt
	v_cvt_pk_bf16_f32 v28, v28, v29
	v_cvt_pk_bf16_f32 v29, v30, v31
	v_lshlrev_b32_e32 v30, 16, v64
	v_and_b32_e32 v31, 0xffff0000, v64
	v_pk_mul_f32 v[24:25], v[24:25], v[30:31]
	v_lshlrev_b64 v[36:37], 11, v[76:77]
	v_cvt_pk_bf16_f32 v30, v24, v25
	v_lshlrev_b32_e32 v24, 16, v65
	v_and_b32_e32 v25, 0xffff0000, v65
	v_pk_mul_f32 v[24:25], v[26:27], v[24:25]
	s_waitcnt vmcnt(6)
	v_lshlrev_b32_e32 v26, 16, v55
	v_and_b32_e32 v27, 0xffff0000, v55
	v_pk_mul_f32 v[22:23], v[22:23], v[26:27]
	v_lshlrev_b32_e32 v26, 16, v54
	v_and_b32_e32 v27, 0xffff0000, v54
	v_pk_mul_f32 v[20:21], v[20:21], v[26:27]
	v_cvt_pk_bf16_f32 v31, v24, v25
	v_cvt_pk_bf16_f32 v20, v20, v21
	v_cvt_pk_bf16_f32 v21, v22, v23
	v_lshlrev_b32_e32 v22, 16, v56
	v_and_b32_e32 v23, 0xffff0000, v56
	v_pk_mul_f32 v[12:13], v[12:13], v[22:23]
	v_lshl_add_u64 v[24:25], s[4:5], 0, v[36:37]
	v_cvt_pk_bf16_f32 v22, v12, v13
	v_lshlrev_b32_e32 v12, 16, v57
	v_and_b32_e32 v13, 0xffff0000, v57
	v_pk_mul_f32 v[12:13], v[14:15], v[12:13]
	v_lshl_add_u64 v[24:25], v[24:25], 0, v[148:149]
	v_cvt_pk_bf16_f32 v23, v12, v13
	s_waitcnt vmcnt(3)
	v_lshlrev_b32_e32 v12, 16, v45
	v_and_b32_e32 v13, 0xffff0000, v45
	v_pk_mul_f32 v[14:15], v[18:19], v[12:13]
	v_lshlrev_b32_e32 v12, 16, v44
	v_and_b32_e32 v13, 0xffff0000, v44
	v_pk_mul_f32 v[12:13], v[16:17], v[12:13]
	global_store_dwordx4 v[24:25], v[20:23], off offset:256 nt
	v_cvt_pk_bf16_f32 v12, v12, v13
	v_cvt_pk_bf16_f32 v13, v14, v15
	v_lshlrev_b32_e32 v14, 16, v46
	v_and_b32_e32 v15, 0xffff0000, v46
	v_pk_mul_f32 v[8:9], v[8:9], v[14:15]
	v_lshlrev_b64 v[20:21], 11, v[52:53]
	v_cvt_pk_bf16_f32 v14, v8, v9
	v_lshlrev_b32_e32 v8, 16, v47
	v_and_b32_e32 v9, 0xffff0000, v47
	v_pk_mul_f32 v[8:9], v[10:11], v[8:9]
	global_store_dwordx4 v[24:25], v[28:31], off nt
	v_cvt_pk_bf16_f32 v15, v8, v9
	v_lshl_add_u64 v[8:9], s[4:5], 0, v[20:21]
	s_waitcnt vmcnt(4)
	v_lshlrev_b32_e32 v10, 16, v40
	v_and_b32_e32 v11, 0xffff0000, v40
	v_pk_mul_f32 v[4:5], v[4:5], v[10:11]
	v_lshlrev_b32_e32 v10, 16, v41
	v_and_b32_e32 v11, 0xffff0000, v41
	v_pk_mul_f32 v[6:7], v[6:7], v[10:11]
	v_cvt_pk_bf16_f32 v4, v4, v5
	v_cvt_pk_bf16_f32 v5, v6, v7
	v_lshlrev_b32_e32 v6, 16, v42
	v_and_b32_e32 v7, 0xffff0000, v42
	v_pk_mul_f32 v[0:1], v[0:1], v[6:7]
	v_lshl_add_u64 v[8:9], v[8:9], 0, v[148:149]
	v_cvt_pk_bf16_f32 v6, v0, v1
	v_lshlrev_b32_e32 v0, 16, v43
	v_and_b32_e32 v1, 0xffff0000, v43
	v_pk_mul_f32 v[0:1], v[2:3], v[0:1]
	global_store_dwordx4 v[8:9], v[12:15], off nt
	v_cvt_pk_bf16_f32 v7, v0, v1
	global_store_dwordx4 v[8:9], v[4:7], off offset:256 nt
	s_cbranch_vccnz .LBB0_2250
	s_andn2_b64 vcc, exec, s[10:11]
	s_cbranch_vccnz .LBB0_2249
	s_barrier
	s_branch .LBB0_2249
